# weight conversion loops for the query and key/value projection tiles de-serialized (loads in flight together); conv input staging loads batched; G3 norm gains loaded once per phase
# speedup vs baseline: 1.0330x; 1.0107x over previous
; #define LAS __attribute__((address_space(3)))
; __device__ __forceinline__ void gla_g3_phase(LAS unsigned char* lds, const bf16_t* PROJ, const bf16_t* ALOW, const float* wa2, const float* ba, const float* gn, const bf16_t* UPD, bf16_t* MIXIN, int G, int tid) {
;     LAS bf16_t* KE = (LAS bf16_t*)lds; LAS bf16_t* QE = (LAS bf16_t*)(lds + 9216); LAS bf16_t* VT = (LAS bf16_t*)(lds + 18432); LAS float* RED = (LAS float*)(lds + 36864);
;     const int lane = tid & 63, wave = __builtin_amdgcn_readfirstlane(tid >> 6);
;     const int eb = wave >> 1, cb = wave & 1, i = lane & 31, kg = lane >> 5;
;     G3In cur; if ((int)blockIdx.x < 2048) cur = g3_load(PROJ, ALOW, UPD, blockIdx.x, lane, wave);
;     for (int u = blockIdx.x; u < 2048; u += G) {
;         G3In nxt; if (u + G < 2048) nxt = g3_load(PROJ, ALOW, UPD, u + G, lane, wave);
;         const int bh = u >> 7, n = u & 127, b = bh >> 2, h = bh & 3, row0 = b * SEQ + n * 64;
;         const size_t row = (size_t)(row0 + 32 * cb + i);
;     ...
;             const f32x4 g4 = *(const f32x4*)(gn + e); const u32x2_t rr = cur.rr[rg];
.LBB0_342:
	s_and_b64 vcc, exec, s[8:9]
	s_cbranch_vccnz .LBB0_418
	s_load_dwordx2 s[4:5], s[4:5], 0x0
	s_nop 0
	s_load_dwordx2 s[8:9], s[10:11], 0x0
	s_nop 0
	s_load_dwordx2 s[10:11], s[12:13], 0x0
	v_readlane_b32 s12, v253, 47
	v_readlane_b32 s13, v253, 48
	s_lshl_b64 s[12:13], s[12:13], 2
	s_waitcnt lgkmcnt(0)
	s_add_u32 s4, s4, s12
	v_writelane_b32 v255, s4, 17
	s_addc_u32 s4, s5, s13
	v_writelane_b32 v255, s4, 18
	v_readlane_b32 s4, v253, 49
	v_readlane_b32 s5, v253, 50
	s_lshl_b64 s[4:5], s[4:5], 2
	s_add_u32 s4, s8, s4
	v_writelane_b32 v255, s4, 19
	s_addc_u32 s4, s9, s5
	v_writelane_b32 v255, s4, 20
	v_lshlrev_b32_e32 v28, 2, v27
	v_readlane_b32 s4, v255, 8
	v_readlane_b32 s5, v255, 9
	s_add_u32 s4, s10, s4
	s_addc_u32 s5, s11, s5
	s_lshl_b32 s15, s6, 4
	s_ashr_i32 s7, s7, 7
	s_and_b32 s48, s15, 0xffffffe0
	v_mul_u32_u24_e32 v27, 0x48, v172
	s_add_i32 s15, s15, 0
	v_lshl_add_u32 v127, v27, 1, s15
	s_lshl_b32 s15, s7, 5
	v_lshlrev_b32_e32 v27, 1, v172
	v_lshrrev_b32_e32 v30, 1, v170
	v_or_b32_e32 v104, s15, v28
	s_and_b32 s14, s6, 1
	s_lshl_b32 s78, s6, 3
	s_lshl_b32 s8, s6, 5
	v_and_b32_e32 v27, 8, v27
	v_and_b32_e32 v29, 51, v170
	v_and_b32_e32 v30, 4, v30
	v_ashrrev_i32_e32 v105, 31, v104
	s_mulk_i32 s6, 0x480
	v_or3_b32 v27, v30, v29, v27
	v_lshl_add_u64 v[106:107], v[104:105], 2, s[4:5]
	s_add_i32 s4, s6, 0
	v_lshl_add_u32 v131, v27, 1, s4
	v_or_b32_e32 v27, 2, v28
	v_cmp_gt_u32_e64 s[18:19], v27, v26
	v_or_b32_e32 v27, 3, v28
	v_cmp_gt_u32_e64 s[20:21], v27, v26
	v_or_b32_e32 v27, 8, v28
	v_lshl_or_b32 v128, s14, 5, v26
	s_movk_i32 s16, 0x90
	v_or_b32_e32 v31, s15, v26
	s_lshl_b32 s7, s7, 8
	v_cmp_gt_u32_e64 s[22:23], v27, v26
	v_or_b32_e32 v27, 9, v28
	v_mad_u32_u24 v29, v128, s16, 0
	v_mul_lo_u32 v31, v31, s16
	s_add_i32 s7, s7, 0
	s_lshl_b32 s16, s14, 7
	v_cmp_gt_u32_e64 s[24:25], v27, v26
	v_or_b32_e32 v27, 10, v28
	s_ashr_i32 s79, s78, 31
	s_ashr_i32 s49, s48, 31
	s_add_i32 s7, s7, s16
	s_add_i32 s16, s16, 0
	v_cmp_gt_u32_e64 s[26:27], v27, v26
	v_or_b32_e32 v27, 11, v28
	s_cmp_eq_u32 s14, 0
	v_cmp_gt_u32_e64 s[28:29], v27, v26
	v_or_b32_e32 v27, 16, v28
	s_cselect_b64 s[4:5], -1, 0
	v_cmp_gt_u32_e64 s[30:31], v27, v26
	v_or_b32_e32 v27, 17, v28
	v_writelane_b32 v255, s4, 21
	s_cmp_eq_u32 s14, 1
	v_cmp_gt_u32_e64 s[34:35], v27, v26
	v_or_b32_e32 v27, 18, v28
	v_writelane_b32 v255, s5, 22
	s_cselect_b64 s[4:5], -1, 0
	v_cmp_gt_u32_e64 s[36:37], v27, v26
	v_or_b32_e32 v27, 19, v28
	v_writelane_b32 v255, s4, 23
	v_cmp_gt_u32_e64 s[38:39], v27, v26
	v_or_b32_e32 v27, 24, v28
	v_writelane_b32 v255, s5, 24
	v_cmp_gt_u32_e64 s[4:5], v28, v26
	v_cmp_gt_u32_e64 s[40:41], v27, v26
	v_or_b32_e32 v27, 25, v28
	v_writelane_b32 v255, s4, 25
	v_cmp_gt_u32_e64 s[42:43], v27, v26
	v_or_b32_e32 v27, 26, v28
	v_lshlrev_b32_e32 v25, 2, v26
	v_writelane_b32 v255, s5, 26
	v_cmp_gt_u32_e64 s[44:45], v27, v26
	v_or_b32_e32 v27, 27, v28
	v_and_or_b32 v126, s8, 32, v26
	v_add_u32_e32 v129, s7, v25
	v_add_u32_e32 v130, s16, v25
	v_mul_u32_u24_e32 v25, 0x90, v26
	v_cmp_lt_u32_e64 s[16:17], v28, v26
	v_cmp_gt_u32_e64 s[46:47], v27, v26
	v_or_b32_e32 v26, s48, v26
	v_writelane_b32 v255, s48, 27
	v_and_b32_e32 v32, 32, v170
	v_lshrrev_b32_e32 v32, 1, v32
	v_mov_b32_e32 v27, s49
	v_lshlrev_b64 v[26:27], 7, v[26:27]
	v_readlane_b32 s4, v253, 15
	v_add_u32_e32 v30, 0, v24
	v_add_u32_e32 v31, 0, v31
	v_or_b32_e32 v26, v26, v32
	v_readlane_b32 s5, v253, 16
	v_cmp_gt_u32_e64 s[8:9], 48, v172
	v_cmp_gt_u32_e64 s[10:11], 32, v172
	v_cmp_lt_u32_e64 s[12:13], 15, v172
	v_writelane_b32 v255, s49, 28
	v_lshl_add_u64 v[108:109], s[4:5], 0, v[26:27]
	v_lshlrev_b32_e32 v164, 1, v28
	v_add_u32_e32 v132, v29, v24
	v_add_u32_e32 v133, v30, v25
	v_add_u32_e32 v134, v31, v24
	v_readlane_b32 s64, v250, 51
	v_readlane_b32 s65, v250, 52
	s_mov_b32 s6, s2
	global_load_dwordx4 v[180:183], v[106:107], off
	global_load_dwordx4 v[184:187], v[106:107], off offset:32
	global_load_dwordx4 v[188:191], v[106:107], off offset:64
	global_load_dwordx4 v[192:195], v[106:107], off offset:96
	s_waitcnt vmcnt(0)
	s_branch .LBB0_345
.LBB0_344:
	s_or_b64 exec, exec, s[6:7]
	s_waitcnt lgkmcnt(0)
	s_barrier
; __device__ __forceinline__ float silu_fast(float x) { return x * __builtin_amdgcn_rcpf(1.f + __expf(-x)); }
; __device__ __forceinline__ unsigned cvtpk(float lo, float hi) { unsigned r; asm volatile("v_cvt_pk_bf16_f32 %0, %1, %2" : "=v"(r) : "v"(lo), "v"(hi)); return r; }
; #define GLA_BAR() do { asm volatile("s_waitcnt lgkmcnt(0)" ::: "memory"); __builtin_amdgcn_s_barrier(); asm volatile("" ::: "memory"); } while (0)
; __device__ __forceinline__ void gla_g3_phase(LAS unsigned char* lds, const bf16_t* PROJ, const bf16_t* ALOW, const float* wa2, const float* ba, const float* gn, const bf16_t* UPD, bf16_t* MIXIN, int G, int tid) {
;     ...
;         const float tot = (RED[32 * cb + i] + RED[64 + 32 * cb + i]) + (RED[128 + 32 * cb + i] + RED[192 + 32 * cb + i]);
;         const float rstd = rsqrtf(tot * (1.f / 128.f) + LN_EPS);
; #pragma unroll
;         for (int rg = 0; rg < 4; ++rg) { const int e = 32 * eb + 8 * rg + 4 * kg;
;             const f32x4 g4 = *(const f32x4*)(gn + e); const u32x2_t rr = cur.rr[rg];
;             const float r0 = __uint_as_float(rr.x << 16), r1 = __uint_as_float(rr.x & 0xffff0000u), r2 = __uint_as_float(rr.y << 16), r3 = __uint_as_float(rr.y & 0xffff0000u);
;             u32x2_t w; w.x = cvtpk(o[4 * rg] * rstd * g4[0] * pg8::silu_fast(r0), o[4 * rg + 1] * rstd * g4[1] * pg8::silu_fast(r1));
;             w.y = cvtpk(o[4 * rg + 2] * rstd * g4[2] * pg8::silu_fast(r2), o[4 * rg + 3] * rstd * g4[3] * pg8::silu_fast(r3));
;             *(u32x2_t*)(MIXIN + row * D + 512 + h * 128 + e) = w; }
;         GLA_BAR();
	ds_read2st64_b32 v[18:19], v130 offset0:144 offset1:145
	ds_read2st64_b32 v[20:21], v130 offset0:146 offset1:147
	v_and_b32_e32 v26, 0xffff0000, v124
	v_lshlrev_b32_e32 v28, 16, v125
	v_and_b32_e32 v30, 0xffff0000, v125
	s_waitcnt lgkmcnt(1)
	v_mov_b32_e32 v22, v18
	s_waitcnt lgkmcnt(0)
	v_mov_b32_e32 v23, v20
	v_mov_b32_e32 v20, v19
	v_pk_add_f32 v[18:19], v[22:23], v[20:21]
	v_mov_b64_e32 v[22:23], v[180:181]
	v_mov_b64_e32 v[24:25], v[182:183]
	v_add_f32_e32 v18, v18, v19
	v_fmamk_f32 v18, v18, 0x3c000000, v173
	v_cmp_gt_f32_e32 vcc, s81, v18
	v_mul_f32_e32 v19, 0x4b800000, v18
	s_and_b32 s4, s64, 0xffffe000
	v_cndmask_b32_e32 v18, v18, v19, vcc
	v_rsq_f32_e32 v18, v18
	s_and_b32 s5, s65, 0x1fc0
	s_or_b32 s4, s4, s5
	v_or_b32_e32 v16, s4, v128
	v_mul_f32_e32 v19, 0x45800000, v18
	v_cndmask_b32_e32 v20, v18, v19, vcc
	v_lshlrev_b32_e32 v18, 16, v124
	v_mul_f32_e32 v19, v0, v20
	v_mul_f32_e32 v0, 0xbfb8aa3b, v18
	v_exp_f32_e32 v0, v0
	v_mul_f32_e32 v27, v1, v20
	v_mul_f32_e32 v29, v2, v20
	v_ashrrev_i32_e32 v17, 31, v16
	v_add_f32_e32 v0, 1.0, v0
	v_rcp_f32_e32 v72, v0
	v_mul_f32_e32 v0, 0xbfb8aa3b, v26
	v_exp_f32_e32 v0, v0
	v_readlane_b32 s4, v250, 10
	v_lshlrev_b64 v[16:17], 11, v[16:17]
	v_readlane_b32 s5, v250, 11
	v_add_f32_e32 v0, 1.0, v0
	v_mul_f32_e32 v31, v3, v20
	v_lshl_add_u64 v[16:17], s[4:5], 0, v[16:17]
	s_lshl_b32 s74, s74, 8
	v_lshl_add_u64 v[16:17], v[16:17], 0, s[74:75]
	v_mul_f32_e32 v3, v4, v20
	v_readlane_b32 s4, v253, 0
	s_add_i32 s65, s65, s4
	v_readlane_b32 s4, v253, 42
	s_add_i32 s64, s64, s4
	v_readlane_b32 s4, v253, 18
	v_readlane_b32 s5, v253, 19
	v_mov_b64_e32 v[78:79], v[62:63]
	v_mov_b64_e32 v[82:83], v[58:59]
	v_mov_b64_e32 v[86:87], v[54:55]
	v_lshl_add_u64 v[108:109], v[108:109], 0, s[4:5]
	s_and_b64 vcc, exec, s[92:93]
	v_mov_b64_e32 v[76:77], v[60:61]
	v_mov_b64_e32 v[80:81], v[56:57]
	v_mov_b64_e32 v[84:85], v[52:53]
	v_mov_b64_e32 v[124:125], v[118:119]
	s_mov_b32 s6, s70
	v_mov_b32_e32 v73, v22
	v_rcp_f32_e32 v22, v0
	v_pk_mul_f32 v[18:19], v[72:73], v[18:19]
	v_mov_b64_e32 v[74:75], v[50:51]
	v_mul_f32_e32 v18, v18, v19
	v_pk_mul_f32 v[0:1], v[22:23], v[26:27]
	v_and_b32_e32 v22, 0xffff0000, v122
	v_mul_f32_e32 v0, v0, v1
	v_cvt_pk_bf16_f32 v18, v18, v0
	v_mul_f32_e32 v0, 0xbfb8aa3b, v28
	v_exp_f32_e32 v0, v0
	v_mov_b32_e32 v1, v24
	v_mul_f32_e32 v23, v5, v20
	v_and_b32_e32 v26, 0xffff0000, v123
	v_add_f32_e32 v0, 1.0, v0
	v_rcp_f32_e32 v0, v0
	v_mul_f32_e32 v27, v7, v20
	v_mov_b64_e32 v[72:73], v[48:49]
	v_pk_mul_f32 v[0:1], v[0:1], v[28:29]
	s_nop 0
	v_mul_f32_e32 v2, v0, v1
	v_mul_f32_e32 v0, 0xbfb8aa3b, v30
	v_exp_f32_e32 v0, v0
	s_nop 0
	v_add_f32_e32 v0, 1.0, v0
	v_rcp_f32_e32 v24, v0
	s_nop 0
	v_pk_mul_f32 v[0:1], v[24:25], v[30:31]
	s_nop 0
	v_mul_f32_e32 v0, v0, v1
	v_cvt_pk_bf16_f32 v19, v2, v0
	v_lshl_add_u64 v[0:1], v[104:105], 1, v[16:17]
	global_store_dwordx2 v[0:1], v[18:19], off offset:1024
	v_mov_b64_e32 v[16:17], v[184:185]
	v_mov_b64_e32 v[18:19], v[186:187]
	v_lshlrev_b32_e32 v2, 16, v122
	v_mul_f32_e32 v4, 0xbfb8aa3b, v2
	v_exp_f32_e32 v4, v4
	v_lshlrev_b32_e32 v24, 16, v123
	v_mul_f32_e32 v25, v6, v20
	v_lshlrev_b32_e32 v6, 16, v120
	v_add_f32_e32 v4, 1.0, v4
	v_rcp_f32_e32 v28, v4
	v_mul_f32_e32 v7, 0xbfb8aa3b, v6
	v_exp_f32_e32 v7, v7
	v_mov_b64_e32 v[122:123], v[116:117]
	v_add_f32_e32 v7, 1.0, v7
	v_mov_b32_e32 v29, v16
	v_pk_mul_f32 v[2:3], v[28:29], v[2:3]
	v_mov_b32_e32 v5, v18
	v_mul_f32_e32 v4, v2, v3
	v_mul_f32_e32 v2, 0xbfb8aa3b, v22
	v_exp_f32_e32 v2, v2
	s_nop 0
	v_add_f32_e32 v2, 1.0, v2
	v_rcp_f32_e32 v16, v2
	s_nop 0
	v_pk_mul_f32 v[2:3], v[16:17], v[22:23]
	s_nop 0
	v_mul_f32_e32 v2, v2, v3
	v_mul_f32_e32 v3, 0xbfb8aa3b, v24
	v_exp_f32_e32 v3, v3
	v_cvt_pk_bf16_f32 v2, v4, v2
	v_and_b32_e32 v16, 0xffff0000, v120
	v_and_b32_e32 v22, 0xffff0000, v121
	v_add_f32_e32 v3, 1.0, v3
	v_rcp_f32_e32 v4, v3
	s_nop 0
	v_pk_mul_f32 v[4:5], v[4:5], v[24:25]
	s_nop 0
	v_mul_f32_e32 v3, v4, v5
	v_mul_f32_e32 v4, 0xbfb8aa3b, v26
	v_exp_f32_e32 v4, v4
	v_rcp_f32_e32 v24, v7
	v_mul_f32_e32 v25, v8, v20
	v_add_f32_e32 v4, 1.0, v4
	v_rcp_f32_e32 v18, v4
	s_nop 0
	v_pk_mul_f32 v[4:5], v[18:19], v[26:27]
	s_nop 0
	v_mul_f32_e32 v4, v4, v5
	v_cvt_pk_bf16_f32 v3, v3, v4
	global_store_dwordx2 v[0:1], v[2:3], off offset:1040
	v_mov_b64_e32 v[2:3], v[188:189]
	v_mov_b64_e32 v[4:5], v[190:191]
	v_lshlrev_b32_e32 v18, 16, v121
	v_mov_b64_e32 v[120:121], v[114:115]
	v_mov_b32_e32 v7, v2
	v_mul_f32_e32 v2, 0xbfb8aa3b, v16
	v_exp_f32_e32 v2, v2
	v_pk_mul_f32 v[6:7], v[24:25], v[6:7]
	v_mov_b32_e32 v17, v3
	v_mul_f32_e32 v8, v6, v7
	v_add_f32_e32 v2, 1.0, v2
	v_rcp_f32_e32 v6, v2
	v_mul_f32_e32 v7, v9, v20
	v_mov_b32_e32 v19, v4
	v_mul_f32_e32 v4, 0xbfb8aa3b, v22
	v_pk_mul_f32 v[2:3], v[6:7], v[16:17]
	v_exp_f32_e32 v4, v4
	v_mul_f32_e32 v2, v2, v3
	v_mul_f32_e32 v3, 0xbfb8aa3b, v18
	v_exp_f32_e32 v3, v3
	v_mul_f32_e32 v7, v10, v20
	v_add_f32_e32 v4, 1.0, v4
	v_mov_b32_e32 v23, v5
	v_add_f32_e32 v3, 1.0, v3
	v_rcp_f32_e32 v6, v3
	v_cvt_pk_bf16_f32 v2, v8, v2
	v_and_b32_e32 v8, 0xffff0000, v110
	v_lshlrev_b32_e32 v10, 16, v111
	v_pk_mul_f32 v[6:7], v[6:7], v[18:19]
	v_mul_f32_e32 v19, v12, v20
	v_mul_f32_e32 v3, v6, v7
	v_rcp_f32_e32 v6, v4
	v_mul_f32_e32 v7, v11, v20
	v_and_b32_e32 v16, 0xffff0000, v111
	v_pk_mul_f32 v[4:5], v[6:7], v[22:23]
	s_nop 0
	v_mul_f32_e32 v4, v4, v5
	v_cvt_pk_bf16_f32 v3, v3, v4
	global_store_dwordx2 v[0:1], v[2:3], off offset:1056
	v_mov_b64_e32 v[2:3], v[192:193]
	v_mov_b64_e32 v[4:5], v[194:195]
	v_lshlrev_b32_e32 v6, 16, v110
	v_mul_f32_e32 v7, 0xbfb8aa3b, v6
	v_exp_f32_e32 v7, v7
	v_mov_b64_e32 v[110:111], v[112:113]
	v_add_f32_e32 v7, 1.0, v7
	v_rcp_f32_e32 v18, v7
	v_mov_b32_e32 v7, v2
	v_mul_f32_e32 v2, 0xbfb8aa3b, v8
	v_exp_f32_e32 v2, v2
	v_pk_mul_f32 v[6:7], v[18:19], v[6:7]
	v_mov_b32_e32 v9, v3
	v_mul_f32_e32 v11, v6, v7
	v_add_f32_e32 v2, 1.0, v2
	v_rcp_f32_e32 v6, v2
	v_mul_f32_e32 v7, v13, v20
	v_mov_b32_e32 v17, v5
	v_pk_mul_f32 v[2:3], v[6:7], v[8:9]
	s_nop 0
	v_mul_f32_e32 v2, v2, v3
	v_mul_f32_e32 v3, 0xbfb8aa3b, v10
	v_exp_f32_e32 v3, v3
	v_cvt_pk_bf16_f32 v2, v11, v2
	v_mov_b32_e32 v11, v4
	v_mul_f32_e32 v4, 0xbfb8aa3b, v16
	v_add_f32_e32 v3, 1.0, v3
	v_rcp_f32_e32 v6, v3
	v_exp_f32_e32 v4, v4
	v_mul_f32_e32 v7, v14, v20
	v_pk_mul_f32 v[6:7], v[6:7], v[10:11]
	v_add_f32_e32 v4, 1.0, v4
	v_mul_f32_e32 v3, v6, v7
	v_rcp_f32_e32 v6, v4
	v_mul_f32_e32 v7, v15, v20
	v_mov_b64_e32 v[20:21], v[32:33]
	v_mov_b64_e32 v[12:13], v[68:69]
	v_pk_mul_f32 v[4:5], v[6:7], v[16:17]
	v_mov_b64_e32 v[16:17], v[36:37]
	v_mul_f32_e32 v4, v4, v5
	v_cvt_pk_bf16_f32 v3, v3, v4
	global_store_dwordx2 v[0:1], v[2:3], off offset:1072
	s_waitcnt lgkmcnt(0)
	s_barrier
	v_mov_b64_e32 v[4:5], v[44:45]
	v_mov_b64_e32 v[0:1], v[40:41]
	v_mov_b64_e32 v[8:9], v[64:65]
	v_mov_b64_e32 v[18:19], v[38:39]
	v_mov_b64_e32 v[22:23], v[34:35]
	v_mov_b64_e32 v[6:7], v[46:47]
	v_mov_b64_e32 v[2:3], v[42:43]
	v_mov_b64_e32 v[14:15], v[70:71]
	v_mov_b64_e32 v[10:11], v[66:67]
	s_cbranch_vccnz .LBB0_418

; #define LAS __attribute__((address_space(3)))
; __device__ __forceinline__ void conv_phase(LAS unsigned char* lds, const bf16_t* PROJ, const float* cw, const float* cb, const float* lg, const float* lb, bf16_t* MIXIN, int G, int tid) {
;     LAS float* U = (LAS float*)lds;
;     for (int u = blockIdx.x; u < M / 32; u += G) {
;         asm volatile("" : "+v"(tid));
;         const int lane = tid & 63, wave = __builtin_amdgcn_readfirstlane(tid >> 6);
;         const int row0 = u * 32, t0 = row0 % SEQ;
;         const int c = tid;
;         float w[31];
; #pragma unroll
;         for (int k = 0; k < 31; ++k) w[k] = cw[k * 512 + c];
;         const float bias = cb[c];
; #pragma unroll
;         for (int pass = 0; pass < 8; ++pass) { const int rr = pass * 8 + wave;
;             if (rr < 62) { f32x4 o0 = (f32x4){0.f, 0.f, 0.f, 0.f}, o1 = o0;
;                 if (t0 - 30 + rr >= 0) { const u32x4 a = *(const u32x4*)(PROJ + (size_t)(row0 - 30 + rr) * PROJ_LD + 8 * lane);
;                     o0 = (f32x4){__uint_as_float(a[0] << 16), __uint_as_float(a[0] & 0xffff0000u), __uint_as_float(a[1] << 16), __uint_as_float(a[1] & 0xffff0000u)};
;                     o1 = (f32x4){__uint_as_float(a[2] << 16), __uint_as_float(a[2] & 0xffff0000u), __uint_as_float(a[3] << 16), __uint_as_float(a[3] & 0xffff0000u)}; }
;                 *(LAS f32x4*)(U + rr * 512 + 8 * lane) = o0; *(LAS f32x4*)(U + rr * 512 + 8 * lane + 4) = o1; } }
;         __syncthreads();
;         float y[32];
; #pragma unroll
;         for (int blk = 0; blk < 4; ++blk) { float win[38];
; #pragma unroll
;             for (int x = 0; x < 38; ++x) win[x] = U[(8 * blk + x) * 512 + c];
; #pragma unroll
;             for (int o = 0; o < 8; ++o) { float acc = bias;
; #pragma unroll
;                 for (int k = 0; k < 31; ++k) acc += w[k] * win[o + k];
.LBB0_427:
	s_andn2_b64 vcc, exec, s[4:5]
	s_mov_b64 s[20:21], 0
	s_cbranch_vccnz .LBB0_542
	v_readlane_b32 s4, v254, 1
	s_cmp_gt_i32 s4, 0
	s_mov_b64 s[4:5], -1
	s_cbranch_scc0 .LBB0_540
	v_readlane_b32 s4, v253, 46
	v_readlane_b32 s5, v255, 14
	s_cmp_ge_u32 s5, s4
	v_readlane_b32 s4, v250, 60
	s_cselect_b64 s[8:9], -1, 0
	v_readlane_b32 s5, v250, 61
	v_readlane_b32 s6, v250, 58
	s_or_b64 s[4:5], s[4:5], s[8:9]
	v_readlane_b32 s7, v250, 59
	s_and_b64 s[4:5], s[6:7], s[4:5]
	s_andn2_b64 vcc, exec, s[4:5]
	s_cbranch_vccnz .LBB0_465
	v_readlane_b32 s6, v250, 62
	v_readlane_b32 s7, v250, 63
	s_mov_b32 s10, 7
	s_mov_b32 s12, 8
	s_mov_b32 s14, 9
	s_mov_b32 s4, 10
	s_andn2_b64 vcc, exec, s[6:7]
	s_cbranch_vccnz .LBB0_465
	s_ashr_i32 s11, s10, 31
	s_lshl_b64 s[6:7], s[10:11], 3
	s_add_u32 s6, s0, s6
	s_addc_u32 s7, s1, s7
	s_load_dwordx2 s[6:7], s[6:7], 0x0
	v_readlane_b32 s10, v255, 10
	v_readlane_b32 s11, v255, 11
	v_readlane_b32 s16, v255, 12
	v_readlane_b32 s17, v255, 13
	s_waitcnt lgkmcnt(0)
	s_add_u32 s10, s6, s10
	s_addc_u32 s11, s7, s11
	s_ashr_i32 s13, s12, 31
	s_lshl_b64 s[6:7], s[12:13], 3
	s_add_u32 s6, s0, s6
	s_addc_u32 s7, s1, s7
	s_load_dwordx2 s[6:7], s[6:7], 0x0
	s_waitcnt vmcnt(0)
	v_mov_b32_e32 v8, v170
	s_waitcnt lgkmcnt(0)
	s_add_u32 s12, s6, s16
	s_addc_u32 s13, s7, s17
	s_ashr_i32 s15, s14, 31
	s_lshl_b64 s[6:7], s[14:15], 3
	s_add_u32 s6, s0, s6
	s_addc_u32 s7, s1, s7
	s_load_dwordx2 s[6:7], s[6:7], 0x0
	s_waitcnt lgkmcnt(0)
	s_add_u32 s14, s6, s16
	s_addc_u32 s15, s7, s17
	s_ashr_i32 s5, s4, 31
	s_lshl_b64 s[4:5], s[4:5], 3
	s_add_u32 s4, s0, s4
	s_addc_u32 s5, s1, s5
	s_load_dwordx2 s[4:5], s[4:5], 0x0
	v_readlane_b32 s6, v253, 22
	s_mov_b32 s7, s2
	s_waitcnt lgkmcnt(0)
	s_add_u32 s16, s4, s16
	s_addc_u32 s17, s5, s17
	s_branch .LBB0_434
.LBB0_433:
	v_lshl_add_u32 v62, v8, 2, 0
	v_add_u32_e32 v63, 0x10000, v62
	v_add_u32_e32 v74, 0x13800, v62
	v_add_u32_e32 v81, 0x17000, v62
	v_add_u32_e32 v88, 0x1a800, v62
	v_add_u32_e32 v95, 0x1e000, v62
	v_lshlrev_b32_e32 v61, 3, v12
	s_waitcnt lgkmcnt(0)
	s_barrier
	ds_read2st64_b32 v[70:71], v62 offset1:8
	ds_read2st64_b32 v[72:73], v62 offset0:16 offset1:24
	ds_read2st64_b32 v[28:29], v62 offset0:32 offset1:40
	ds_read2st64_b32 v[26:27], v62 offset0:48 offset1:56
	ds_read2st64_b32 v[24:25], v62 offset0:64 offset1:72
	ds_read2st64_b32 v[22:23], v62 offset0:80 offset1:88
	ds_read2st64_b32 v[20:21], v62 offset0:96 offset1:104
	ds_read2st64_b32 v[18:19], v62 offset0:112 offset1:120
	ds_read2st64_b32 v[16:17], v62 offset0:128 offset1:136
	ds_read2st64_b32 v[14:15], v62 offset0:144 offset1:152
	ds_read2st64_b32 v[12:13], v62 offset0:160 offset1:168
	ds_read2st64_b32 v[10:11], v62 offset0:176 offset1:184
	ds_read2st64_b32 v[6:7], v62 offset0:192 offset1:200
	ds_read2st64_b32 v[4:5], v62 offset0:208 offset1:216
	ds_read2st64_b32 v[2:3], v62 offset0:224 offset1:232
	ds_read2st64_b32 v[0:1], v62 offset0:240 offset1:248
	ds_read_b32 v64, v63
	ds_read_b32 v74, v74
	ds_read_b32 v81, v81
	ds_read_b32 v88, v88
	ds_read_b32 v95, v95
	v_add_u32_e32 v63, 0x10800, v62
	v_add_u32_e32 v75, 0x14000, v62
	v_add_u32_e32 v82, 0x17800, v62
	v_add_u32_e32 v89, 0x1b000, v62
	v_add_u32_e32 v96, 0x1e800, v62
	ds_read_b32 v65, v63
	ds_read_b32 v75, v75
	ds_read_b32 v82, v82
	ds_read_b32 v89, v89
	ds_read_b32 v96, v96
	v_add_u32_e32 v63, 0x11000, v62
	v_add_u32_e32 v76, 0x14800, v62
	v_add_u32_e32 v83, 0x18000, v62
	v_add_u32_e32 v90, 0x1b800, v62
	ds_read_b32 v66, v63
	ds_read_b32 v76, v76
	ds_read_b32 v83, v83
	ds_read_b32 v90, v90
	v_add_u32_e32 v63, 0x11800, v62
	v_add_u32_e32 v77, 0x15000, v62
	v_add_u32_e32 v84, 0x18800, v62
	v_add_u32_e32 v91, 0x1c000, v62
	ds_read_b32 v67, v63
	ds_read_b32 v77, v77
	ds_read_b32 v84, v84
	ds_read_b32 v91, v91
	v_add_u32_e32 v63, 0x12000, v62
	v_add_u32_e32 v78, 0x15800, v62
	v_add_u32_e32 v85, 0x19000, v62
	v_add_u32_e32 v92, 0x1c800, v62
	ds_read_b32 v68, v63
	ds_read_b32 v78, v78
	ds_read_b32 v85, v85
	ds_read_b32 v92, v92
	v_add_u32_e32 v63, 0x12800, v62
	v_add_u32_e32 v79, 0x16000, v62
	v_add_u32_e32 v86, 0x19800, v62
	v_add_u32_e32 v93, 0x1d000, v62
	ds_read_b32 v69, v63
	ds_read_b32 v79, v79
	ds_read_b32 v86, v86
	ds_read_b32 v93, v93
	s_waitcnt vmcnt(0) lgkmcnt(14)
	v_fma_f32 v63, v36, v70, v49
	v_fmac_f32_e32 v63, v35, v71
	v_fma_f32 v70, v36, v71, v49
	v_fmac_f32_e32 v63, v34, v72
	v_fmac_f32_e32 v70, v35, v72
	v_fma_f32 v71, v36, v72, v49
	v_fmac_f32_e32 v63, v33, v73
	v_fmac_f32_e32 v70, v34, v73
	v_fmac_f32_e32 v71, v35, v73
	v_fma_f32 v72, v36, v73, v49
	v_fmac_f32_e32 v63, v31, v28
	v_fmac_f32_e32 v70, v33, v28
	v_fmac_f32_e32 v71, v34, v28
	v_fmac_f32_e32 v72, v35, v28
	v_fma_f32 v28, v36, v28, v49
	v_fmac_f32_e32 v63, v9, v29
	v_fmac_f32_e32 v70, v31, v29
	v_fmac_f32_e32 v71, v33, v29
	v_fmac_f32_e32 v72, v34, v29
	v_fmac_f32_e32 v28, v35, v29
	v_fma_f32 v29, v36, v29, v49
	v_fmac_f32_e32 v63, v32, v26
	v_fmac_f32_e32 v70, v9, v26
	v_fmac_f32_e32 v71, v31, v26
	v_fmac_f32_e32 v72, v33, v26
	v_fmac_f32_e32 v28, v34, v26
	v_fmac_f32_e32 v29, v35, v26
	v_fma_f32 v26, v36, v26, v49
	v_fmac_f32_e32 v63, v30, v27
	v_fmac_f32_e32 v70, v32, v27
	v_fmac_f32_e32 v71, v9, v27
	v_fmac_f32_e32 v72, v31, v27
	v_fmac_f32_e32 v28, v33, v27
	v_fmac_f32_e32 v29, v34, v27
	v_fmac_f32_e32 v26, v35, v27
	v_fma_f32 v27, v36, v27, v49
	v_fmac_f32_e32 v63, v44, v24
	v_fmac_f32_e32 v70, v30, v24
	v_fmac_f32_e32 v71, v32, v24
	v_fmac_f32_e32 v72, v9, v24
	v_fmac_f32_e32 v28, v31, v24
	v_fmac_f32_e32 v29, v33, v24
	v_fmac_f32_e32 v26, v34, v24
	v_fmac_f32_e32 v27, v35, v24
	v_fma_f32 v24, v36, v24, v49
	v_fmac_f32_e32 v63, v43, v25
	v_fmac_f32_e32 v70, v44, v25
	v_fmac_f32_e32 v71, v30, v25
; __device__ __forceinline__ void conv_phase(LAS unsigned char* lds, const bf16_t* PROJ, const float* cw, const float* cb, const float* lg, const float* lb, bf16_t* MIXIN, int G, int tid) {
;     ...
;         for (int blk = 0; blk < 4; ++blk) { float win[38];
; #pragma unroll
;             for (int x = 0; x < 38; ++x) win[x] = U[(8 * blk + x) * 512 + c];
; #pragma unroll
;             for (int o = 0; o < 8; ++o) { float acc = bias;
; #pragma unroll
;                 for (int k = 0; k < 31; ++k) acc += w[k] * win[o + k];
;                 y[8 * blk + o] = acc; } }
	v_fmac_f32_e32 v72, v32, v25
	v_fmac_f32_e32 v28, v9, v25
	v_fmac_f32_e32 v29, v31, v25
	v_fmac_f32_e32 v26, v33, v25
	v_fmac_f32_e32 v27, v34, v25
	v_fmac_f32_e32 v24, v35, v25
	v_fma_f32 v25, v36, v25, v49
	v_fmac_f32_e32 v63, v42, v22
	v_fmac_f32_e32 v70, v43, v22
	v_fmac_f32_e32 v71, v44, v22
	v_fmac_f32_e32 v72, v30, v22
	v_fmac_f32_e32 v28, v32, v22
	v_fmac_f32_e32 v29, v9, v22
	v_fmac_f32_e32 v26, v31, v22
	v_fmac_f32_e32 v27, v33, v22
	v_fmac_f32_e32 v24, v34, v22
	v_fmac_f32_e32 v25, v35, v22
	v_fma_f32 v22, v36, v22, v49
	v_fmac_f32_e32 v63, v41, v23
	v_fmac_f32_e32 v70, v42, v23
	v_fmac_f32_e32 v71, v43, v23
	v_fmac_f32_e32 v72, v44, v23
	v_fmac_f32_e32 v28, v30, v23
	v_fmac_f32_e32 v29, v32, v23
	v_fmac_f32_e32 v26, v9, v23
	v_fmac_f32_e32 v27, v31, v23
	v_fmac_f32_e32 v24, v33, v23
	v_fmac_f32_e32 v25, v34, v23
	v_fmac_f32_e32 v22, v35, v23
	v_fma_f32 v23, v36, v23, v49
	v_fmac_f32_e32 v63, v39, v20
	v_fmac_f32_e32 v70, v41, v20
	v_fmac_f32_e32 v71, v42, v20
	v_fmac_f32_e32 v72, v43, v20
	v_fmac_f32_e32 v28, v44, v20
	v_fmac_f32_e32 v29, v30, v20
	v_fmac_f32_e32 v26, v32, v20
	v_fmac_f32_e32 v27, v9, v20
	v_fmac_f32_e32 v24, v31, v20
	v_fmac_f32_e32 v25, v33, v20
	v_fmac_f32_e32 v22, v34, v20
	v_fmac_f32_e32 v23, v35, v20
	v_fma_f32 v20, v36, v20, v49
	v_fmac_f32_e32 v63, v37, v21
	v_fmac_f32_e32 v70, v39, v21
	v_fmac_f32_e32 v71, v41, v21
	v_fmac_f32_e32 v72, v42, v21
	v_fmac_f32_e32 v28, v43, v21
	v_fmac_f32_e32 v29, v44, v21
	v_fmac_f32_e32 v26, v30, v21
	v_fmac_f32_e32 v27, v32, v21
	v_fmac_f32_e32 v24, v9, v21
	v_fmac_f32_e32 v25, v31, v21
	v_fmac_f32_e32 v22, v33, v21
	v_fmac_f32_e32 v23, v34, v21
	v_fmac_f32_e32 v20, v35, v21
	v_fma_f32 v21, v36, v21, v49
	v_fmac_f32_e32 v63, v40, v18
	v_fmac_f32_e32 v70, v37, v18
	v_fmac_f32_e32 v71, v39, v18
	v_fmac_f32_e32 v72, v41, v18
	v_fmac_f32_e32 v28, v42, v18
	v_fmac_f32_e32 v29, v43, v18
	v_fmac_f32_e32 v26, v44, v18
	v_fmac_f32_e32 v27, v30, v18
	v_fmac_f32_e32 v24, v32, v18
	v_fmac_f32_e32 v25, v9, v18
	v_fmac_f32_e32 v22, v31, v18
	v_fmac_f32_e32 v23, v33, v18
	v_fmac_f32_e32 v20, v34, v18
	v_fmac_f32_e32 v21, v35, v18
	v_fma_f32 v18, v36, v18, v49
	v_fmac_f32_e32 v63, v38, v19
	v_fmac_f32_e32 v70, v40, v19
	v_fmac_f32_e32 v71, v37, v19
	v_fmac_f32_e32 v72, v39, v19
	v_fmac_f32_e32 v28, v41, v19
	v_fmac_f32_e32 v29, v42, v19
	v_fmac_f32_e32 v26, v43, v19
	v_fmac_f32_e32 v27, v44, v19
	v_fmac_f32_e32 v24, v30, v19
	v_fmac_f32_e32 v25, v32, v19
	v_fmac_f32_e32 v22, v9, v19
	v_fmac_f32_e32 v23, v31, v19
	v_fmac_f32_e32 v20, v33, v19
	v_fmac_f32_e32 v21, v34, v19
	v_fmac_f32_e32 v18, v35, v19
	v_fma_f32 v19, v36, v19, v49
	v_fmac_f32_e32 v63, v53, v16
	v_fmac_f32_e32 v70, v38, v16
	v_fmac_f32_e32 v71, v40, v16
	v_fmac_f32_e32 v72, v37, v16
	v_fmac_f32_e32 v28, v39, v16
	v_fmac_f32_e32 v29, v41, v16
	v_fmac_f32_e32 v26, v42, v16
	v_fmac_f32_e32 v27, v43, v16
	v_fmac_f32_e32 v24, v44, v16
	v_fmac_f32_e32 v25, v30, v16
	v_fmac_f32_e32 v22, v32, v16
	v_fmac_f32_e32 v23, v9, v16
	v_fmac_f32_e32 v20, v31, v16
	v_fmac_f32_e32 v21, v33, v16
	v_fmac_f32_e32 v18, v34, v16
	v_fmac_f32_e32 v19, v35, v16
	v_fma_f32 v16, v36, v16, v49
	v_fmac_f32_e32 v63, v60, v17
	v_fmac_f32_e32 v70, v53, v17
	v_fmac_f32_e32 v71, v38, v17
	v_fmac_f32_e32 v72, v40, v17
	v_fmac_f32_e32 v28, v37, v17
	v_fmac_f32_e32 v29, v39, v17
	v_fmac_f32_e32 v26, v41, v17
	v_fmac_f32_e32 v27, v42, v17
	v_fmac_f32_e32 v24, v43, v17
	v_fmac_f32_e32 v25, v44, v17
	v_fmac_f32_e32 v22, v30, v17
	v_fmac_f32_e32 v23, v32, v17
	v_fmac_f32_e32 v20, v9, v17
	v_fmac_f32_e32 v21, v31, v17
	v_fmac_f32_e32 v18, v33, v17
	v_fmac_f32_e32 v19, v34, v17
	v_fmac_f32_e32 v16, v35, v17
	v_fma_f32 v17, v36, v17, v49
	v_fmac_f32_e32 v63, v52, v14
	v_fmac_f32_e32 v70, v60, v14
	v_fmac_f32_e32 v71, v53, v14
	v_fmac_f32_e32 v72, v38, v14
	v_fmac_f32_e32 v28, v40, v14
	v_fmac_f32_e32 v29, v37, v14
	v_fmac_f32_e32 v26, v39, v14
	v_fmac_f32_e32 v27, v41, v14
	v_fmac_f32_e32 v24, v42, v14
	v_fmac_f32_e32 v25, v43, v14
	v_fmac_f32_e32 v22, v44, v14
	v_fmac_f32_e32 v23, v30, v14
	v_fmac_f32_e32 v20, v32, v14
	v_fmac_f32_e32 v21, v9, v14
	v_fmac_f32_e32 v18, v31, v14
	v_fmac_f32_e32 v19, v33, v14
	v_fmac_f32_e32 v16, v34, v14
	v_fmac_f32_e32 v17, v35, v14
	v_fma_f32 v14, v36, v14, v49
	v_fmac_f32_e32 v63, v51, v15
	v_fmac_f32_e32 v70, v52, v15
	v_fmac_f32_e32 v71, v60, v15
	v_fmac_f32_e32 v72, v53, v15
	v_fmac_f32_e32 v28, v38, v15
	v_fmac_f32_e32 v29, v40, v15
	v_fmac_f32_e32 v26, v37, v15
	v_fmac_f32_e32 v27, v39, v15
	v_fmac_f32_e32 v24, v41, v15
	v_fmac_f32_e32 v25, v42, v15
	v_fmac_f32_e32 v22, v43, v15
	v_fmac_f32_e32 v23, v44, v15
	v_fmac_f32_e32 v20, v30, v15
	v_fmac_f32_e32 v21, v32, v15
	v_fmac_f32_e32 v18, v9, v15
	v_fmac_f32_e32 v19, v31, v15
	v_fmac_f32_e32 v16, v33, v15
	v_fmac_f32_e32 v17, v34, v15
	v_fmac_f32_e32 v14, v35, v15
	v_fma_f32 v15, v36, v15, v49
	v_fmac_f32_e32 v63, v50, v12
	v_fmac_f32_e32 v70, v51, v12
	v_fmac_f32_e32 v71, v52, v12
	v_fmac_f32_e32 v72, v60, v12
	v_fmac_f32_e32 v28, v53, v12
	v_fmac_f32_e32 v29, v38, v12
	v_fmac_f32_e32 v26, v40, v12
	v_fmac_f32_e32 v27, v37, v12
	v_fmac_f32_e32 v24, v39, v12
	v_fmac_f32_e32 v25, v41, v12
	v_fmac_f32_e32 v22, v42, v12
	v_fmac_f32_e32 v23, v43, v12
	v_fmac_f32_e32 v20, v44, v12
	v_fmac_f32_e32 v21, v30, v12
	v_fmac_f32_e32 v18, v32, v12
	v_fmac_f32_e32 v19, v9, v12
	v_fmac_f32_e32 v16, v31, v12
	v_fmac_f32_e32 v17, v33, v12
	v_fmac_f32_e32 v14, v34, v12
	v_fmac_f32_e32 v15, v35, v12
	v_fma_f32 v12, v36, v12, v49
	v_fmac_f32_e32 v63, v59, v13
	v_fmac_f32_e32 v70, v50, v13
	v_fmac_f32_e32 v71, v51, v13
	v_fmac_f32_e32 v72, v52, v13
	v_fmac_f32_e32 v28, v60, v13
; __device__ __forceinline__ void conv_phase(LAS unsigned char* lds, const bf16_t* PROJ, const float* cw, const float* cb, const float* lg, const float* lb, bf16_t* MIXIN, int G, int tid) {
;     ...
;         for (int blk = 0; blk < 4; ++blk) { float win[38];
; #pragma unroll
;             for (int x = 0; x < 38; ++x) win[x] = U[(8 * blk + x) * 512 + c];
; #pragma unroll
;             for (int o = 0; o < 8; ++o) { float acc = bias;
; #pragma unroll
;                 for (int k = 0; k < 31; ++k) acc += w[k] * win[o + k];
;                 y[8 * blk + o] = acc; } }
	v_fmac_f32_e32 v29, v53, v13
	v_fmac_f32_e32 v26, v38, v13
	v_fmac_f32_e32 v27, v40, v13
	v_fmac_f32_e32 v24, v37, v13
	v_fmac_f32_e32 v25, v39, v13
	v_fmac_f32_e32 v22, v41, v13
	v_fmac_f32_e32 v23, v42, v13
	v_fmac_f32_e32 v20, v43, v13
	v_fmac_f32_e32 v21, v44, v13
	v_fmac_f32_e32 v18, v30, v13
	v_fmac_f32_e32 v19, v32, v13
	v_fmac_f32_e32 v16, v9, v13
	v_fmac_f32_e32 v17, v31, v13
	v_fmac_f32_e32 v14, v33, v13
	v_fmac_f32_e32 v15, v34, v13
	v_fmac_f32_e32 v12, v35, v13
	v_fma_f32 v13, v36, v13, v49
	v_fmac_f32_e32 v63, v47, v10
	v_fmac_f32_e32 v70, v59, v10
	v_fmac_f32_e32 v71, v50, v10
	v_fmac_f32_e32 v72, v51, v10
	v_fmac_f32_e32 v28, v52, v10
	v_fmac_f32_e32 v29, v60, v10
	v_fmac_f32_e32 v26, v53, v10
	v_fmac_f32_e32 v27, v38, v10
	v_fmac_f32_e32 v24, v40, v10
	v_fmac_f32_e32 v25, v37, v10
	v_fmac_f32_e32 v22, v39, v10
	v_fmac_f32_e32 v23, v41, v10
	v_fmac_f32_e32 v20, v42, v10
	v_fmac_f32_e32 v21, v43, v10
	v_fmac_f32_e32 v18, v44, v10
	v_fmac_f32_e32 v19, v30, v10
	v_fmac_f32_e32 v16, v32, v10
	v_fmac_f32_e32 v17, v9, v10
	v_fmac_f32_e32 v14, v31, v10
	v_fmac_f32_e32 v15, v33, v10
	v_fmac_f32_e32 v12, v34, v10
	v_fmac_f32_e32 v13, v35, v10
	v_fma_f32 v10, v36, v10, v49
	v_fmac_f32_e32 v63, v46, v11
	v_fmac_f32_e32 v70, v47, v11
	v_fmac_f32_e32 v71, v59, v11
	v_fmac_f32_e32 v72, v50, v11
	v_fmac_f32_e32 v28, v51, v11
	v_fmac_f32_e32 v29, v52, v11
	v_fmac_f32_e32 v26, v60, v11
	v_fmac_f32_e32 v27, v53, v11
	v_fmac_f32_e32 v24, v38, v11
	v_fmac_f32_e32 v25, v40, v11
	v_fmac_f32_e32 v22, v37, v11
	v_fmac_f32_e32 v23, v39, v11
	v_fmac_f32_e32 v20, v41, v11
	v_fmac_f32_e32 v21, v42, v11
	v_fmac_f32_e32 v18, v43, v11
	v_fmac_f32_e32 v19, v44, v11
	v_fmac_f32_e32 v16, v30, v11
	v_fmac_f32_e32 v17, v32, v11
	v_fmac_f32_e32 v14, v9, v11
	v_fmac_f32_e32 v15, v31, v11
	v_fmac_f32_e32 v12, v33, v11
	v_fmac_f32_e32 v13, v34, v11
	v_fmac_f32_e32 v10, v35, v11
	v_fma_f32 v11, v36, v11, v49
	v_fmac_f32_e32 v63, v48, v6
	v_fmac_f32_e32 v70, v46, v6
	v_fmac_f32_e32 v71, v47, v6
	v_fmac_f32_e32 v72, v59, v6
	v_fmac_f32_e32 v28, v50, v6
	v_fmac_f32_e32 v29, v51, v6
	v_fmac_f32_e32 v26, v52, v6
	v_fmac_f32_e32 v27, v60, v6
	v_fmac_f32_e32 v24, v53, v6
	v_fmac_f32_e32 v25, v38, v6
	v_fmac_f32_e32 v22, v40, v6
	v_fmac_f32_e32 v23, v37, v6
	v_fmac_f32_e32 v20, v39, v6
	v_fmac_f32_e32 v21, v41, v6
	v_fmac_f32_e32 v18, v42, v6
	v_fmac_f32_e32 v19, v43, v6
	v_fmac_f32_e32 v16, v44, v6
	v_fmac_f32_e32 v17, v30, v6
	v_fmac_f32_e32 v14, v32, v6
	v_fmac_f32_e32 v15, v9, v6
	v_fmac_f32_e32 v12, v31, v6
	v_fmac_f32_e32 v13, v33, v6
	v_fmac_f32_e32 v10, v34, v6
	v_fmac_f32_e32 v11, v35, v6
	v_fma_f32 v6, v36, v6, v49
	v_fmac_f32_e32 v63, v56, v7
	v_fmac_f32_e32 v70, v48, v7
	v_fmac_f32_e32 v71, v46, v7
	v_fmac_f32_e32 v72, v47, v7
	v_fmac_f32_e32 v28, v59, v7
	v_fmac_f32_e32 v29, v50, v7
	v_fmac_f32_e32 v26, v51, v7
	v_fmac_f32_e32 v27, v52, v7
	v_fmac_f32_e32 v24, v60, v7
	v_fmac_f32_e32 v25, v53, v7
	v_fmac_f32_e32 v22, v38, v7
	v_fmac_f32_e32 v23, v40, v7
	v_fmac_f32_e32 v20, v37, v7
	v_fmac_f32_e32 v21, v39, v7
	v_fmac_f32_e32 v18, v41, v7
	v_fmac_f32_e32 v19, v42, v7
	v_fmac_f32_e32 v16, v43, v7
	v_fmac_f32_e32 v17, v44, v7
	v_fmac_f32_e32 v14, v30, v7
	v_fmac_f32_e32 v15, v32, v7
	v_fmac_f32_e32 v12, v9, v7
	v_fmac_f32_e32 v13, v31, v7
	v_fmac_f32_e32 v10, v33, v7
	v_fmac_f32_e32 v11, v34, v7
	v_fmac_f32_e32 v6, v35, v7
	v_fma_f32 v7, v36, v7, v49
	v_fmac_f32_e32 v63, v45, v4
	v_fmac_f32_e32 v70, v56, v4
	v_fmac_f32_e32 v71, v48, v4
	v_fmac_f32_e32 v72, v46, v4
	v_fmac_f32_e32 v28, v47, v4
	v_fmac_f32_e32 v29, v59, v4
	v_fmac_f32_e32 v26, v50, v4
	v_fmac_f32_e32 v27, v51, v4
	v_fmac_f32_e32 v24, v52, v4
	v_fmac_f32_e32 v25, v60, v4
	v_fmac_f32_e32 v22, v53, v4
	v_fmac_f32_e32 v23, v38, v4
	v_fmac_f32_e32 v20, v40, v4
	v_fmac_f32_e32 v21, v37, v4
	v_fmac_f32_e32 v18, v39, v4
	v_fmac_f32_e32 v19, v41, v4
	v_fmac_f32_e32 v16, v42, v4
	v_fmac_f32_e32 v17, v43, v4
	v_fmac_f32_e32 v14, v44, v4
	v_fmac_f32_e32 v15, v30, v4
	v_fmac_f32_e32 v12, v32, v4
	v_fmac_f32_e32 v13, v9, v4
	v_fmac_f32_e32 v10, v31, v4
	v_fmac_f32_e32 v11, v33, v4
	v_fmac_f32_e32 v6, v34, v4
	v_fmac_f32_e32 v7, v35, v4
	v_fma_f32 v4, v36, v4, v49
	v_fmac_f32_e32 v63, v58, v5
	v_fmac_f32_e32 v70, v45, v5
	v_fmac_f32_e32 v71, v56, v5
	v_fmac_f32_e32 v72, v48, v5
	v_fmac_f32_e32 v28, v46, v5
	v_fmac_f32_e32 v29, v47, v5
	v_fmac_f32_e32 v26, v59, v5
	v_fmac_f32_e32 v27, v50, v5
	v_fmac_f32_e32 v24, v51, v5
	v_fmac_f32_e32 v25, v52, v5
	v_fmac_f32_e32 v22, v60, v5
	v_fmac_f32_e32 v23, v53, v5
	v_fmac_f32_e32 v20, v38, v5
	v_fmac_f32_e32 v21, v40, v5
	v_fmac_f32_e32 v18, v37, v5
	v_fmac_f32_e32 v19, v39, v5
	v_fmac_f32_e32 v16, v41, v5
	v_fmac_f32_e32 v17, v42, v5
	v_fmac_f32_e32 v14, v43, v5
	v_fmac_f32_e32 v15, v44, v5
	v_fmac_f32_e32 v12, v30, v5
	v_fmac_f32_e32 v13, v32, v5
	v_fmac_f32_e32 v10, v9, v5
	v_fmac_f32_e32 v11, v31, v5
	v_fmac_f32_e32 v6, v33, v5
	v_fmac_f32_e32 v7, v34, v5
	v_fmac_f32_e32 v4, v35, v5
	v_fma_f32 v5, v36, v5, v49
	v_fmac_f32_e32 v63, v57, v2
	v_fmac_f32_e32 v70, v58, v2
	v_fmac_f32_e32 v71, v45, v2
	v_fmac_f32_e32 v72, v56, v2
	v_fmac_f32_e32 v28, v48, v2
	v_fmac_f32_e32 v29, v46, v2
	v_fmac_f32_e32 v26, v47, v2
	v_fmac_f32_e32 v27, v59, v2
	v_fmac_f32_e32 v24, v50, v2
	v_fmac_f32_e32 v25, v51, v2
	v_fmac_f32_e32 v22, v52, v2
	v_fmac_f32_e32 v23, v60, v2
	v_fmac_f32_e32 v20, v53, v2
	v_fmac_f32_e32 v21, v38, v2
	v_fmac_f32_e32 v18, v40, v2
	v_fmac_f32_e32 v19, v37, v2
	v_fmac_f32_e32 v16, v39, v2
	v_fmac_f32_e32 v17, v41, v2
	v_fmac_f32_e32 v14, v42, v2
	v_fmac_f32_e32 v15, v43, v2
	v_fmac_f32_e32 v12, v44, v2
	v_fmac_f32_e32 v13, v30, v2
	v_fmac_f32_e32 v10, v32, v2
; __device__ __forceinline__ void conv_phase(LAS unsigned char* lds, const bf16_t* PROJ, const float* cw, const float* cb, const float* lg, const float* lb, bf16_t* MIXIN, int G, int tid) {
;     ...
;         for (int blk = 0; blk < 4; ++blk) { float win[38];
; #pragma unroll
;             for (int x = 0; x < 38; ++x) win[x] = U[(8 * blk + x) * 512 + c];
; #pragma unroll
;             for (int o = 0; o < 8; ++o) { float acc = bias;
; #pragma unroll
;                 for (int k = 0; k < 31; ++k) acc += w[k] * win[o + k];
;                 y[8 * blk + o] = acc; } }
	v_fmac_f32_e32 v11, v9, v2
	v_fmac_f32_e32 v6, v31, v2
	v_fmac_f32_e32 v7, v33, v2
	v_fmac_f32_e32 v4, v34, v2
	v_fmac_f32_e32 v5, v35, v2
	v_fma_f32 v2, v36, v2, v49
	v_fmac_f32_e32 v63, v54, v3
	v_fmac_f32_e32 v70, v57, v3
	v_fmac_f32_e32 v71, v58, v3
	v_fmac_f32_e32 v72, v45, v3
	v_fmac_f32_e32 v28, v56, v3
	v_fmac_f32_e32 v29, v48, v3
	v_fmac_f32_e32 v26, v46, v3
	v_fmac_f32_e32 v27, v47, v3
	v_fmac_f32_e32 v24, v59, v3
	v_fmac_f32_e32 v25, v50, v3
	v_fmac_f32_e32 v22, v51, v3
	v_fmac_f32_e32 v23, v52, v3
	v_fmac_f32_e32 v20, v60, v3
	v_fmac_f32_e32 v21, v53, v3
	v_fmac_f32_e32 v18, v38, v3
	v_fmac_f32_e32 v19, v40, v3
	v_fmac_f32_e32 v16, v37, v3
	v_fmac_f32_e32 v17, v39, v3
	v_fmac_f32_e32 v14, v41, v3
	v_fmac_f32_e32 v15, v42, v3
	v_fmac_f32_e32 v12, v43, v3
	v_fmac_f32_e32 v13, v44, v3
	v_fmac_f32_e32 v10, v30, v3
	v_fmac_f32_e32 v11, v32, v3
	v_fmac_f32_e32 v6, v9, v3
	v_fmac_f32_e32 v7, v31, v3
	v_fmac_f32_e32 v4, v33, v3
	v_fmac_f32_e32 v5, v34, v3
	v_fmac_f32_e32 v2, v35, v3
	v_fma_f32 v3, v36, v3, v49
	v_fmac_f32_e32 v63, v55, v0
	v_fmac_f32_e32 v70, v54, v0
	v_fmac_f32_e32 v71, v57, v0
	v_fmac_f32_e32 v72, v58, v0
	v_fmac_f32_e32 v28, v45, v0
	v_fmac_f32_e32 v29, v56, v0
	v_fmac_f32_e32 v26, v48, v0
	v_fmac_f32_e32 v27, v46, v0
	v_fmac_f32_e32 v24, v47, v0
	v_fmac_f32_e32 v25, v59, v0
	v_fmac_f32_e32 v22, v50, v0
	v_fmac_f32_e32 v23, v51, v0
	v_fmac_f32_e32 v20, v52, v0
	v_fmac_f32_e32 v21, v60, v0
	v_fmac_f32_e32 v18, v53, v0
	v_fmac_f32_e32 v19, v38, v0
	v_fmac_f32_e32 v16, v40, v0
	v_fmac_f32_e32 v17, v37, v0
	v_fmac_f32_e32 v14, v39, v0
	v_fmac_f32_e32 v15, v41, v0
	v_fmac_f32_e32 v12, v42, v0
	v_fmac_f32_e32 v13, v43, v0
	v_fmac_f32_e32 v10, v44, v0
	v_fmac_f32_e32 v11, v30, v0
	v_fmac_f32_e32 v6, v32, v0
	v_fmac_f32_e32 v7, v9, v0
	v_fmac_f32_e32 v4, v31, v0
	v_fmac_f32_e32 v5, v33, v0
	v_fmac_f32_e32 v2, v34, v0
	v_fmac_f32_e32 v3, v35, v0
	v_fma_f32 v0, v36, v0, v49
	v_fmac_f32_e32 v0, v35, v1
	v_fmac_f32_e32 v49, v36, v1
	v_add_u32_e32 v73, 0x13000, v62
	v_fmac_f32_e32 v0, v34, v64
	v_fmac_f32_e32 v49, v35, v64
	ds_read_b32 v73, v73
	v_fmac_f32_e32 v3, v34, v1
	v_fmac_f32_e32 v0, v33, v65
	v_fmac_f32_e32 v49, v34, v65
	v_fmac_f32_e32 v2, v33, v1
	v_fmac_f32_e32 v3, v33, v64
	v_fmac_f32_e32 v0, v31, v66
	v_fmac_f32_e32 v49, v33, v66
	v_fmac_f32_e32 v5, v31, v1
	v_fmac_f32_e32 v2, v31, v64
	v_fmac_f32_e32 v3, v31, v65
	s_waitcnt lgkmcnt(12)
	v_fmac_f32_e32 v0, v9, v67
	v_fmac_f32_e32 v49, v31, v67
	v_fmac_f32_e32 v4, v9, v1
	v_fmac_f32_e32 v5, v9, v64
	v_fmac_f32_e32 v2, v9, v65
	v_fmac_f32_e32 v3, v9, v66
	s_waitcnt lgkmcnt(8)
	v_fmac_f32_e32 v0, v32, v68
	v_fmac_f32_e32 v49, v9, v68
	v_add_u32_e32 v80, 0x16800, v62
	v_add_u32_e32 v87, 0x1a000, v62
	v_add_u32_e32 v94, 0x1d800, v62
	v_fmac_f32_e32 v7, v32, v1
	v_fmac_f32_e32 v4, v32, v64
	v_fmac_f32_e32 v5, v32, v65
	v_fmac_f32_e32 v2, v32, v66
	v_fmac_f32_e32 v3, v32, v67
	s_waitcnt lgkmcnt(4)
	v_fmac_f32_e32 v0, v30, v69
	v_fmac_f32_e32 v49, v32, v69
	ds_read_b32 v80, v80
	ds_read_b32 v87, v87
	ds_read_b32 v94, v94
	v_fmac_f32_e32 v6, v30, v1
	v_fmac_f32_e32 v7, v30, v64
	v_fmac_f32_e32 v4, v30, v65
	v_fmac_f32_e32 v5, v30, v66
	v_fmac_f32_e32 v2, v30, v67
	v_fmac_f32_e32 v3, v30, v68
	s_waitcnt lgkmcnt(3)
	v_fmac_f32_e32 v0, v44, v73
	v_fmac_f32_e32 v49, v30, v73
	v_fmac_f32_e32 v11, v44, v1
	v_fmac_f32_e32 v6, v44, v64
	v_fmac_f32_e32 v7, v44, v65
	v_fmac_f32_e32 v4, v44, v66
	v_fmac_f32_e32 v5, v44, v67
	v_fmac_f32_e32 v2, v44, v68
	v_fmac_f32_e32 v3, v44, v69
	v_fmac_f32_e32 v0, v43, v74
	v_fmac_f32_e32 v49, v44, v74
	v_fmac_f32_e32 v10, v43, v1
	v_fmac_f32_e32 v11, v43, v64
	v_fmac_f32_e32 v6, v43, v65
	v_fmac_f32_e32 v7, v43, v66
	v_fmac_f32_e32 v4, v43, v67
	v_fmac_f32_e32 v5, v43, v68
	v_fmac_f32_e32 v2, v43, v69
	v_fmac_f32_e32 v3, v43, v73
	v_fmac_f32_e32 v0, v42, v75
	v_fmac_f32_e32 v49, v43, v75
	v_fmac_f32_e32 v13, v42, v1
	v_fmac_f32_e32 v10, v42, v64
	v_fmac_f32_e32 v11, v42, v65
	v_fmac_f32_e32 v6, v42, v66
	v_fmac_f32_e32 v7, v42, v67
	v_fmac_f32_e32 v4, v42, v68
	v_fmac_f32_e32 v5, v42, v69
	v_fmac_f32_e32 v2, v42, v73
	v_fmac_f32_e32 v3, v42, v74
	v_fmac_f32_e32 v0, v41, v76
	v_fmac_f32_e32 v49, v42, v76
	v_fmac_f32_e32 v12, v41, v1
	v_fmac_f32_e32 v13, v41, v64
	v_fmac_f32_e32 v10, v41, v65
	v_fmac_f32_e32 v11, v41, v66
	v_fmac_f32_e32 v6, v41, v67
	v_fmac_f32_e32 v7, v41, v68
	v_fmac_f32_e32 v4, v41, v69
	v_fmac_f32_e32 v5, v41, v73
	v_fmac_f32_e32 v2, v41, v74
	v_fmac_f32_e32 v3, v41, v75
	v_fmac_f32_e32 v0, v39, v77
	v_fmac_f32_e32 v49, v41, v77
	v_fmac_f32_e32 v15, v39, v1
	v_fmac_f32_e32 v12, v39, v64
	v_fmac_f32_e32 v13, v39, v65
	v_fmac_f32_e32 v10, v39, v66
	v_fmac_f32_e32 v11, v39, v67
	v_fmac_f32_e32 v6, v39, v68
	v_fmac_f32_e32 v7, v39, v69
	v_fmac_f32_e32 v4, v39, v73
	v_fmac_f32_e32 v5, v39, v74
	v_fmac_f32_e32 v2, v39, v75
	v_fmac_f32_e32 v3, v39, v76
	v_fmac_f32_e32 v0, v37, v78
	v_fmac_f32_e32 v49, v39, v78
	v_fmac_f32_e32 v14, v37, v1
	v_fmac_f32_e32 v15, v37, v64
	v_fmac_f32_e32 v12, v37, v65
	v_fmac_f32_e32 v13, v37, v66
	v_fmac_f32_e32 v10, v37, v67
	v_fmac_f32_e32 v11, v37, v68
	v_fmac_f32_e32 v6, v37, v69
	v_fmac_f32_e32 v7, v37, v73
	v_fmac_f32_e32 v4, v37, v74
	v_fmac_f32_e32 v5, v37, v75
	v_fmac_f32_e32 v2, v37, v76
	v_fmac_f32_e32 v3, v37, v77
	v_fmac_f32_e32 v0, v40, v79
	v_fmac_f32_e32 v49, v37, v79
	v_fmac_f32_e32 v17, v40, v1
	v_fmac_f32_e32 v14, v40, v64
	v_fmac_f32_e32 v15, v40, v65
	v_fmac_f32_e32 v12, v40, v66
	v_fmac_f32_e32 v13, v40, v67
	v_fmac_f32_e32 v10, v40, v68
	v_fmac_f32_e32 v11, v40, v69
	v_fmac_f32_e32 v6, v40, v73
	v_fmac_f32_e32 v7, v40, v74
	v_fmac_f32_e32 v4, v40, v75
	v_fmac_f32_e32 v5, v40, v76
	v_fmac_f32_e32 v2, v40, v77
	v_fmac_f32_e32 v3, v40, v78
	s_waitcnt lgkmcnt(2)
; __device__ __forceinline__ void conv_phase(LAS unsigned char* lds, const bf16_t* PROJ, const float* cw, const float* cb, const float* lg, const float* lb, bf16_t* MIXIN, int G, int tid) {
;     ...
;         for (int blk = 0; blk < 4; ++blk) { float win[38];
; #pragma unroll
;             for (int x = 0; x < 38; ++x) win[x] = U[(8 * blk + x) * 512 + c];
; #pragma unroll
;             for (int o = 0; o < 8; ++o) { float acc = bias;
; #pragma unroll
;                 for (int k = 0; k < 31; ++k) acc += w[k] * win[o + k];
;                 y[8 * blk + o] = acc; } }
	v_fmac_f32_e32 v0, v38, v80
	v_fmac_f32_e32 v49, v40, v80
	v_fmac_f32_e32 v16, v38, v1
	v_fmac_f32_e32 v17, v38, v64
	v_fmac_f32_e32 v14, v38, v65
	v_fmac_f32_e32 v15, v38, v66
	v_fmac_f32_e32 v12, v38, v67
	v_fmac_f32_e32 v13, v38, v68
	v_fmac_f32_e32 v10, v38, v69
	v_fmac_f32_e32 v11, v38, v73
	v_fmac_f32_e32 v6, v38, v74
	v_fmac_f32_e32 v7, v38, v75
	v_fmac_f32_e32 v4, v38, v76
	v_fmac_f32_e32 v5, v38, v77
	v_fmac_f32_e32 v2, v38, v78
	v_fmac_f32_e32 v3, v38, v79
	v_fmac_f32_e32 v0, v53, v81
	v_fmac_f32_e32 v49, v38, v81
	v_fmac_f32_e32 v19, v53, v1
	v_fmac_f32_e32 v16, v53, v64
	v_fmac_f32_e32 v17, v53, v65
	v_fmac_f32_e32 v14, v53, v66
	v_fmac_f32_e32 v15, v53, v67
	v_fmac_f32_e32 v12, v53, v68
	v_fmac_f32_e32 v13, v53, v69
	v_fmac_f32_e32 v10, v53, v73
	v_fmac_f32_e32 v11, v53, v74
	v_fmac_f32_e32 v6, v53, v75
	v_fmac_f32_e32 v7, v53, v76
	v_fmac_f32_e32 v4, v53, v77
	v_fmac_f32_e32 v5, v53, v78
	v_fmac_f32_e32 v2, v53, v79
	v_fmac_f32_e32 v3, v53, v80
	v_fmac_f32_e32 v0, v60, v82
	v_fmac_f32_e32 v49, v53, v82
	v_fmac_f32_e32 v18, v60, v1
	v_fmac_f32_e32 v19, v60, v64
	v_fmac_f32_e32 v16, v60, v65
	v_fmac_f32_e32 v17, v60, v66
	v_fmac_f32_e32 v14, v60, v67
	v_fmac_f32_e32 v15, v60, v68
	v_fmac_f32_e32 v12, v60, v69
	v_fmac_f32_e32 v13, v60, v73
	v_fmac_f32_e32 v10, v60, v74
	v_fmac_f32_e32 v11, v60, v75
	v_fmac_f32_e32 v6, v60, v76
	v_fmac_f32_e32 v7, v60, v77
	v_fmac_f32_e32 v4, v60, v78
	v_fmac_f32_e32 v5, v60, v79
	v_fmac_f32_e32 v2, v60, v80
	v_fmac_f32_e32 v3, v60, v81
	v_fmac_f32_e32 v0, v52, v83
	v_fmac_f32_e32 v49, v60, v83
	v_fmac_f32_e32 v21, v52, v1
	v_fmac_f32_e32 v18, v52, v64
	v_fmac_f32_e32 v19, v52, v65
	v_fmac_f32_e32 v16, v52, v66
	v_fmac_f32_e32 v17, v52, v67
	v_fmac_f32_e32 v14, v52, v68
	v_fmac_f32_e32 v15, v52, v69
	v_fmac_f32_e32 v12, v52, v73
	v_fmac_f32_e32 v13, v52, v74
	v_fmac_f32_e32 v10, v52, v75
	v_fmac_f32_e32 v11, v52, v76
	v_fmac_f32_e32 v6, v52, v77
	v_fmac_f32_e32 v7, v52, v78
	v_fmac_f32_e32 v4, v52, v79
	v_fmac_f32_e32 v5, v52, v80
	v_fmac_f32_e32 v2, v52, v81
	v_fmac_f32_e32 v3, v52, v82
	v_fmac_f32_e32 v0, v51, v84
	v_fmac_f32_e32 v49, v52, v84
	v_fmac_f32_e32 v20, v51, v1
	v_fmac_f32_e32 v21, v51, v64
	v_fmac_f32_e32 v18, v51, v65
	v_fmac_f32_e32 v19, v51, v66
	v_fmac_f32_e32 v16, v51, v67
	v_fmac_f32_e32 v17, v51, v68
	v_fmac_f32_e32 v14, v51, v69
	v_fmac_f32_e32 v15, v51, v73
	v_fmac_f32_e32 v12, v51, v74
	v_fmac_f32_e32 v13, v51, v75
	v_fmac_f32_e32 v10, v51, v76
	v_fmac_f32_e32 v11, v51, v77
	v_fmac_f32_e32 v6, v51, v78
	v_fmac_f32_e32 v7, v51, v79
	v_fmac_f32_e32 v4, v51, v80
	v_fmac_f32_e32 v5, v51, v81
	v_fmac_f32_e32 v2, v51, v82
	v_fmac_f32_e32 v3, v51, v83
	v_fmac_f32_e32 v0, v50, v85
	v_fmac_f32_e32 v49, v51, v85
	v_fmac_f32_e32 v23, v50, v1
	v_fmac_f32_e32 v20, v50, v64
	v_fmac_f32_e32 v21, v50, v65
	v_fmac_f32_e32 v18, v50, v66
	v_fmac_f32_e32 v19, v50, v67
	v_fmac_f32_e32 v16, v50, v68
	v_fmac_f32_e32 v17, v50, v69
	v_fmac_f32_e32 v14, v50, v73
	v_fmac_f32_e32 v15, v50, v74
	v_fmac_f32_e32 v12, v50, v75
	v_fmac_f32_e32 v13, v50, v76
	v_fmac_f32_e32 v10, v50, v77
	v_fmac_f32_e32 v11, v50, v78
	v_fmac_f32_e32 v6, v50, v79
	v_fmac_f32_e32 v7, v50, v80
	v_fmac_f32_e32 v4, v50, v81
	v_fmac_f32_e32 v5, v50, v82
	v_fmac_f32_e32 v2, v50, v83
	v_fmac_f32_e32 v3, v50, v84
	v_fmac_f32_e32 v0, v59, v86
	v_fmac_f32_e32 v49, v50, v86
	v_fmac_f32_e32 v22, v59, v1
	v_fmac_f32_e32 v23, v59, v64
	v_fmac_f32_e32 v20, v59, v65
	v_fmac_f32_e32 v21, v59, v66
	v_fmac_f32_e32 v18, v59, v67
	v_fmac_f32_e32 v19, v59, v68
	v_fmac_f32_e32 v16, v59, v69
	v_fmac_f32_e32 v17, v59, v73
	v_fmac_f32_e32 v14, v59, v74
	v_fmac_f32_e32 v15, v59, v75
	v_fmac_f32_e32 v12, v59, v76
	v_fmac_f32_e32 v13, v59, v77
	v_fmac_f32_e32 v10, v59, v78
	v_fmac_f32_e32 v11, v59, v79
	v_fmac_f32_e32 v6, v59, v80
	v_fmac_f32_e32 v7, v59, v81
	v_fmac_f32_e32 v4, v59, v82
	v_fmac_f32_e32 v5, v59, v83
	v_fmac_f32_e32 v2, v59, v84
	v_fmac_f32_e32 v3, v59, v85
	s_waitcnt lgkmcnt(1)
	v_fmac_f32_e32 v0, v47, v87
	v_fmac_f32_e32 v49, v59, v87
	v_fmac_f32_e32 v25, v47, v1
	v_fmac_f32_e32 v22, v47, v64
	v_fmac_f32_e32 v23, v47, v65
	v_fmac_f32_e32 v20, v47, v66
	v_fmac_f32_e32 v21, v47, v67
	v_fmac_f32_e32 v18, v47, v68
	v_fmac_f32_e32 v19, v47, v69
	v_fmac_f32_e32 v16, v47, v73
	v_fmac_f32_e32 v17, v47, v74
	v_fmac_f32_e32 v14, v47, v75
	v_fmac_f32_e32 v15, v47, v76
	v_fmac_f32_e32 v12, v47, v77
	v_fmac_f32_e32 v13, v47, v78
	v_fmac_f32_e32 v10, v47, v79
	v_fmac_f32_e32 v11, v47, v80
	v_fmac_f32_e32 v6, v47, v81
	v_fmac_f32_e32 v7, v47, v82
	v_fmac_f32_e32 v4, v47, v83
	v_fmac_f32_e32 v5, v47, v84
	v_fmac_f32_e32 v2, v47, v85
	v_fmac_f32_e32 v3, v47, v86
	v_fmac_f32_e32 v0, v46, v88
	v_fmac_f32_e32 v49, v47, v88
	v_fmac_f32_e32 v24, v46, v1
	v_fmac_f32_e32 v25, v46, v64
	v_fmac_f32_e32 v22, v46, v65
	v_fmac_f32_e32 v23, v46, v66
	v_fmac_f32_e32 v20, v46, v67
	v_fmac_f32_e32 v21, v46, v68
	v_fmac_f32_e32 v18, v46, v69
	v_fmac_f32_e32 v19, v46, v73
	v_fmac_f32_e32 v16, v46, v74
	v_fmac_f32_e32 v17, v46, v75
	v_fmac_f32_e32 v14, v46, v76
	v_fmac_f32_e32 v15, v46, v77
	v_fmac_f32_e32 v12, v46, v78
	v_fmac_f32_e32 v13, v46, v79
	v_fmac_f32_e32 v10, v46, v80
	v_fmac_f32_e32 v11, v46, v81
	v_fmac_f32_e32 v6, v46, v82
	v_fmac_f32_e32 v7, v46, v83
	v_fmac_f32_e32 v4, v46, v84
	v_fmac_f32_e32 v5, v46, v85
	v_fmac_f32_e32 v2, v46, v86
	v_fmac_f32_e32 v3, v46, v87
	v_fmac_f32_e32 v0, v48, v89
	v_fmac_f32_e32 v49, v46, v89
	v_fmac_f32_e32 v27, v48, v1
	v_fmac_f32_e32 v24, v48, v64
	v_fmac_f32_e32 v25, v48, v65
	v_fmac_f32_e32 v22, v48, v66
	v_fmac_f32_e32 v23, v48, v67
	v_fmac_f32_e32 v20, v48, v68
	v_fmac_f32_e32 v21, v48, v69
	v_fmac_f32_e32 v18, v48, v73
; __device__ __forceinline__ void conv_phase(LAS unsigned char* lds, const bf16_t* PROJ, const float* cw, const float* cb, const float* lg, const float* lb, bf16_t* MIXIN, int G, int tid) {
;     ...
;         for (int blk = 0; blk < 4; ++blk) { float win[38];
; #pragma unroll
;             for (int x = 0; x < 38; ++x) win[x] = U[(8 * blk + x) * 512 + c];
; #pragma unroll
;             for (int o = 0; o < 8; ++o) { float acc = bias;
; #pragma unroll
;                 for (int k = 0; k < 31; ++k) acc += w[k] * win[o + k];
;                 y[8 * blk + o] = acc; } }
;         __syncthreads();
	v_fmac_f32_e32 v19, v48, v74
	v_fmac_f32_e32 v16, v48, v75
	v_fmac_f32_e32 v17, v48, v76
	v_fmac_f32_e32 v14, v48, v77
	v_fmac_f32_e32 v15, v48, v78
	v_fmac_f32_e32 v12, v48, v79
	v_fmac_f32_e32 v13, v48, v80
	v_fmac_f32_e32 v10, v48, v81
	v_fmac_f32_e32 v11, v48, v82
	v_fmac_f32_e32 v6, v48, v83
	v_fmac_f32_e32 v7, v48, v84
	v_fmac_f32_e32 v4, v48, v85
	v_fmac_f32_e32 v5, v48, v86
	v_fmac_f32_e32 v2, v48, v87
	v_fmac_f32_e32 v3, v48, v88
	v_fmac_f32_e32 v0, v56, v90
	v_fmac_f32_e32 v49, v48, v90
	v_fmac_f32_e32 v26, v56, v1
	v_fmac_f32_e32 v27, v56, v64
	v_fmac_f32_e32 v24, v56, v65
	v_fmac_f32_e32 v25, v56, v66
	v_fmac_f32_e32 v22, v56, v67
	v_fmac_f32_e32 v23, v56, v68
	v_fmac_f32_e32 v20, v56, v69
	v_fmac_f32_e32 v21, v56, v73
	v_fmac_f32_e32 v18, v56, v74
	v_fmac_f32_e32 v19, v56, v75
	v_fmac_f32_e32 v16, v56, v76
	v_fmac_f32_e32 v17, v56, v77
	v_fmac_f32_e32 v14, v56, v78
	v_fmac_f32_e32 v15, v56, v79
	v_fmac_f32_e32 v12, v56, v80
	v_fmac_f32_e32 v13, v56, v81
	v_fmac_f32_e32 v10, v56, v82
	v_fmac_f32_e32 v11, v56, v83
	v_fmac_f32_e32 v6, v56, v84
	v_fmac_f32_e32 v7, v56, v85
	v_fmac_f32_e32 v4, v56, v86
	v_fmac_f32_e32 v5, v56, v87
	v_fmac_f32_e32 v2, v56, v88
	v_fmac_f32_e32 v3, v56, v89
	v_fmac_f32_e32 v0, v45, v91
	v_fmac_f32_e32 v49, v56, v91
	v_fmac_f32_e32 v29, v45, v1
	v_fmac_f32_e32 v26, v45, v64
	v_fmac_f32_e32 v27, v45, v65
	v_fmac_f32_e32 v24, v45, v66
	v_fmac_f32_e32 v25, v45, v67
	v_fmac_f32_e32 v22, v45, v68
	v_fmac_f32_e32 v23, v45, v69
	v_fmac_f32_e32 v20, v45, v73
	v_fmac_f32_e32 v21, v45, v74
	v_fmac_f32_e32 v18, v45, v75
	v_fmac_f32_e32 v19, v45, v76
	v_fmac_f32_e32 v16, v45, v77
	v_fmac_f32_e32 v17, v45, v78
	v_fmac_f32_e32 v14, v45, v79
	v_fmac_f32_e32 v15, v45, v80
	v_fmac_f32_e32 v12, v45, v81
	v_fmac_f32_e32 v13, v45, v82
	v_fmac_f32_e32 v10, v45, v83
	v_fmac_f32_e32 v11, v45, v84
	v_fmac_f32_e32 v6, v45, v85
	v_fmac_f32_e32 v7, v45, v86
	v_fmac_f32_e32 v4, v45, v87
	v_fmac_f32_e32 v5, v45, v88
	v_fmac_f32_e32 v2, v45, v89
	v_fmac_f32_e32 v3, v45, v90
	v_fmac_f32_e32 v0, v58, v92
	v_fmac_f32_e32 v49, v45, v92
	v_fmac_f32_e32 v28, v58, v1
	v_fmac_f32_e32 v29, v58, v64
	v_fmac_f32_e32 v26, v58, v65
	v_fmac_f32_e32 v27, v58, v66
	v_fmac_f32_e32 v24, v58, v67
	v_fmac_f32_e32 v25, v58, v68
	v_fmac_f32_e32 v22, v58, v69
	v_fmac_f32_e32 v23, v58, v73
	v_fmac_f32_e32 v20, v58, v74
	v_fmac_f32_e32 v21, v58, v75
	v_fmac_f32_e32 v18, v58, v76
	v_fmac_f32_e32 v19, v58, v77
	v_fmac_f32_e32 v16, v58, v78
	v_fmac_f32_e32 v17, v58, v79
	v_fmac_f32_e32 v14, v58, v80
	v_fmac_f32_e32 v15, v58, v81
	v_fmac_f32_e32 v12, v58, v82
	v_fmac_f32_e32 v13, v58, v83
	v_fmac_f32_e32 v10, v58, v84
	v_fmac_f32_e32 v11, v58, v85
	v_fmac_f32_e32 v6, v58, v86
	v_fmac_f32_e32 v7, v58, v87
	v_fmac_f32_e32 v4, v58, v88
	v_fmac_f32_e32 v5, v58, v89
	v_fmac_f32_e32 v2, v58, v90
	v_fmac_f32_e32 v3, v58, v91
	v_fmac_f32_e32 v0, v57, v93
	v_fmac_f32_e32 v49, v58, v93
	v_fmac_f32_e32 v72, v57, v1
	v_fmac_f32_e32 v28, v57, v64
	v_fmac_f32_e32 v29, v57, v65
	v_fmac_f32_e32 v26, v57, v66
	v_fmac_f32_e32 v27, v57, v67
	v_fmac_f32_e32 v24, v57, v68
	v_fmac_f32_e32 v25, v57, v69
	v_fmac_f32_e32 v22, v57, v73
	v_fmac_f32_e32 v23, v57, v74
	v_fmac_f32_e32 v20, v57, v75
	v_fmac_f32_e32 v21, v57, v76
	v_fmac_f32_e32 v18, v57, v77
	v_fmac_f32_e32 v19, v57, v78
	v_fmac_f32_e32 v16, v57, v79
	v_fmac_f32_e32 v17, v57, v80
	v_fmac_f32_e32 v14, v57, v81
	v_fmac_f32_e32 v15, v57, v82
	v_fmac_f32_e32 v12, v57, v83
	v_fmac_f32_e32 v13, v57, v84
	v_fmac_f32_e32 v10, v57, v85
	v_fmac_f32_e32 v11, v57, v86
	v_fmac_f32_e32 v6, v57, v87
	v_fmac_f32_e32 v7, v57, v88
	v_fmac_f32_e32 v4, v57, v89
	v_fmac_f32_e32 v5, v57, v90
	v_fmac_f32_e32 v2, v57, v91
	v_fmac_f32_e32 v3, v57, v92
	s_waitcnt lgkmcnt(0)
	v_fmac_f32_e32 v0, v54, v94
	v_fmac_f32_e32 v49, v57, v94
	v_fmac_f32_e32 v70, v55, v1
	v_fmac_f32_e32 v71, v54, v1
	v_fmac_f32_e32 v72, v54, v64
	v_fmac_f32_e32 v28, v54, v65
	v_fmac_f32_e32 v29, v54, v66
	v_fmac_f32_e32 v26, v54, v67
	v_fmac_f32_e32 v27, v54, v68
	v_fmac_f32_e32 v24, v54, v69
	v_fmac_f32_e32 v25, v54, v73
	v_fmac_f32_e32 v22, v54, v74
	v_fmac_f32_e32 v23, v54, v75
	v_fmac_f32_e32 v20, v54, v76
	v_fmac_f32_e32 v21, v54, v77
	v_fmac_f32_e32 v18, v54, v78
	v_fmac_f32_e32 v19, v54, v79
	v_fmac_f32_e32 v16, v54, v80
	v_fmac_f32_e32 v17, v54, v81
	v_fmac_f32_e32 v14, v54, v82
	v_fmac_f32_e32 v15, v54, v83
	v_fmac_f32_e32 v12, v54, v84
	v_fmac_f32_e32 v13, v54, v85
	v_fmac_f32_e32 v10, v54, v86
	v_fmac_f32_e32 v11, v54, v87
	v_fmac_f32_e32 v6, v54, v88
	v_fmac_f32_e32 v7, v54, v89
	v_fmac_f32_e32 v4, v54, v90
	v_fmac_f32_e32 v5, v54, v91
	v_fmac_f32_e32 v2, v54, v92
	v_fmac_f32_e32 v3, v54, v93
	v_fmac_f32_e32 v0, v55, v95
	v_fmac_f32_e32 v49, v54, v95
	v_fmac_f32_e32 v71, v55, v64
	v_fmac_f32_e32 v72, v55, v65
	v_fmac_f32_e32 v28, v55, v66
	v_fmac_f32_e32 v29, v55, v67
	v_fmac_f32_e32 v26, v55, v68
	v_fmac_f32_e32 v27, v55, v69
	v_fmac_f32_e32 v24, v55, v73
	v_fmac_f32_e32 v25, v55, v74
	v_fmac_f32_e32 v22, v55, v75
	v_fmac_f32_e32 v23, v55, v76
	v_fmac_f32_e32 v20, v55, v77
	v_fmac_f32_e32 v21, v55, v78
	v_fmac_f32_e32 v18, v55, v79
	v_fmac_f32_e32 v19, v55, v80
	v_fmac_f32_e32 v16, v55, v81
	v_fmac_f32_e32 v17, v55, v82
	v_fmac_f32_e32 v14, v55, v83
	v_fmac_f32_e32 v15, v55, v84
	v_fmac_f32_e32 v12, v55, v85
	v_fmac_f32_e32 v13, v55, v86
	v_fmac_f32_e32 v10, v55, v87
	v_fmac_f32_e32 v11, v55, v88
	v_fmac_f32_e32 v6, v55, v89
	v_fmac_f32_e32 v7, v55, v90
	v_fmac_f32_e32 v4, v55, v91
	v_fmac_f32_e32 v5, v55, v92
	v_fmac_f32_e32 v2, v55, v93
	v_fmac_f32_e32 v3, v55, v94
	v_fmac_f32_e32 v49, v55, v96
	s_barrier
; __device__ __forceinline__ u32x4 pack8(const f32x4 v0, const f32x4 v1) { u32x4 w; w.x = cvt_pk_bf16(v0[0], v0[1]); w.y = cvt_pk_bf16(v0[2], v0[3]); w.z = cvt_pk_bf16(v1[0], v1[1]); w.w = cvt_pk_bf16(v1[2], v1[3]); return w; }
; __device__ __forceinline__ float silu_fast(float x) { return x * __builtin_amdgcn_rcpf(1.f + __expf(-x)); }
; #define LAS __attribute__((address_space(3)))
; __device__ __forceinline__ void conv_phase(LAS unsigned char* lds, const bf16_t* PROJ, const float* cw, const float* cb, const float* lg, const float* lb, bf16_t* MIXIN, int G, int tid) {
;     ...
;         __syncthreads();
; #pragma unroll
;         for (int tt = 0; tt < 32; ++tt) U[tt * 512 + c] = y[tt];
;         __syncthreads();
; #pragma unroll
;         for (int q = 0; q < 4; ++q) { const int tt = 4 * wave + q;
;             f32x4 a = *(const LAS f32x4*)(U + tt * 512 + 8 * lane), b = *(const LAS f32x4*)(U + tt * 512 + 8 * lane + 4);
;             const float mean = wave_sum((a[0] + a[1]) + (a[2] + a[3]) + (b[0] + b[1]) + (b[2] + b[3])) * (1.f / 512.f);
;             a = a - mean; b = b - mean;
;             const float var = wave_sum((a[0] * a[0] + a[1] * a[1]) + (a[2] * a[2] + a[3] * a[3]) + (b[0] * b[0] + b[1] * b[1]) + (b[2] * b[2] + b[3] * b[3])) * (1.f / 512.f);
;             const float rstd = rsqrtf(var + LN_EPS);
;             a = a * rstd * *(const f32x4*)(lg + 8 * lane) + *(const f32x4*)(lb + 8 * lane); b = b * rstd * *(const f32x4*)(lg + 8 * lane + 4) + *(const f32x4*)(lb + 8 * lane + 4);
; #pragma unroll
;             for (int x = 0; x < 4; ++x) { a[x] = pg8::silu_fast(a[x]); b[x] = pg8::silu_fast(b[x]); }
;             *(u32x4*)(MIXIN + (size_t)(row0 + tt) * D + 8 * lane) = pg8::pack8(a, b); }
	ds_write2st64_b32 v62, v63, v70 offset1:8
	ds_write2st64_b32 v62, v71, v72 offset0:16 offset1:24
	ds_write2st64_b32 v62, v28, v29 offset0:32 offset1:40
	ds_write2st64_b32 v62, v26, v27 offset0:48 offset1:56
	ds_write2st64_b32 v62, v24, v25 offset0:64 offset1:72
	ds_write2st64_b32 v62, v22, v23 offset0:80 offset1:88
	ds_write2st64_b32 v62, v20, v21 offset0:96 offset1:104
	ds_write2st64_b32 v62, v18, v19 offset0:112 offset1:120
	ds_write2st64_b32 v62, v16, v17 offset0:128 offset1:136
	ds_write2st64_b32 v62, v14, v15 offset0:144 offset1:152
	ds_write2st64_b32 v62, v12, v13 offset0:160 offset1:168
	ds_write2st64_b32 v62, v10, v11 offset0:176 offset1:184
	ds_write2st64_b32 v62, v6, v7 offset0:192 offset1:200
	ds_write2st64_b32 v62, v4, v5 offset0:208 offset1:216
	ds_write2st64_b32 v62, v2, v3 offset0:224 offset1:232
	ds_write2st64_b32 v62, v0, v49 offset0:240 offset1:248
	v_and_b32_e32 v0, 64, v230
	v_add_u32_e32 v0, 64, v0
	v_xor_b32_e32 v1, 1, v230
	v_cmp_lt_i32_e32 vcc, v1, v0
	s_lshl_b32 s5, s4, 2
	s_lshl_b32 s4, s4, 13
	v_cndmask_b32_e32 v1, v230, v1, vcc
	v_lshlrev_b32_e32 v13, 2, v1
	v_xor_b32_e32 v1, 2, v230
	v_cmp_lt_i32_e32 vcc, v1, v0
	v_lshlrev_b32_e32 v9, 2, v61
	s_add_i32 s4, s4, 0
	v_cndmask_b32_e32 v1, v230, v1, vcc
	v_lshlrev_b32_e32 v18, 2, v1
	v_xor_b32_e32 v1, 4, v230
	v_cmp_lt_i32_e32 vcc, v1, v0
	v_add_u32_e32 v23, s4, v9
	s_waitcnt lgkmcnt(0)
	v_cndmask_b32_e32 v1, v230, v1, vcc
	v_lshlrev_b32_e32 v19, 2, v1
	v_xor_b32_e32 v1, 8, v230
	v_cmp_lt_i32_e32 vcc, v1, v0
	s_barrier
	s_nop 0
	v_cndmask_b32_e32 v1, v230, v1, vcc
	v_lshlrev_b32_e32 v20, 2, v1
	v_xor_b32_e32 v1, 16, v230
	v_cmp_lt_i32_e32 vcc, v1, v0
	v_readlane_b32 s18, v250, 10
	s_add_i32 s4, s6, s5
	v_cndmask_b32_e32 v1, v230, v1, vcc
	v_lshlrev_b32_e32 v21, 2, v1
	v_xor_b32_e32 v1, 32, v230
	v_cmp_lt_i32_e32 vcc, v1, v0
	v_lshlrev_b32_e32 v164, 1, v61
	v_readlane_b32 s19, v250, 11
	v_cndmask_b32_e32 v0, v230, v1, vcc
	v_lshlrev_b32_e32 v22, 2, v0
	ds_read_b128 v[4:7], v23
	ds_read_b128 v[0:3], v23 offset:16
	s_ashr_i32 s5, s4, 31
	v_lshl_add_u64 v[10:11], s[18:19], 0, v[164:165]
	s_lshl_b64 s[18:19], s[4:5], 11
	s_waitcnt lgkmcnt(1)
	v_mov_b32_e32 v14, v5
	v_mov_b32_e32 v15, v6
	v_mov_b32_e32 v16, v4
	v_mov_b32_e32 v17, v7
	v_pk_add_f32 v[14:15], v[14:15], v[16:17]
	s_waitcnt lgkmcnt(0)
	v_mov_b32_e32 v16, v2
	v_mov_b32_e32 v17, v0
	v_mov_b32_e32 v24, v3
	v_mov_b32_e32 v25, v1
	v_pk_add_f32 v[16:17], v[16:17], v[24:25]
	v_add_f32_e32 v12, v14, v15
	v_add_f32_e32 v12, v12, v17
	v_add_f32_e32 v12, v16, v12
	ds_bpermute_b32 v14, v13, v12
	s_add_i32 s7, s7, s50
	s_waitcnt lgkmcnt(0)
	v_add_f32_e32 v12, v12, v14
	ds_bpermute_b32 v14, v18, v12
	s_waitcnt lgkmcnt(0)
	v_add_f32_e32 v12, v12, v14
	ds_bpermute_b32 v14, v19, v12
	s_waitcnt lgkmcnt(0)
	v_add_f32_e32 v12, v12, v14
	ds_bpermute_b32 v14, v20, v12
	s_waitcnt lgkmcnt(0)
	v_add_f32_e32 v12, v12, v14
	ds_bpermute_b32 v14, v21, v12
	s_waitcnt lgkmcnt(0)
	v_add_f32_e32 v12, v12, v14
	ds_bpermute_b32 v14, v22, v12
	s_waitcnt lgkmcnt(0)
	v_add_f32_e32 v12, v12, v14
	v_fmamk_f32 v5, v12, 0xbb000000, v5
	v_fmamk_f32 v4, v12, 0xbb000000, v4
	v_fmamk_f32 v7, v12, 0xbb000000, v7
	v_fmac_f32_e32 v6, 0xbb000000, v12
	v_pk_mul_f32 v[14:15], v[6:7], v[6:7]
	v_pk_mul_f32 v[16:17], v[4:5], v[4:5]
	v_fmamk_f32 v1, v12, 0xbb000000, v1
	v_fmamk_f32 v0, v12, 0xbb000000, v0
	v_fmamk_f32 v3, v12, 0xbb000000, v3
	v_fmac_f32_e32 v2, 0xbb000000, v12
	v_pk_mov_b32 v[24:25], v[16:17], v[14:15] op_sel:[1,0]
	v_mov_b32_e32 v17, v15
	v_pk_add_f32 v[14:15], v[24:25], v[16:17]
	v_pk_mul_f32 v[16:17], v[2:3], v[2:3]
	v_pk_mul_f32 v[24:25], v[0:1], v[0:1]
	v_mov_b32_e32 v26, v16
	v_mov_b32_e32 v27, v24
	v_mov_b32_e32 v24, v17
	v_pk_add_f32 v[16:17], v[26:27], v[24:25]
	v_add_f32_e32 v12, v14, v15
	v_add_f32_e32 v12, v17, v12
	v_add_f32_e32 v12, v16, v12
	ds_bpermute_b32 v14, v13, v12
	s_waitcnt lgkmcnt(0)
	v_add_f32_e32 v12, v12, v14
	ds_bpermute_b32 v14, v18, v12
	s_waitcnt lgkmcnt(0)
	v_add_f32_e32 v12, v12, v14
	ds_bpermute_b32 v14, v19, v12
	s_waitcnt lgkmcnt(0)
	v_add_f32_e32 v12, v12, v14
	ds_bpermute_b32 v14, v20, v12
	s_waitcnt lgkmcnt(0)
	v_add_f32_e32 v12, v12, v14
	ds_bpermute_b32 v14, v21, v12
	s_waitcnt lgkmcnt(0)
	v_add_f32_e32 v12, v12, v14
	ds_bpermute_b32 v14, v22, v12
	s_waitcnt lgkmcnt(0)
	v_add_f32_e32 v12, v12, v14
	v_fmamk_f32 v12, v12, 0x3b000000, v173
	v_cmp_gt_f32_e32 vcc, s81, v12
	v_mul_f32_e32 v14, 0x4b800000, v12
	s_nop 0
	v_cndmask_b32_e32 v12, v12, v14, vcc
	v_rsq_f32_e32 v12, v12
	s_nop 0
	v_mul_f32_e32 v14, 0x45800000, v12
	v_cndmask_b32_e32 v12, v12, v14, vcc
	v_pk_mul_f32 v[14:15], v[4:5], v[12:13] op_sel_hi:[1,0]
	v_pk_mul_f32 v[16:17], v[6:7], v[12:13] op_sel_hi:[1,0]
	global_load_dwordx4 v[4:7], v9, s[14:15] offset:16
	global_load_dwordx4 v[24:27], v9, s[14:15]
	global_load_dwordx4 v[28:31], v9, s[16:17] offset:16
	global_load_dwordx4 v[32:35], v9, s[16:17]
	v_pk_mul_f32 v[0:1], v[0:1], v[12:13] op_sel_hi:[1,0]
	v_pk_mul_f32 v[2:3], v[2:3], v[12:13] op_sel_hi:[1,0]
	s_waitcnt vmcnt(1)
	v_pk_fma_f32 v[0:1], v[4:5], v[0:1], v[28:29]
	v_pk_fma_f32 v[2:3], v[6:7], v[2:3], v[30:31]
	v_mul_f32_e32 v5, 0xbfb8aa3b, v0
	v_mul_f32_e32 v6, 0xbfb8aa3b, v1
	v_mul_f32_e32 v7, 0xbfb8aa3b, v2
	v_exp_f32_e32 v5, v5
	v_exp_f32_e32 v6, v6
	v_exp_f32_e32 v7, v7
	s_waitcnt vmcnt(0)
; __device__ __forceinline__ u32x4 pack8(const f32x4 v0, const f32x4 v1) { u32x4 w; w.x = cvt_pk_bf16(v0[0], v0[1]); w.y = cvt_pk_bf16(v0[2], v0[3]); w.z = cvt_pk_bf16(v1[0], v1[1]); w.w = cvt_pk_bf16(v1[2], v1[3]); return w; }
; __device__ __forceinline__ float silu_fast(float x) { return x * __builtin_amdgcn_rcpf(1.f + __expf(-x)); }
; #define LAS __attribute__((address_space(3)))
; __device__ __forceinline__ void conv_phase(LAS unsigned char* lds, const bf16_t* PROJ, const float* cw, const float* cb, const float* lg, const float* lb, bf16_t* MIXIN, int G, int tid) {
;     ...
;         for (int q = 0; q < 4; ++q) { const int tt = 4 * wave + q;
;             f32x4 a = *(const LAS f32x4*)(U + tt * 512 + 8 * lane), b = *(const LAS f32x4*)(U + tt * 512 + 8 * lane + 4);
;             const float mean = wave_sum((a[0] + a[1]) + (a[2] + a[3]) + (b[0] + b[1]) + (b[2] + b[3])) * (1.f / 512.f);
;             a = a - mean; b = b - mean;
;             const float var = wave_sum((a[0] * a[0] + a[1] * a[1]) + (a[2] * a[2] + a[3] * a[3]) + (b[0] * b[0] + b[1] * b[1]) + (b[2] * b[2] + b[3] * b[3])) * (1.f / 512.f);
;             const float rstd = rsqrtf(var + LN_EPS);
;             a = a * rstd * *(const f32x4*)(lg + 8 * lane) + *(const f32x4*)(lb + 8 * lane); b = b * rstd * *(const f32x4*)(lg + 8 * lane + 4) + *(const f32x4*)(lb + 8 * lane + 4);
; #pragma unroll
;             for (int x = 0; x < 4; ++x) { a[x] = pg8::silu_fast(a[x]); b[x] = pg8::silu_fast(b[x]); }
;             *(u32x4*)(MIXIN + (size_t)(row0 + tt) * D + 8 * lane) = pg8::pack8(a, b); }
	v_pk_fma_f32 v[16:17], v[26:27], v[16:17], v[34:35]
	v_add_f32_e32 v5, 1.0, v5
	v_add_f32_e32 v6, 1.0, v6
	v_add_f32_e32 v7, 1.0, v7
	v_rcp_f32_e32 v5, v5
	v_rcp_f32_e32 v6, v6
	v_rcp_f32_e32 v7, v7
	v_pk_fma_f32 v[14:15], v[24:25], v[14:15], v[32:33]
	v_mul_f32_e32 v5, v0, v5
	v_mul_f32_e32 v4, 0xbfb8aa3b, v14
	v_mul_f32_e32 v0, 0xbfb8aa3b, v15
	v_mul_f32_e32 v6, v1, v6
	v_mul_f32_e32 v1, 0xbfb8aa3b, v16
	v_mul_f32_e32 v7, v2, v7
	v_mul_f32_e32 v2, 0xbfb8aa3b, v17
	v_exp_f32_e32 v4, v4
	v_exp_f32_e32 v0, v0
	v_exp_f32_e32 v1, v1
	v_exp_f32_e32 v2, v2
	v_mul_f32_e32 v12, 0xbfb8aa3b, v3
	v_exp_f32_e32 v12, v12
	v_add_f32_e32 v4, 1.0, v4
	v_add_f32_e32 v0, 1.0, v0
	v_add_f32_e32 v1, 1.0, v1
	v_add_f32_e32 v2, 1.0, v2
	v_rcp_f32_e32 v4, v4
	v_rcp_f32_e32 v0, v0
	v_rcp_f32_e32 v1, v1
	v_rcp_f32_e32 v2, v2
	v_add_f32_e32 v12, 1.0, v12
	v_rcp_f32_e32 v12, v12
	v_mul_f32_e32 v4, v14, v4
	v_mul_f32_e32 v0, v15, v0
	v_mul_f32_e32 v1, v16, v1
	v_mul_f32_e32 v2, v17, v2
	v_mul_f32_e32 v3, v3, v12
	v_cvt_pk_bf16_f32 v0, v4, v0
	v_cvt_pk_bf16_f32 v1, v1, v2
	v_cvt_pk_bf16_f32 v2, v5, v6
	v_lshl_add_u64 v[4:5], v[10:11], 0, s[18:19]
	v_cvt_pk_bf16_f32 v3, v7, v3
	global_store_dwordx4 v[4:5], v[0:3], off
	ds_read_b128 v[4:7], v23 offset:2048
	ds_read_b128 v[0:3], v23 offset:2064
	s_add_i32 s18, s4, 1
	s_ashr_i32 s19, s18, 31
	s_lshl_b64 s[18:19], s[18:19], 11
	s_waitcnt lgkmcnt(1)
	v_mov_b32_e32 v14, v5
	v_mov_b32_e32 v15, v6
	v_mov_b32_e32 v16, v4
	v_mov_b32_e32 v17, v7
	v_pk_add_f32 v[14:15], v[14:15], v[16:17]
	s_waitcnt lgkmcnt(0)
	v_mov_b32_e32 v16, v2
	v_mov_b32_e32 v17, v0
	v_mov_b32_e32 v24, v3
	v_mov_b32_e32 v25, v1
	v_pk_add_f32 v[16:17], v[16:17], v[24:25]
	v_add_f32_e32 v12, v14, v15
	v_add_f32_e32 v12, v12, v17
	v_add_f32_e32 v12, v16, v12
	ds_bpermute_b32 v14, v13, v12
	s_waitcnt lgkmcnt(0)
	v_add_f32_e32 v12, v12, v14
	ds_bpermute_b32 v14, v18, v12
	s_waitcnt lgkmcnt(0)
	v_add_f32_e32 v12, v12, v14
	ds_bpermute_b32 v14, v19, v12
	s_waitcnt lgkmcnt(0)
	v_add_f32_e32 v12, v12, v14
	ds_bpermute_b32 v14, v20, v12
	s_waitcnt lgkmcnt(0)
	v_add_f32_e32 v12, v12, v14
	ds_bpermute_b32 v14, v21, v12
	s_waitcnt lgkmcnt(0)
	v_add_f32_e32 v12, v12, v14
	ds_bpermute_b32 v14, v22, v12
	s_waitcnt lgkmcnt(0)
	v_add_f32_e32 v12, v12, v14
	v_fmamk_f32 v5, v12, 0xbb000000, v5
	v_fmamk_f32 v4, v12, 0xbb000000, v4
	v_fmamk_f32 v7, v12, 0xbb000000, v7
	v_fmac_f32_e32 v6, 0xbb000000, v12
	v_pk_mul_f32 v[14:15], v[6:7], v[6:7]
	v_pk_mul_f32 v[16:17], v[4:5], v[4:5]
	v_fmamk_f32 v1, v12, 0xbb000000, v1
	v_fmamk_f32 v0, v12, 0xbb000000, v0
	v_fmamk_f32 v3, v12, 0xbb000000, v3
	v_fmac_f32_e32 v2, 0xbb000000, v12
	v_pk_mov_b32 v[24:25], v[16:17], v[14:15] op_sel:[1,0]
	v_mov_b32_e32 v17, v15
	v_pk_add_f32 v[14:15], v[24:25], v[16:17]
	v_pk_mul_f32 v[16:17], v[2:3], v[2:3]
	v_pk_mul_f32 v[24:25], v[0:1], v[0:1]
	v_mov_b32_e32 v26, v16
	v_mov_b32_e32 v27, v24
	v_mov_b32_e32 v24, v17
	v_pk_add_f32 v[16:17], v[26:27], v[24:25]
	v_add_f32_e32 v12, v14, v15
	v_add_f32_e32 v12, v17, v12
	v_add_f32_e32 v12, v16, v12
	ds_bpermute_b32 v14, v13, v12
	s_waitcnt lgkmcnt(0)
	v_add_f32_e32 v12, v12, v14
	ds_bpermute_b32 v14, v18, v12
	s_waitcnt lgkmcnt(0)
	v_add_f32_e32 v12, v12, v14
	ds_bpermute_b32 v14, v19, v12
	s_waitcnt lgkmcnt(0)
	v_add_f32_e32 v12, v12, v14
	ds_bpermute_b32 v14, v20, v12
	s_waitcnt lgkmcnt(0)
	v_add_f32_e32 v12, v12, v14
	ds_bpermute_b32 v14, v21, v12
	s_waitcnt lgkmcnt(0)
	v_add_f32_e32 v12, v12, v14
	ds_bpermute_b32 v14, v22, v12
	s_waitcnt lgkmcnt(0)
	v_add_f32_e32 v12, v12, v14
	v_fmamk_f32 v12, v12, 0x3b000000, v173
	v_cmp_gt_f32_e32 vcc, s81, v12
	v_mul_f32_e32 v14, 0x4b800000, v12
	s_nop 0
	v_cndmask_b32_e32 v12, v12, v14, vcc
	v_rsq_f32_e32 v12, v12
	s_nop 0
	v_mul_f32_e32 v14, 0x45800000, v12
	v_cndmask_b32_e32 v12, v12, v14, vcc
	v_pk_mul_f32 v[14:15], v[4:5], v[12:13] op_sel_hi:[1,0]
	v_pk_mul_f32 v[16:17], v[6:7], v[12:13] op_sel_hi:[1,0]
	global_load_dwordx4 v[4:7], v9, s[14:15] offset:16
	global_load_dwordx4 v[24:27], v9, s[14:15]
	global_load_dwordx4 v[28:31], v9, s[16:17] offset:16
	global_load_dwordx4 v[32:35], v9, s[16:17]
	v_pk_mul_f32 v[0:1], v[0:1], v[12:13] op_sel_hi:[1,0]
	v_pk_mul_f32 v[2:3], v[2:3], v[12:13] op_sel_hi:[1,0]
	s_waitcnt vmcnt(1)
	v_pk_fma_f32 v[0:1], v[4:5], v[0:1], v[28:29]
	v_pk_fma_f32 v[2:3], v[6:7], v[2:3], v[30:31]
	v_mul_f32_e32 v5, 0xbfb8aa3b, v0
	v_mul_f32_e32 v6, 0xbfb8aa3b, v1
	v_mul_f32_e32 v7, 0xbfb8aa3b, v2
	v_exp_f32_e32 v5, v5
	v_exp_f32_e32 v6, v6
	v_exp_f32_e32 v7, v7
	s_waitcnt vmcnt(0)
	v_pk_fma_f32 v[16:17], v[26:27], v[16:17], v[34:35]
	v_add_f32_e32 v5, 1.0, v5
	v_add_f32_e32 v6, 1.0, v6
	v_add_f32_e32 v7, 1.0, v7
	v_rcp_f32_e32 v5, v5
	v_rcp_f32_e32 v6, v6
	v_rcp_f32_e32 v7, v7
	v_pk_fma_f32 v[14:15], v[24:25], v[14:15], v[32:33]
	v_mul_f32_e32 v5, v0, v5
	v_mul_f32_e32 v4, 0xbfb8aa3b, v14
	v_mul_f32_e32 v0, 0xbfb8aa3b, v15
	v_mul_f32_e32 v6, v1, v6
	v_mul_f32_e32 v1, 0xbfb8aa3b, v16
	v_mul_f32_e32 v7, v2, v7
	v_mul_f32_e32 v2, 0xbfb8aa3b, v17
	v_exp_f32_e32 v4, v4
	v_exp_f32_e32 v0, v0
	v_exp_f32_e32 v1, v1
	v_exp_f32_e32 v2, v2
	v_mul_f32_e32 v12, 0xbfb8aa3b, v3
	v_exp_f32_e32 v12, v12
	v_add_f32_e32 v4, 1.0, v4
	v_add_f32_e32 v0, 1.0, v0
	v_add_f32_e32 v1, 1.0, v1
	v_add_f32_e32 v2, 1.0, v2
	v_rcp_f32_e32 v4, v4
	v_rcp_f32_e32 v0, v0
	v_rcp_f32_e32 v1, v1
	v_rcp_f32_e32 v2, v2
	v_add_f32_e32 v12, 1.0, v12
	v_rcp_f32_e32 v12, v12
	v_mul_f32_e32 v4, v14, v4
	v_mul_f32_e32 v0, v15, v0
	v_mul_f32_e32 v1, v16, v1
	v_mul_f32_e32 v2, v17, v2
	v_mul_f32_e32 v3, v3, v12
	v_cvt_pk_bf16_f32 v0, v4, v0
	v_cvt_pk_bf16_f32 v1, v1, v2
	v_cvt_pk_bf16_f32 v2, v5, v6
	v_lshl_add_u64 v[4:5], v[10:11], 0, s[18:19]
	v_cvt_pk_bf16_f32 v3, v7, v3
	global_store_dwordx4 v[4:5], v[0:3], off
	ds_read_b128 v[4:7], v23 offset:4096
	ds_read_b128 v[0:3], v23 offset:4112
	s_add_i32 s18, s4, 2
	s_ashr_i32 s19, s18, 31
	s_lshl_b64 s[18:19], s[18:19], 11
	s_waitcnt lgkmcnt(1)
; __device__ __forceinline__ u32x4 pack8(const f32x4 v0, const f32x4 v1) { u32x4 w; w.x = cvt_pk_bf16(v0[0], v0[1]); w.y = cvt_pk_bf16(v0[2], v0[3]); w.z = cvt_pk_bf16(v1[0], v1[1]); w.w = cvt_pk_bf16(v1[2], v1[3]); return w; }
; __device__ __forceinline__ float silu_fast(float x) { return x * __builtin_amdgcn_rcpf(1.f + __expf(-x)); }
; #define LAS __attribute__((address_space(3)))
; __device__ __forceinline__ void conv_phase(LAS unsigned char* lds, const bf16_t* PROJ, const float* cw, const float* cb, const float* lg, const float* lb, bf16_t* MIXIN, int G, int tid) {
;     ...
;         for (int q = 0; q < 4; ++q) { const int tt = 4 * wave + q;
;             f32x4 a = *(const LAS f32x4*)(U + tt * 512 + 8 * lane), b = *(const LAS f32x4*)(U + tt * 512 + 8 * lane + 4);
;             const float mean = wave_sum((a[0] + a[1]) + (a[2] + a[3]) + (b[0] + b[1]) + (b[2] + b[3])) * (1.f / 512.f);
;             a = a - mean; b = b - mean;
;             const float var = wave_sum((a[0] * a[0] + a[1] * a[1]) + (a[2] * a[2] + a[3] * a[3]) + (b[0] * b[0] + b[1] * b[1]) + (b[2] * b[2] + b[3] * b[3])) * (1.f / 512.f);
;             const float rstd = rsqrtf(var + LN_EPS);
;             a = a * rstd * *(const f32x4*)(lg + 8 * lane) + *(const f32x4*)(lb + 8 * lane); b = b * rstd * *(const f32x4*)(lg + 8 * lane + 4) + *(const f32x4*)(lb + 8 * lane + 4);
; #pragma unroll
;             for (int x = 0; x < 4; ++x) { a[x] = pg8::silu_fast(a[x]); b[x] = pg8::silu_fast(b[x]); }
;             *(u32x4*)(MIXIN + (size_t)(row0 + tt) * D + 8 * lane) = pg8::pack8(a, b); }
	v_mov_b32_e32 v14, v5
	v_mov_b32_e32 v15, v6
	v_mov_b32_e32 v16, v4
	v_mov_b32_e32 v17, v7
	v_pk_add_f32 v[14:15], v[14:15], v[16:17]
	s_waitcnt lgkmcnt(0)
	v_mov_b32_e32 v16, v2
	v_mov_b32_e32 v17, v0
	v_mov_b32_e32 v24, v3
	v_mov_b32_e32 v25, v1
	v_pk_add_f32 v[16:17], v[16:17], v[24:25]
	v_add_f32_e32 v12, v14, v15
	v_add_f32_e32 v12, v12, v17
	v_add_f32_e32 v12, v16, v12
	ds_bpermute_b32 v14, v13, v12
	s_add_i32 s4, s4, 3
	s_ashr_i32 s5, s4, 31
	s_lshl_b64 s[4:5], s[4:5], 11
	s_waitcnt lgkmcnt(0)
	v_add_f32_e32 v12, v12, v14
	ds_bpermute_b32 v14, v18, v12
	s_waitcnt lgkmcnt(0)
	v_add_f32_e32 v12, v12, v14
	ds_bpermute_b32 v14, v19, v12
	s_waitcnt lgkmcnt(0)
	v_add_f32_e32 v12, v12, v14
	ds_bpermute_b32 v14, v20, v12
	s_waitcnt lgkmcnt(0)
	v_add_f32_e32 v12, v12, v14
	ds_bpermute_b32 v14, v21, v12
	s_waitcnt lgkmcnt(0)
	v_add_f32_e32 v12, v12, v14
	ds_bpermute_b32 v14, v22, v12
	s_waitcnt lgkmcnt(0)
	v_add_f32_e32 v12, v12, v14
	v_fmamk_f32 v5, v12, 0xbb000000, v5
	v_fmamk_f32 v4, v12, 0xbb000000, v4
	v_fmamk_f32 v7, v12, 0xbb000000, v7
	v_fmac_f32_e32 v6, 0xbb000000, v12
	v_pk_mul_f32 v[14:15], v[6:7], v[6:7]
	v_pk_mul_f32 v[16:17], v[4:5], v[4:5]
	v_fmamk_f32 v1, v12, 0xbb000000, v1
	v_fmamk_f32 v0, v12, 0xbb000000, v0
	v_fmamk_f32 v3, v12, 0xbb000000, v3
	v_fmac_f32_e32 v2, 0xbb000000, v12
	v_pk_mov_b32 v[24:25], v[16:17], v[14:15] op_sel:[1,0]
	v_mov_b32_e32 v17, v15
	v_pk_add_f32 v[14:15], v[24:25], v[16:17]
	v_pk_mul_f32 v[16:17], v[2:3], v[2:3]
	v_pk_mul_f32 v[24:25], v[0:1], v[0:1]
	v_mov_b32_e32 v26, v16
	v_mov_b32_e32 v27, v24
	v_mov_b32_e32 v24, v17
	v_pk_add_f32 v[16:17], v[26:27], v[24:25]
	v_add_f32_e32 v12, v14, v15
	v_add_f32_e32 v12, v17, v12
	v_add_f32_e32 v12, v16, v12
	ds_bpermute_b32 v14, v13, v12
	s_waitcnt lgkmcnt(0)
	v_add_f32_e32 v12, v12, v14
	ds_bpermute_b32 v14, v18, v12
	s_waitcnt lgkmcnt(0)
	v_add_f32_e32 v12, v12, v14
	ds_bpermute_b32 v14, v19, v12
	s_waitcnt lgkmcnt(0)
	v_add_f32_e32 v12, v12, v14
	ds_bpermute_b32 v14, v20, v12
	s_waitcnt lgkmcnt(0)
	v_add_f32_e32 v12, v12, v14
	ds_bpermute_b32 v14, v21, v12
	s_waitcnt lgkmcnt(0)
	v_add_f32_e32 v12, v12, v14
	ds_bpermute_b32 v14, v22, v12
	s_waitcnt lgkmcnt(0)
	v_add_f32_e32 v12, v12, v14
	v_fmamk_f32 v12, v12, 0x3b000000, v173
	v_cmp_gt_f32_e32 vcc, s81, v12
	v_mul_f32_e32 v14, 0x4b800000, v12
	s_nop 0
	v_cndmask_b32_e32 v12, v12, v14, vcc
	v_rsq_f32_e32 v12, v12
	s_nop 0
	v_mul_f32_e32 v14, 0x45800000, v12
	v_cndmask_b32_e32 v12, v12, v14, vcc
	v_pk_mul_f32 v[14:15], v[4:5], v[12:13] op_sel_hi:[1,0]
	v_pk_mul_f32 v[16:17], v[6:7], v[12:13] op_sel_hi:[1,0]
	global_load_dwordx4 v[4:7], v9, s[14:15] offset:16
	global_load_dwordx4 v[24:27], v9, s[14:15]
	global_load_dwordx4 v[28:31], v9, s[16:17] offset:16
	global_load_dwordx4 v[32:35], v9, s[16:17]
	v_pk_mul_f32 v[0:1], v[0:1], v[12:13] op_sel_hi:[1,0]
	v_pk_mul_f32 v[2:3], v[2:3], v[12:13] op_sel_hi:[1,0]
	s_waitcnt vmcnt(1)
	v_pk_fma_f32 v[0:1], v[4:5], v[0:1], v[28:29]
	v_pk_fma_f32 v[2:3], v[6:7], v[2:3], v[30:31]
	v_mul_f32_e32 v5, 0xbfb8aa3b, v0
	v_mul_f32_e32 v6, 0xbfb8aa3b, v1
	v_mul_f32_e32 v7, 0xbfb8aa3b, v2
	v_exp_f32_e32 v5, v5
	v_exp_f32_e32 v6, v6
	v_exp_f32_e32 v7, v7
	s_waitcnt vmcnt(0)
	v_pk_fma_f32 v[16:17], v[26:27], v[16:17], v[34:35]
	v_add_f32_e32 v5, 1.0, v5
	v_add_f32_e32 v6, 1.0, v6
	v_add_f32_e32 v7, 1.0, v7
	v_rcp_f32_e32 v5, v5
	v_rcp_f32_e32 v6, v6
	v_rcp_f32_e32 v7, v7
	v_pk_fma_f32 v[14:15], v[24:25], v[14:15], v[32:33]
	v_mul_f32_e32 v5, v0, v5
	v_mul_f32_e32 v4, 0xbfb8aa3b, v14
	v_mul_f32_e32 v0, 0xbfb8aa3b, v15
	v_mul_f32_e32 v6, v1, v6
	v_mul_f32_e32 v1, 0xbfb8aa3b, v16
	v_mul_f32_e32 v7, v2, v7
	v_mul_f32_e32 v2, 0xbfb8aa3b, v17
	v_exp_f32_e32 v4, v4
	v_exp_f32_e32 v0, v0
	v_exp_f32_e32 v1, v1
	v_exp_f32_e32 v2, v2
	v_mul_f32_e32 v12, 0xbfb8aa3b, v3
	v_exp_f32_e32 v12, v12
	v_add_f32_e32 v4, 1.0, v4
	v_add_f32_e32 v0, 1.0, v0
	v_add_f32_e32 v1, 1.0, v1
	v_add_f32_e32 v2, 1.0, v2
	v_rcp_f32_e32 v4, v4
	v_rcp_f32_e32 v0, v0
	v_rcp_f32_e32 v1, v1
	v_rcp_f32_e32 v2, v2
	v_add_f32_e32 v12, 1.0, v12
	v_rcp_f32_e32 v12, v12
	v_mul_f32_e32 v4, v14, v4
	v_mul_f32_e32 v0, v15, v0
	v_mul_f32_e32 v1, v16, v1
	v_mul_f32_e32 v2, v17, v2
	v_mul_f32_e32 v3, v3, v12
	v_cvt_pk_bf16_f32 v0, v4, v0
	v_cvt_pk_bf16_f32 v1, v1, v2
	v_cvt_pk_bf16_f32 v2, v5, v6
	v_lshl_add_u64 v[4:5], v[10:11], 0, s[18:19]
	v_cvt_pk_bf16_f32 v3, v7, v3
	global_store_dwordx4 v[4:5], v[0:3], off
	ds_read_b128 v[4:7], v23 offset:6144
	ds_read_b128 v[0:3], v23 offset:6160
	s_waitcnt lgkmcnt(1)
	v_mov_b32_e32 v14, v5
	v_mov_b32_e32 v15, v6
	v_mov_b32_e32 v16, v4
	v_mov_b32_e32 v17, v7
	v_pk_add_f32 v[14:15], v[14:15], v[16:17]
	s_waitcnt lgkmcnt(0)
	v_mov_b32_e32 v16, v2
	v_mov_b32_e32 v17, v0
	v_mov_b32_e32 v24, v3
	v_mov_b32_e32 v25, v1
	v_pk_add_f32 v[16:17], v[16:17], v[24:25]
	v_add_f32_e32 v12, v14, v15
	v_add_f32_e32 v12, v12, v17
	v_add_f32_e32 v12, v16, v12
	ds_bpermute_b32 v14, v13, v12
	s_waitcnt lgkmcnt(0)
	v_add_f32_e32 v12, v12, v14
	ds_bpermute_b32 v14, v18, v12
	s_waitcnt lgkmcnt(0)
	v_add_f32_e32 v12, v12, v14
	ds_bpermute_b32 v14, v19, v12
	s_waitcnt lgkmcnt(0)
	v_add_f32_e32 v12, v12, v14
	ds_bpermute_b32 v14, v20, v12
	s_waitcnt lgkmcnt(0)
	v_add_f32_e32 v12, v12, v14
	ds_bpermute_b32 v14, v21, v12
	s_waitcnt lgkmcnt(0)
	v_add_f32_e32 v12, v12, v14
	ds_bpermute_b32 v14, v22, v12
	s_waitcnt lgkmcnt(0)
; __device__ __forceinline__ u32x4 pack8(const f32x4 v0, const f32x4 v1) { u32x4 w; w.x = cvt_pk_bf16(v0[0], v0[1]); w.y = cvt_pk_bf16(v0[2], v0[3]); w.z = cvt_pk_bf16(v1[0], v1[1]); w.w = cvt_pk_bf16(v1[2], v1[3]); return w; }
; __device__ __forceinline__ float silu_fast(float x) { return x * __builtin_amdgcn_rcpf(1.f + __expf(-x)); }
; #define LAS __attribute__((address_space(3)))
; __device__ __forceinline__ void conv_phase(LAS unsigned char* lds, const bf16_t* PROJ, const float* cw, const float* cb, const float* lg, const float* lb, bf16_t* MIXIN, int G, int tid) {
;     ...
;     for (int u = blockIdx.x; u < M / 32; u += G) {
;         asm volatile("" : "+v"(tid));
;         const int lane = tid & 63, wave = __builtin_amdgcn_readfirstlane(tid >> 6);
;         const int row0 = u * 32, t0 = row0 % SEQ;
;         const int c = tid;
;         float w[31];
; #pragma unroll
;         for (int k = 0; k < 31; ++k) w[k] = cw[k * 512 + c];
;         const float bias = cb[c];
;     ...
;         for (int q = 0; q < 4; ++q) { const int tt = 4 * wave + q;
;             f32x4 a = *(const LAS f32x4*)(U + tt * 512 + 8 * lane), b = *(const LAS f32x4*)(U + tt * 512 + 8 * lane + 4);
;             const float mean = wave_sum((a[0] + a[1]) + (a[2] + a[3]) + (b[0] + b[1]) + (b[2] + b[3])) * (1.f / 512.f);
;             a = a - mean; b = b - mean;
;             const float var = wave_sum((a[0] * a[0] + a[1] * a[1]) + (a[2] * a[2] + a[3] * a[3]) + (b[0] * b[0] + b[1] * b[1]) + (b[2] * b[2] + b[3] * b[3])) * (1.f / 512.f);
;             const float rstd = rsqrtf(var + LN_EPS);
;             a = a * rstd * *(const f32x4*)(lg + 8 * lane) + *(const f32x4*)(lb + 8 * lane); b = b * rstd * *(const f32x4*)(lg + 8 * lane + 4) + *(const f32x4*)(lb + 8 * lane + 4);
; #pragma unroll
;             for (int x = 0; x < 4; ++x) { a[x] = pg8::silu_fast(a[x]); b[x] = pg8::silu_fast(b[x]); }
;             *(u32x4*)(MIXIN + (size_t)(row0 + tt) * D + 8 * lane) = pg8::pack8(a, b); }
;         __syncthreads();
	v_add_f32_e32 v12, v12, v14
	v_fmamk_f32 v5, v12, 0xbb000000, v5
	v_fmamk_f32 v4, v12, 0xbb000000, v4
	v_fmamk_f32 v7, v12, 0xbb000000, v7
	v_fmac_f32_e32 v6, 0xbb000000, v12
	v_pk_mul_f32 v[14:15], v[6:7], v[6:7]
	v_pk_mul_f32 v[16:17], v[4:5], v[4:5]
	v_fmamk_f32 v1, v12, 0xbb000000, v1
	v_fmamk_f32 v0, v12, 0xbb000000, v0
	v_fmamk_f32 v3, v12, 0xbb000000, v3
	v_fmac_f32_e32 v2, 0xbb000000, v12
	v_pk_mov_b32 v[24:25], v[16:17], v[14:15] op_sel:[1,0]
	v_mov_b32_e32 v17, v15
	v_pk_add_f32 v[14:15], v[24:25], v[16:17]
	v_pk_mul_f32 v[16:17], v[2:3], v[2:3]
	v_pk_mul_f32 v[24:25], v[0:1], v[0:1]
	v_mov_b32_e32 v26, v16
	v_mov_b32_e32 v27, v24
	v_mov_b32_e32 v24, v17
	v_pk_add_f32 v[16:17], v[26:27], v[24:25]
	v_add_f32_e32 v12, v14, v15
	v_add_f32_e32 v12, v17, v12
	v_add_f32_e32 v12, v16, v12
	ds_bpermute_b32 v13, v13, v12
	s_waitcnt lgkmcnt(0)
	v_add_f32_e32 v12, v12, v13
	ds_bpermute_b32 v13, v18, v12
	s_waitcnt lgkmcnt(0)
	v_add_f32_e32 v12, v12, v13
	ds_bpermute_b32 v13, v19, v12
	s_waitcnt lgkmcnt(0)
	v_add_f32_e32 v12, v12, v13
	ds_bpermute_b32 v13, v20, v12
	s_waitcnt lgkmcnt(0)
	v_add_f32_e32 v12, v12, v13
	ds_bpermute_b32 v13, v21, v12
	s_waitcnt lgkmcnt(0)
	v_add_f32_e32 v12, v12, v13
	ds_bpermute_b32 v13, v22, v12
	s_waitcnt lgkmcnt(0)
	v_add_f32_e32 v12, v12, v13
	v_fmamk_f32 v12, v12, 0x3b000000, v173
	v_cmp_gt_f32_e32 vcc, s81, v12
	v_mul_f32_e32 v13, 0x4b800000, v12
	s_nop 0
	v_cndmask_b32_e32 v12, v12, v13, vcc
	v_rsq_f32_e32 v12, v12
	s_nop 0
	v_mul_f32_e32 v13, 0x45800000, v12
	v_cndmask_b32_e32 v12, v12, v13, vcc
	v_pk_mul_f32 v[14:15], v[4:5], v[12:13] op_sel_hi:[1,0]
	v_pk_mul_f32 v[16:17], v[6:7], v[12:13] op_sel_hi:[1,0]
	global_load_dwordx4 v[4:7], v9, s[14:15] offset:16
	global_load_dwordx4 v[18:21], v9, s[14:15]
	global_load_dwordx4 v[22:25], v9, s[16:17] offset:16
	global_load_dwordx4 v[26:29], v9, s[16:17]
	v_pk_mul_f32 v[0:1], v[0:1], v[12:13] op_sel_hi:[1,0]
	v_pk_mul_f32 v[2:3], v[2:3], v[12:13] op_sel_hi:[1,0]
	s_waitcnt vmcnt(1)
	v_pk_fma_f32 v[0:1], v[4:5], v[0:1], v[22:23]
	v_pk_fma_f32 v[2:3], v[6:7], v[2:3], v[24:25]
	v_mul_f32_e32 v5, 0xbfb8aa3b, v0
	v_mul_f32_e32 v6, 0xbfb8aa3b, v1
	v_mul_f32_e32 v7, 0xbfb8aa3b, v2
	v_exp_f32_e32 v5, v5
	v_exp_f32_e32 v6, v6
	v_exp_f32_e32 v7, v7
	s_waitcnt vmcnt(0)
	v_pk_fma_f32 v[16:17], v[20:21], v[16:17], v[28:29]
	v_add_f32_e32 v5, 1.0, v5
	v_add_f32_e32 v6, 1.0, v6
	v_add_f32_e32 v7, 1.0, v7
	v_rcp_f32_e32 v5, v5
	v_rcp_f32_e32 v6, v6
	v_rcp_f32_e32 v7, v7
	v_pk_fma_f32 v[14:15], v[18:19], v[14:15], v[26:27]
	v_mul_f32_e32 v5, v0, v5
	v_mul_f32_e32 v4, 0xbfb8aa3b, v14
	v_mul_f32_e32 v0, 0xbfb8aa3b, v15
	v_mul_f32_e32 v6, v1, v6
	v_mul_f32_e32 v1, 0xbfb8aa3b, v16
	v_mul_f32_e32 v7, v2, v7
	v_mul_f32_e32 v2, 0xbfb8aa3b, v17
	v_exp_f32_e32 v4, v4
	v_exp_f32_e32 v0, v0
	v_exp_f32_e32 v1, v1
	v_exp_f32_e32 v2, v2
	v_mul_f32_e32 v9, 0xbfb8aa3b, v3
	v_exp_f32_e32 v9, v9
	v_add_f32_e32 v4, 1.0, v4
	v_add_f32_e32 v0, 1.0, v0
	v_add_f32_e32 v1, 1.0, v1
	v_add_f32_e32 v2, 1.0, v2
	v_rcp_f32_e32 v4, v4
	v_rcp_f32_e32 v0, v0
	v_rcp_f32_e32 v1, v1
	v_rcp_f32_e32 v2, v2
	v_add_f32_e32 v9, 1.0, v9
	v_rcp_f32_e32 v9, v9
	v_mul_f32_e32 v4, v14, v4
	v_mul_f32_e32 v0, v15, v0
	v_mul_f32_e32 v1, v16, v1
	v_mul_f32_e32 v2, v17, v2
	v_cvt_pk_bf16_f32 v0, v4, v0
	v_cvt_pk_bf16_f32 v1, v1, v2
	v_cvt_pk_bf16_f32 v2, v5, v6
	v_lshl_add_u64 v[4:5], v[10:11], 0, s[4:5]
	v_readlane_b32 s4, v253, 9
	s_add_i32 s6, s6, s4
	v_mul_f32_e32 v3, v3, v9
	s_cmpk_lt_i32 s7, 0x400
	v_cvt_pk_bf16_f32 v3, v7, v3
	global_store_dwordx4 v[4:5], v[0:3], off
	s_barrier
	v_readlane_b32 s5, v253, 10
	s_cbranch_scc0 .LBB0_465
.LBB0_434:
	s_movk_i32 s4, 0x2000
	v_ashrrev_i32_e32 v9, 31, v8
	v_lshlrev_b64 v[0:1], 2, v[8:9]
	v_lshl_add_u64 v[2:3], s[10:11], 0, v[0:1]
	v_add_co_u32_e32 v4, vcc, 0x1000, v2
	v_lshl_add_u64 v[0:1], s[12:13], 0, v[0:1]
	s_nop 0
	v_addc_co_u32_e32 v5, vcc, 0, v3, vcc
	v_add_co_u32_e32 v6, vcc, s4, v2
	s_movk_i32 s4, 0x4000
	s_nop 0
	v_addc_co_u32_e32 v7, vcc, 0, v3, vcc
	v_add_co_u32_e32 v10, vcc, 0x3000, v2
	s_ashr_i32 s5, s6, 31
	s_nop 0
	v_addc_co_u32_e32 v11, vcc, 0, v3, vcc
	global_load_dword v36, v[2:3], off
	global_load_dword v35, v[2:3], off offset:2048
	global_load_dword v34, v[4:5], off
	global_load_dword v33, v[4:5], off offset:2048
	global_load_dword v31, v[6:7], off
	global_load_dword v9, v[6:7], off offset:2048
	global_load_dword v32, v[10:11], off
	global_load_dword v30, v[10:11], off offset:2048
	v_add_co_u32_e32 v4, vcc, s4, v2
	s_movk_i32 s4, 0x6000
	s_nop 0
	v_addc_co_u32_e32 v5, vcc, 0, v3, vcc
	v_add_co_u32_e32 v6, vcc, 0x5000, v2
	s_lshr_b32 s5, s5, 19
	s_nop 0
	v_addc_co_u32_e32 v7, vcc, 0, v3, vcc
	v_add_co_u32_e32 v10, vcc, s4, v2
	s_mov_b32 s4, 0x8000
	s_nop 0
	v_addc_co_u32_e32 v11, vcc, 0, v3, vcc
	v_add_co_u32_e32 v12, vcc, 0x7000, v2
	s_add_i32 s5, s6, s5
	s_nop 0
	v_addc_co_u32_e32 v13, vcc, 0, v3, vcc
	global_load_dword v44, v[4:5], off
	global_load_dword v43, v[4:5], off offset:2048
	global_load_dword v42, v[6:7], off
	global_load_dword v41, v[6:7], off offset:2048
	global_load_dword v39, v[10:11], off
	global_load_dword v37, v[10:11], off offset:2048
	global_load_dword v40, v[12:13], off
	global_load_dword v38, v[12:13], off offset:2048
	v_add_co_u32_e32 v4, vcc, s4, v2
	s_mov_b32 s4, 0x9000
	s_nop 0
	v_addc_co_u32_e32 v5, vcc, 0, v3, vcc
	v_add_co_u32_e32 v6, vcc, s4, v2
	s_mov_b32 s4, 0xa000
	s_nop 0
	v_addc_co_u32_e32 v7, vcc, 0, v3, vcc
	v_add_co_u32_e32 v10, vcc, s4, v2
	s_mov_b32 s4, 0xb000
	s_nop 0
	v_addc_co_u32_e32 v11, vcc, 0, v3, vcc
	v_add_co_u32_e32 v12, vcc, s4, v2
	s_mov_b32 s4, 0xc000
	s_nop 0
	v_addc_co_u32_e32 v13, vcc, 0, v3, vcc
; #define LAS __attribute__((address_space(3)))
; __device__ __forceinline__ void conv_phase(LAS unsigned char* lds, const bf16_t* PROJ, const float* cw, const float* cb, const float* lg, const float* lb, bf16_t* MIXIN, int G, int tid) {
;     ...
;         for (int k = 0; k < 31; ++k) w[k] = cw[k * 512 + c];
;         const float bias = cb[c];
; #pragma unroll
;         for (int pass = 0; pass < 8; ++pass) { const int rr = pass * 8 + wave;
;             if (rr < 62) { f32x4 o0 = (f32x4){0.f, 0.f, 0.f, 0.f}, o1 = o0;
;                 if (t0 - 30 + rr >= 0) { const u32x4 a = *(const u32x4*)(PROJ + (size_t)(row0 - 30 + rr) * PROJ_LD + 8 * lane);
;                     o0 = (f32x4){__uint_as_float(a[0] << 16), __uint_as_float(a[0] & 0xffff0000u), __uint_as_float(a[1] << 16), __uint_as_float(a[1] & 0xffff0000u)};
;                     o1 = (f32x4){__uint_as_float(a[2] << 16), __uint_as_float(a[2] & 0xffff0000u), __uint_as_float(a[3] << 16), __uint_as_float(a[3] & 0xffff0000u)}; }
;                 *(LAS f32x4*)(U + rr * 512 + 8 * lane) = o0; *(LAS f32x4*)(U + rr * 512 + 8 * lane + 4) = o1; } }
	v_add_co_u32_e32 v14, vcc, s4, v2
	s_mov_b32 s4, 0xd000
	s_nop 0
	v_addc_co_u32_e32 v15, vcc, 0, v3, vcc
	v_add_co_u32_e32 v16, vcc, s4, v2
	s_mov_b32 s4, 0xe000
	s_nop 0
	v_addc_co_u32_e32 v17, vcc, 0, v3, vcc
	global_load_dword v53, v[6:7], off offset:-4096
	global_load_dword v52, v[6:7], off
	global_load_dword v51, v[6:7], off offset:2048
	global_load_dword v50, v[12:13], off offset:-4096
	global_load_dword v47, v[12:13], off
	global_load_dword v46, v[12:13], off offset:2048
	global_load_dword v48, v[16:17], off offset:-4096
	global_load_dword v45, v[16:17], off
	v_add_co_u32_e32 v6, vcc, s4, v2
	s_mov_b32 s4, 0xf000
	s_nop 0
	v_addc_co_u32_e32 v7, vcc, 0, v3, vcc
	v_add_co_u32_e32 v2, vcc, s4, v2
	s_and_b32 s5, s5, 0xffffe000
	s_nop 0
	v_addc_co_u32_e32 v3, vcc, 0, v3, vcc
	global_load_dword v60, v[4:5], off offset:2048
	global_load_dword v59, v[10:11], off offset:2048
	global_load_dword v56, v[14:15], off offset:2048
	global_load_dword v54, v[6:7], off offset:2048
	global_load_dword v58, v[16:17], off offset:2048
	global_load_dword v57, v[2:3], off offset:-4096
	global_load_dword v55, v[2:3], off
	global_load_dword v49, v[0:1], off
	v_readfirstlane_b32 s4, v8
	v_and_b32_e32 v12, 63, v8
	s_sub_i32 s5, s5, s6
	v_readlane_b32 s18, v252, 36
	s_ashr_i32 s4, s4, 6
	s_add_i32 s5, s5, 29
	v_lshlrev_b32_e32 v164, 4, v12
	v_readlane_b32 s19, v252, 37
	s_cmp_gt_i32 s4, 61
	v_lshl_add_u32 v13, v12, 5, 0
	v_lshl_add_u64 v[10:11], s[18:19], 0, v[164:165]
	s_add_i32 s18, s4, 0
	v_mov_b32_e32 v180, 0
	v_mov_b32_e32 v181, 0
	v_mov_b32_e32 v182, 0
	v_mov_b32_e32 v183, 0
	s_cmp_gt_i32 s18, 61
	s_cbranch_scc1 .Lcs_a0
	s_cmp_le_i32 s18, s5
	s_cbranch_scc1 .Lcs_a0
	s_add_i32 s19, s6, s18
	s_sub_i32 s19, s19, 30
	v_mad_i64_i32 v[0:1], s[20:21], s19, v232, v[10:11]
	global_load_dwordx4 v[180:183], v[0:1], off
.Lcs_a0:
	s_add_i32 s18, s4, 8
	v_mov_b32_e32 v184, 0
	v_mov_b32_e32 v185, 0
	v_mov_b32_e32 v186, 0
	v_mov_b32_e32 v187, 0
	s_cmp_gt_i32 s18, 61
	s_cbranch_scc1 .Lcs_a1
	s_cmp_le_i32 s18, s5
	s_cbranch_scc1 .Lcs_a1
	s_add_i32 s19, s6, s18
	s_sub_i32 s19, s19, 30
	v_mad_i64_i32 v[0:1], s[20:21], s19, v232, v[10:11]
	global_load_dwordx4 v[184:187], v[0:1], off
.Lcs_a1:
	s_add_i32 s18, s4, 16
	v_mov_b32_e32 v188, 0
	v_mov_b32_e32 v189, 0
	v_mov_b32_e32 v190, 0
	v_mov_b32_e32 v191, 0
	s_cmp_gt_i32 s18, 61
	s_cbranch_scc1 .Lcs_a2
	s_cmp_le_i32 s18, s5
	s_cbranch_scc1 .Lcs_a2
	s_add_i32 s19, s6, s18
	s_sub_i32 s19, s19, 30
	v_mad_i64_i32 v[0:1], s[20:21], s19, v232, v[10:11]
	global_load_dwordx4 v[188:191], v[0:1], off
.Lcs_a2:
	s_add_i32 s18, s4, 24
	v_mov_b32_e32 v192, 0
	v_mov_b32_e32 v193, 0
	v_mov_b32_e32 v194, 0
	v_mov_b32_e32 v195, 0
	s_cmp_gt_i32 s18, 61
	s_cbranch_scc1 .Lcs_a3
	s_cmp_le_i32 s18, s5
	s_cbranch_scc1 .Lcs_a3
	s_add_i32 s19, s6, s18
	s_sub_i32 s19, s19, 30
	v_mad_i64_i32 v[0:1], s[20:21], s19, v232, v[10:11]
	global_load_dwordx4 v[192:195], v[0:1], off
.Lcs_a3:
	s_add_i32 s18, s4, 32
	v_mov_b32_e32 v196, 0
	v_mov_b32_e32 v197, 0
	v_mov_b32_e32 v198, 0
	v_mov_b32_e32 v199, 0
	s_cmp_gt_i32 s18, 61
	s_cbranch_scc1 .Lcs_a4
	s_cmp_le_i32 s18, s5
	s_cbranch_scc1 .Lcs_a4
	s_add_i32 s19, s6, s18
	s_sub_i32 s19, s19, 30
	v_mad_i64_i32 v[0:1], s[20:21], s19, v232, v[10:11]
	global_load_dwordx4 v[196:199], v[0:1], off
.Lcs_a4:
	s_add_i32 s18, s4, 40
	v_mov_b32_e32 v200, 0
	v_mov_b32_e32 v201, 0
	v_mov_b32_e32 v202, 0
	v_mov_b32_e32 v203, 0
	s_cmp_gt_i32 s18, 61
	s_cbranch_scc1 .Lcs_a5
	s_cmp_le_i32 s18, s5
	s_cbranch_scc1 .Lcs_a5
	s_add_i32 s19, s6, s18
	s_sub_i32 s19, s19, 30
	v_mad_i64_i32 v[0:1], s[20:21], s19, v232, v[10:11]
	global_load_dwordx4 v[200:203], v[0:1], off
.Lcs_a5:
	s_add_i32 s18, s4, 48
	v_mov_b32_e32 v204, 0
	v_mov_b32_e32 v205, 0
	v_mov_b32_e32 v206, 0
	v_mov_b32_e32 v207, 0
	s_cmp_gt_i32 s18, 61
	s_cbranch_scc1 .Lcs_a6
	s_cmp_le_i32 s18, s5
	s_cbranch_scc1 .Lcs_a6
	s_add_i32 s19, s6, s18
	s_sub_i32 s19, s19, 30
	v_mad_i64_i32 v[0:1], s[20:21], s19, v232, v[10:11]
	global_load_dwordx4 v[204:207], v[0:1], off
.Lcs_a6:
	s_add_i32 s18, s4, 56
	v_mov_b32_e32 v208, 0
	v_mov_b32_e32 v209, 0
	v_mov_b32_e32 v210, 0
	v_mov_b32_e32 v211, 0
	s_cmp_gt_i32 s18, 61
	s_cbranch_scc1 .Lcs_a7
	s_cmp_le_i32 s18, s5
	s_cbranch_scc1 .Lcs_a7
	s_add_i32 s19, s6, s18
	s_sub_i32 s19, s19, 30
	v_mad_i64_i32 v[0:1], s[20:21], s19, v232, v[10:11]
	global_load_dwordx4 v[208:211], v[0:1], off
; #define LAS __attribute__((address_space(3)))
; __device__ __forceinline__ void conv_phase(LAS unsigned char* lds, const bf16_t* PROJ, const float* cw, const float* cb, const float* lg, const float* lb, bf16_t* MIXIN, int G, int tid) {
;     ...
;         for (int pass = 0; pass < 8; ++pass) { const int rr = pass * 8 + wave;
;             if (rr < 62) { f32x4 o0 = (f32x4){0.f, 0.f, 0.f, 0.f}, o1 = o0;
;                 if (t0 - 30 + rr >= 0) { const u32x4 a = *(const u32x4*)(PROJ + (size_t)(row0 - 30 + rr) * PROJ_LD + 8 * lane);
;                     o0 = (f32x4){__uint_as_float(a[0] << 16), __uint_as_float(a[0] & 0xffff0000u), __uint_as_float(a[1] << 16), __uint_as_float(a[1] & 0xffff0000u)};
;                     o1 = (f32x4){__uint_as_float(a[2] << 16), __uint_as_float(a[2] & 0xffff0000u), __uint_as_float(a[3] << 16), __uint_as_float(a[3] & 0xffff0000u)}; }
;                 *(LAS f32x4*)(U + rr * 512 + 8 * lane) = o0; *(LAS f32x4*)(U + rr * 512 + 8 * lane + 4) = o1; } }
; __device__ __forceinline__ void gla_g1_phase(LAS unsigned char* lds, const bf16_t* PROJ, const bf16_t* ALOW, const float* wa2, const float* ba, float* UPD, float* DEC, int G, int tid) {
;     LAS bf16_t* KD = (LAS bf16_t*)lds; LAS bf16_t* VT = (LAS bf16_t*)(lds + 18432);
;     const int lane = tid & 63, wave = __builtin_amdgcn_readfirstlane(tid >> 6);
;     G1In cur; if ((int)blockIdx.x < 2048) cur = g1_load(PROJ, ALOW, blockIdx.x, lane, wave);
;     for (int u = blockIdx.x; u < 2048; u += G) {
;         G1In nxt; if (u + G < 2048) nxt = g1_load(PROJ, ALOW, u + G, lane, wave);
.Lcs_a7:
	s_waitcnt vmcnt(0)
	s_add_i32 s18, s4, 0
	s_cmp_gt_i32 s18, 61
	s_cbranch_scc1 .Lcs_done
	v_lshlrev_b32_e32 v4, 16, v180
	v_and_b32_e32 v5, 0xffff0000, v180
	v_lshlrev_b32_e32 v6, 16, v181
	v_and_b32_e32 v7, 0xffff0000, v181
	v_lshlrev_b32_e32 v0, 16, v182
	v_and_b32_e32 v1, 0xffff0000, v182
	v_lshlrev_b32_e32 v2, 16, v183
	v_and_b32_e32 v3, 0xffff0000, v183
	v_lshl_add_u32 v14, s18, 11, v13
	ds_write_b128 v14, v[4:7]
	ds_write_b128 v14, v[0:3] offset:16
	s_add_i32 s18, s4, 8
	s_cmp_gt_i32 s18, 61
	s_cbranch_scc1 .Lcs_done
	v_lshlrev_b32_e32 v4, 16, v184
	v_and_b32_e32 v5, 0xffff0000, v184
	v_lshlrev_b32_e32 v6, 16, v185
	v_and_b32_e32 v7, 0xffff0000, v185
	v_lshlrev_b32_e32 v0, 16, v186
	v_and_b32_e32 v1, 0xffff0000, v186
	v_lshlrev_b32_e32 v2, 16, v187
	v_and_b32_e32 v3, 0xffff0000, v187
	v_lshl_add_u32 v14, s18, 11, v13
	ds_write_b128 v14, v[4:7]
	ds_write_b128 v14, v[0:3] offset:16
	s_add_i32 s18, s4, 16
	s_cmp_gt_i32 s18, 61
	s_cbranch_scc1 .Lcs_done
	v_lshlrev_b32_e32 v4, 16, v188
	v_and_b32_e32 v5, 0xffff0000, v188
	v_lshlrev_b32_e32 v6, 16, v189
	v_and_b32_e32 v7, 0xffff0000, v189
	v_lshlrev_b32_e32 v0, 16, v190
	v_and_b32_e32 v1, 0xffff0000, v190
	v_lshlrev_b32_e32 v2, 16, v191
	v_and_b32_e32 v3, 0xffff0000, v191
	v_lshl_add_u32 v14, s18, 11, v13
	ds_write_b128 v14, v[4:7]
	ds_write_b128 v14, v[0:3] offset:16
	s_add_i32 s18, s4, 24
	s_cmp_gt_i32 s18, 61
	s_cbranch_scc1 .Lcs_done
	v_lshlrev_b32_e32 v4, 16, v192
	v_and_b32_e32 v5, 0xffff0000, v192
	v_lshlrev_b32_e32 v6, 16, v193
	v_and_b32_e32 v7, 0xffff0000, v193
	v_lshlrev_b32_e32 v0, 16, v194
	v_and_b32_e32 v1, 0xffff0000, v194
	v_lshlrev_b32_e32 v2, 16, v195
	v_and_b32_e32 v3, 0xffff0000, v195
	v_lshl_add_u32 v14, s18, 11, v13
	ds_write_b128 v14, v[4:7]
	ds_write_b128 v14, v[0:3] offset:16
	s_add_i32 s18, s4, 32
	s_cmp_gt_i32 s18, 61
	s_cbranch_scc1 .Lcs_done
	v_lshlrev_b32_e32 v4, 16, v196
	v_and_b32_e32 v5, 0xffff0000, v196
	v_lshlrev_b32_e32 v6, 16, v197
	v_and_b32_e32 v7, 0xffff0000, v197
	v_lshlrev_b32_e32 v0, 16, v198
	v_and_b32_e32 v1, 0xffff0000, v198
	v_lshlrev_b32_e32 v2, 16, v199
	v_and_b32_e32 v3, 0xffff0000, v199
	v_lshl_add_u32 v14, s18, 11, v13
	ds_write_b128 v14, v[4:7]
	ds_write_b128 v14, v[0:3] offset:16
	s_add_i32 s18, s4, 40
	s_cmp_gt_i32 s18, 61
	s_cbranch_scc1 .Lcs_done
	v_lshlrev_b32_e32 v4, 16, v200
	v_and_b32_e32 v5, 0xffff0000, v200
	v_lshlrev_b32_e32 v6, 16, v201
	v_and_b32_e32 v7, 0xffff0000, v201
	v_lshlrev_b32_e32 v0, 16, v202
	v_and_b32_e32 v1, 0xffff0000, v202
	v_lshlrev_b32_e32 v2, 16, v203
	v_and_b32_e32 v3, 0xffff0000, v203
	v_lshl_add_u32 v14, s18, 11, v13
	ds_write_b128 v14, v[4:7]
	ds_write_b128 v14, v[0:3] offset:16
	s_add_i32 s18, s4, 48
	s_cmp_gt_i32 s18, 61
	s_cbranch_scc1 .Lcs_done
	v_lshlrev_b32_e32 v4, 16, v204
	v_and_b32_e32 v5, 0xffff0000, v204
	v_lshlrev_b32_e32 v6, 16, v205
	v_and_b32_e32 v7, 0xffff0000, v205
	v_lshlrev_b32_e32 v0, 16, v206
	v_and_b32_e32 v1, 0xffff0000, v206
	v_lshlrev_b32_e32 v2, 16, v207
	v_and_b32_e32 v3, 0xffff0000, v207
	v_lshl_add_u32 v14, s18, 11, v13
	ds_write_b128 v14, v[4:7]
	ds_write_b128 v14, v[0:3] offset:16
	s_add_i32 s18, s4, 56
	s_cmp_gt_i32 s18, 61
	s_cbranch_scc1 .Lcs_done
	v_lshlrev_b32_e32 v4, 16, v208
	v_and_b32_e32 v5, 0xffff0000, v208
	v_lshlrev_b32_e32 v6, 16, v209
	v_and_b32_e32 v7, 0xffff0000, v209
	v_lshlrev_b32_e32 v0, 16, v210
	v_and_b32_e32 v1, 0xffff0000, v210
	v_lshlrev_b32_e32 v2, 16, v211
	v_and_b32_e32 v3, 0xffff0000, v211
	v_lshl_add_u32 v14, s18, 11, v13
	ds_write_b128 v14, v[4:7]
	ds_write_b128 v14, v[0:3] offset:16
.Lcs_done:
	s_branch .LBB0_433
.LBB0_465:
	v_readlane_b32 s4, v251, 2
	v_readlane_b32 s5, v251, 3
	v_readlane_b32 s6, v251, 0
	s_or_b64 s[4:5], s[4:5], s[8:9]
	v_readlane_b32 s7, v251, 1
	s_and_b64 s[4:5], s[6:7], s[4:5]
	s_andn2_b64 vcc, exec, s[4:5]
	s_cbranch_vccnz .LBB0_539
	s_mov_b32 s4, 5
	s_ashr_i32 s5, s4, 31
	s_lshl_b64 s[4:5], s[4:5], 3
	s_add_u32 s4, s0, s4
	s_mov_b32 s6, 6
	s_addc_u32 s5, s1, s5
	s_ashr_i32 s7, s6, 31
	v_readlane_b32 s12, v250, 49
	s_lshl_b64 s[6:7], s[6:7], 3
	v_readlane_b32 s13, v250, 50
	s_add_u32 s10, s0, s6
	v_readfirstlane_b32 s6, v170
	s_waitcnt vmcnt(0)
	v_cndmask_b32_e64 v0, 0, 1, s[12:13]
	s_addc_u32 s11, s1, s7
	v_cmp_ne_u32_e64 s[8:9], 1, v0
	s_andn2_b64 vcc, exec, s[12:13]
	s_ashr_i32 s7, s6, 6
	s_cbranch_vccnz .LBB0_468
	v_readlane_b32 s12, v250, 53
	v_readlane_b32 s14, v250, 55
	s_nop 0
	v_or_b32_e32 v0, s12, v172
	v_readlane_b32 s12, v252, 36
	v_readlane_b32 s13, v252, 37
	s_waitcnt lgkmcnt(0)
	v_ashrrev_i32_e32 v1, 31, v0
	v_mov_b64_e32 v[2:3], s[12:13]
	s_movk_i32 s12, 0x1400
	v_mad_i64_i32 v[2:3], s[12:13], v0, s12, v[2:3]
	v_readlane_b32 s12, v250, 8
	v_lshlrev_b64 v[0:1], 5, v[0:1]
	v_readlane_b32 s13, v250, 9
	s_nop 1
	v_lshl_add_u64 v[0:1], s[12:13], 0, v[0:1]
	v_readlane_b32 s12, v250, 54
	s_lshl_b32 s74, s12, 1
	s_lshl_b32 s12, s7, 3
	global_load_dwordx4 v[12:15], v[0:1], off offset:16
	global_load_dwordx4 v[36:39], v[0:1], off
	v_lshl_add_u64 v[0:1], v[2:3], 0, s[74:75]
	s_ashr_i32 s13, s12, 31
	s_lshl_b32 s74, s14, 1
	s_lshl_b64 s[12:13], s[12:13], 1
	v_lshl_add_u64 v[2:3], v[2:3], 0, s[74:75]
	v_lshl_add_u64 v[0:1], v[0:1], 0, s[12:13]
	v_lshl_add_u64 v[2:3], v[2:3], 0, s[12:13]
	global_load_dwordx4 v[8:11], v[0:1], off offset:2560
	global_load_dwordx4 v[4:7], v[2:3], off offset:3072
	s_nop 0
	global_load_dwordx4 v[0:3], v[2:3], off offset:3200

; #define LAS __attribute__((address_space(3)))
; #define LDS_WAIT() asm volatile("s_waitcnt lgkmcnt(0)" ::: "memory")
; #define INP(k) ({ int k_ = (k); asm volatile("" : "+s"(k_)); a.in[k_]; })
; __device__ __forceinline__ void cvt_item(const float* W, int K, int N, int k0, int n0, bf16_t* dst, LAS float* scr, int lane) {
; #pragma unroll
;     for (int i = 0; i < 32; ++i) { const int kk = 2 * i + (lane >> 5), n = n0 + (lane & 31); scr[kk * 33 + (lane & 31)] = n < N ? W[(size_t)(k0 + kk) * N + n] : 0.f; }
;     LDS_WAIT(); asm volatile("" ::: "memory");
; __global__ void __launch_bounds__(NWAVES * 64) mega(Args a) {
;     ...
;                 if (r < I_XKV) { const int kb = r / 64, n0 = 32 * (r % 64);
;                     bf16_t* dst = n0 < 1024 ? WT + WT_XK + (size_t)(l * 1024 + n0) * 1024 : WT + WT_XV + (size_t)(l * 1024 + n0 - 1024) * 1024;
;                     cvt_item(INP(16) + (size_t)l * 1024 * 2048, 1024, 2048, 64 * kb, n0, dst, scr, lane); continue; } r -= I_XKV;
.LBB0_773:
	s_andn2_b64 vcc, exec, s[4:5]
	s_cbranch_vccnz .LBB0_775
	s_add_i32 s4, s25, 0xfffff4f0
	s_and_b32 s74, s4, 0xffffffc0
	s_lshl_b32 s4, s10, 9
	s_sub_i32 s4, s6, s4
	s_and_b32 s16, s4, 0x7e0
	s_cmpk_lt_u32 s16, 0x400
	s_cselect_b64 s[4:5], -1, 0
	s_lshl_b32 s12, s10, 10
	s_add_i32 s13, s12, s16
	s_addk_i32 s13, 0xfc00
	s_or_b32 s12, s16, s12
	s_and_b64 s[4:5], s[4:5], exec
	s_cselect_b32 s4, s12, s13
	v_readlane_b32 s5, v252, 45
	v_readlane_b32 s12, v252, 16
	s_cselect_b32 s13, s5, s12
	v_readlane_b32 s5, v252, 44
	v_readlane_b32 s12, v252, 15
	s_cselect_b32 s12, s5, s12
	s_ashr_i32 s5, s4, 31
	s_lshl_b64 s[4:5], s[4:5], 11
	s_add_u32 s12, s12, s4
	s_mov_b32 s4, 16
	s_addc_u32 s13, s13, s5
	s_ashr_i32 s5, s4, 31
	s_lshl_b64 s[4:5], s[4:5], 3
	s_add_u32 s4, s0, s4
	s_addc_u32 s5, s1, s5
	s_load_dwordx2 s[4:5], s[4:5], 0x0
	s_lshl_b64 s[14:15], s[10:11], 23
	v_or_b32_e32 v7, s16, v1
	v_or_b32_e32 v16, s74, v2
	v_lshl_or_b32 v164, v16, 11, v7
	s_waitcnt lgkmcnt(0)
	s_add_u32 s4, s4, s14
	s_addc_u32 s5, s5, s15
	v_lshl_add_u64 v[16:17], v[164:165], 2, s[4:5]
	v_mov_b32_e32 v180, v16
	v_mov_b32_e32 v181, v17
	v_add_u32_e32 v214, v5, v9
	s_mov_b64 vcc, 0x4000
	global_load_dword v182, v[180:181], off
	v_lshl_add_u64 v[180:181], v[180:181], 0, vcc
	global_load_dword v183, v[180:181], off
	v_lshl_add_u64 v[180:181], v[180:181], 0, vcc
	global_load_dword v184, v[180:181], off
	v_lshl_add_u64 v[180:181], v[180:181], 0, vcc
	global_load_dword v185, v[180:181], off
	v_lshl_add_u64 v[180:181], v[180:181], 0, vcc
	global_load_dword v186, v[180:181], off
	v_lshl_add_u64 v[180:181], v[180:181], 0, vcc
	global_load_dword v187, v[180:181], off
	v_lshl_add_u64 v[180:181], v[180:181], 0, vcc
	global_load_dword v188, v[180:181], off
	v_lshl_add_u64 v[180:181], v[180:181], 0, vcc
	global_load_dword v189, v[180:181], off
	v_lshl_add_u64 v[180:181], v[180:181], 0, vcc
	global_load_dword v190, v[180:181], off
	v_lshl_add_u64 v[180:181], v[180:181], 0, vcc
	global_load_dword v191, v[180:181], off
	v_lshl_add_u64 v[180:181], v[180:181], 0, vcc
	global_load_dword v192, v[180:181], off
	v_lshl_add_u64 v[180:181], v[180:181], 0, vcc
	global_load_dword v193, v[180:181], off
	v_lshl_add_u64 v[180:181], v[180:181], 0, vcc
	global_load_dword v194, v[180:181], off
	v_lshl_add_u64 v[180:181], v[180:181], 0, vcc
	global_load_dword v195, v[180:181], off
	v_lshl_add_u64 v[180:181], v[180:181], 0, vcc
	global_load_dword v196, v[180:181], off
	v_lshl_add_u64 v[180:181], v[180:181], 0, vcc
	global_load_dword v197, v[180:181], off
	v_lshl_add_u64 v[180:181], v[180:181], 0, vcc
	global_load_dword v198, v[180:181], off
	v_lshl_add_u64 v[180:181], v[180:181], 0, vcc
	global_load_dword v199, v[180:181], off
	v_lshl_add_u64 v[180:181], v[180:181], 0, vcc
	global_load_dword v200, v[180:181], off
	v_lshl_add_u64 v[180:181], v[180:181], 0, vcc
	global_load_dword v201, v[180:181], off
	v_lshl_add_u64 v[180:181], v[180:181], 0, vcc
	global_load_dword v202, v[180:181], off
	v_lshl_add_u64 v[180:181], v[180:181], 0, vcc
	global_load_dword v203, v[180:181], off
	v_lshl_add_u64 v[180:181], v[180:181], 0, vcc
	global_load_dword v204, v[180:181], off
	v_lshl_add_u64 v[180:181], v[180:181], 0, vcc
	global_load_dword v205, v[180:181], off
	v_lshl_add_u64 v[180:181], v[180:181], 0, vcc
	global_load_dword v206, v[180:181], off
	v_lshl_add_u64 v[180:181], v[180:181], 0, vcc
	global_load_dword v207, v[180:181], off
	v_lshl_add_u64 v[180:181], v[180:181], 0, vcc
	global_load_dword v208, v[180:181], off
	v_lshl_add_u64 v[180:181], v[180:181], 0, vcc
	global_load_dword v209, v[180:181], off
	v_lshl_add_u64 v[180:181], v[180:181], 0, vcc
	global_load_dword v210, v[180:181], off
	v_lshl_add_u64 v[180:181], v[180:181], 0, vcc
	global_load_dword v211, v[180:181], off
	v_lshl_add_u64 v[180:181], v[180:181], 0, vcc
	global_load_dword v212, v[180:181], off
	v_lshl_add_u64 v[180:181], v[180:181], 0, vcc
	global_load_dword v213, v[180:181], off
	s_waitcnt vmcnt(31)
	ds_write_b32 v214, v182
	s_waitcnt vmcnt(30)
	ds_write_b32 v214, v183 offset:264
	s_waitcnt vmcnt(29)
	ds_write_b32 v214, v184 offset:528
	s_waitcnt vmcnt(28)
	ds_write_b32 v214, v185 offset:792
	s_waitcnt vmcnt(27)
	ds_write_b32 v214, v186 offset:1056
	s_waitcnt vmcnt(26)
	ds_write_b32 v214, v187 offset:1320
	s_waitcnt vmcnt(25)
	ds_write_b32 v214, v188 offset:1584
	s_waitcnt vmcnt(24)
	ds_write_b32 v214, v189 offset:1848
	s_waitcnt vmcnt(23)
	ds_write_b32 v214, v190 offset:2112
	s_waitcnt vmcnt(22)
	ds_write_b32 v214, v191 offset:2376
	s_waitcnt vmcnt(21)
	ds_write_b32 v214, v192 offset:2640
	s_waitcnt vmcnt(20)
	ds_write_b32 v214, v193 offset:2904
	s_waitcnt vmcnt(19)
	ds_write_b32 v214, v194 offset:3168
	s_waitcnt vmcnt(18)
	ds_write_b32 v214, v195 offset:3432
	s_waitcnt vmcnt(17)
	ds_write_b32 v214, v196 offset:3696
	s_waitcnt vmcnt(16)
	ds_write_b32 v214, v197 offset:3960
	s_waitcnt vmcnt(15)
	ds_write_b32 v214, v198 offset:4224
	s_waitcnt vmcnt(14)
	ds_write_b32 v214, v199 offset:4488
	s_waitcnt vmcnt(13)
	ds_write_b32 v214, v200 offset:4752
	s_waitcnt vmcnt(12)
	ds_write_b32 v214, v201 offset:5016
	s_waitcnt vmcnt(11)
	ds_write_b32 v214, v202 offset:5280
	s_waitcnt vmcnt(10)
	ds_write_b32 v214, v203 offset:5544
	s_waitcnt vmcnt(9)
; #define LAS __attribute__((address_space(3)))
; #define LDS_WAIT() asm volatile("s_waitcnt lgkmcnt(0)" ::: "memory")
; __device__ __forceinline__ unsigned pk2(float lo, float hi) { return (unsigned)f2bf(lo) | ((unsigned)f2bf(hi) << 16); }
; __device__ __forceinline__ void cvt_item(const float* W, int K, int N, int k0, int n0, bf16_t* dst, LAS float* scr, int lane) {
;     ...
;     for (int i = 0; i < 32; ++i) { const int kk = 2 * i + (lane >> 5), n = n0 + (lane & 31); scr[kk * 33 + (lane & 31)] = n < N ? W[(size_t)(k0 + kk) * N + n] : 0.f; }
;     LDS_WAIT(); asm volatile("" ::: "memory");
;     const int c = lane & 7;
; #pragma unroll
;     for (int j = 0; j < 4; ++j) { const int n = (lane >> 3) + 8 * j; const LAS float* s = scr + (8 * c) * 33 + n;
;         u32x4 o; o.x = pk2(s[0 * 33], s[1 * 33]); o.y = pk2(s[2 * 33], s[3 * 33]); o.z = pk2(s[4 * 33], s[5 * 33]); o.w = pk2(s[6 * 33], s[7 * 33]);
;         *(u32x4*)(dst + (size_t)n * K + k0 + 8 * c) = o; }
;     LDS_WAIT(); asm volatile("" ::: "memory");
	ds_write_b32 v214, v204 offset:5808
	s_waitcnt vmcnt(8)
	ds_write_b32 v214, v205 offset:6072
	s_waitcnt vmcnt(7)
	ds_write_b32 v214, v206 offset:6336
	s_waitcnt vmcnt(6)
	ds_write_b32 v214, v207 offset:6600
	s_waitcnt vmcnt(5)
	ds_write_b32 v214, v208 offset:6864
	s_waitcnt vmcnt(4)
	ds_write_b32 v214, v209 offset:7128
	s_waitcnt vmcnt(3)
	ds_write_b32 v214, v210 offset:7392
	s_waitcnt vmcnt(2)
	ds_write_b32 v214, v211 offset:7656
	s_waitcnt vmcnt(1)
	ds_write_b32 v214, v212 offset:7920
	s_waitcnt vmcnt(0)
	ds_write_b32 v214, v213 offset:8184
	s_lshl_b64 s[4:5], s[74:75], 1
	s_add_u32 s4, s12, s4
	s_addc_u32 s5, s13, s5
	v_lshlrev_b32_e32 v164, 1, v4
	v_lshl_add_u64 v[16:17], s[4:5], 0, v[164:165]
	v_lshlrev_b32_e32 v164, 1, v8
	v_lshl_add_u64 v[92:93], v[16:17], 0, v[164:165]
	v_lshlrev_b32_e32 v164, 1, v10
	s_waitcnt lgkmcnt(0)
	ds_read2_b32 v[76:77], v24 offset0:33 offset1:41
	ds_read2_b32 v[78:79], v24 offset1:8
	ds_read2_b32 v[80:81], v24 offset0:66 offset1:74
	ds_read2_b32 v[82:83], v24 offset0:99 offset1:107
	ds_read2_b32 v[84:85], v24 offset0:132 offset1:140
	ds_read2_b32 v[86:87], v24 offset0:165 offset1:173
	ds_read2_b32 v[88:89], v24 offset0:198 offset1:206
	ds_read2_b32 v[90:91], v24 offset0:231 offset1:239
	s_waitcnt lgkmcnt(7)
	v_bfe_u32 v18, v76, 16, 1
	s_waitcnt lgkmcnt(6)
	v_bfe_u32 v7, v78, 16, 1
	v_add3_u32 v7, v78, v7, s67
	v_lshrrev_b32_e32 v7, 16, v7
	v_add3_u32 v18, v76, v18, s67
	v_and_or_b32 v18, v18, s57, v7
	s_waitcnt lgkmcnt(5)
	v_bfe_u32 v7, v80, 16, 1
	v_add3_u32 v7, v80, v7, s67
	s_waitcnt lgkmcnt(4)
	v_bfe_u32 v19, v82, 16, 1
	v_lshrrev_b32_e32 v7, 16, v7
	v_add3_u32 v19, v82, v19, s67
	v_and_or_b32 v19, v19, s57, v7
	s_waitcnt lgkmcnt(3)
	v_bfe_u32 v7, v84, 16, 1
	v_add3_u32 v7, v84, v7, s67
	s_waitcnt lgkmcnt(2)
	v_bfe_u32 v20, v86, 16, 1
	v_lshrrev_b32_e32 v7, 16, v7
	v_add3_u32 v20, v86, v20, s67
	v_and_or_b32 v20, v20, s57, v7
	s_waitcnt lgkmcnt(1)
	v_bfe_u32 v7, v88, 16, 1
	v_add3_u32 v7, v88, v7, s67
	s_waitcnt lgkmcnt(0)
	v_bfe_u32 v21, v90, 16, 1
	v_lshrrev_b32_e32 v7, 16, v7
	v_add3_u32 v21, v90, v21, s67
	v_and_or_b32 v21, v21, s57, v7
	v_bfe_u32 v7, v79, 16, 1
	global_store_dwordx4 v[92:93], v[18:21], off
	v_add3_u32 v7, v79, v7, s67
	v_lshrrev_b32_e32 v7, 16, v7
	v_bfe_u32 v18, v77, 16, 1
	v_add3_u32 v18, v77, v18, s67
	v_and_or_b32 v18, v18, s57, v7
	v_bfe_u32 v7, v81, 16, 1
	v_add3_u32 v7, v81, v7, s67
	v_bfe_u32 v19, v83, 16, 1
	v_lshrrev_b32_e32 v7, 16, v7
	v_add3_u32 v19, v83, v19, s67
	v_and_or_b32 v19, v19, s57, v7
	v_bfe_u32 v7, v85, 16, 1
	v_add3_u32 v7, v85, v7, s67
	v_bfe_u32 v20, v87, 16, 1
	v_lshrrev_b32_e32 v7, 16, v7
	v_add3_u32 v20, v87, v20, s67
	v_and_or_b32 v20, v20, s57, v7
	v_bfe_u32 v7, v89, 16, 1
	v_add3_u32 v7, v89, v7, s67
	v_bfe_u32 v21, v91, 16, 1
	v_lshrrev_b32_e32 v7, 16, v7
	v_add3_u32 v21, v91, v21, s67
	v_and_or_b32 v21, v21, s57, v7
	v_lshl_add_u64 v[76:77], v[16:17], 0, v[164:165]
	global_store_dwordx4 v[76:77], v[18:21], off
	ds_read2_b32 v[76:77], v24 offset0:49 offset1:57
	ds_read2_b32 v[78:79], v24 offset0:16 offset1:24
	ds_read2_b32 v[80:81], v24 offset0:82 offset1:90
	ds_read2_b32 v[82:83], v24 offset0:115 offset1:123
	ds_read2_b32 v[84:85], v24 offset0:148 offset1:156
	ds_read2_b32 v[86:87], v24 offset0:181 offset1:189
	ds_read2_b32 v[88:89], v24 offset0:214 offset1:222
	ds_read2_b32 v[90:91], v24 offset0:247 offset1:255
	s_waitcnt lgkmcnt(7)
	v_bfe_u32 v18, v76, 16, 1
	s_waitcnt lgkmcnt(6)
	v_bfe_u32 v7, v78, 16, 1
	v_add3_u32 v7, v78, v7, s67
	v_lshrrev_b32_e32 v7, 16, v7
	v_add3_u32 v18, v76, v18, s67
	v_and_or_b32 v18, v18, s57, v7
	s_waitcnt lgkmcnt(5)
	v_bfe_u32 v7, v80, 16, 1
	v_add3_u32 v7, v80, v7, s67
	s_waitcnt lgkmcnt(4)
	v_bfe_u32 v19, v82, 16, 1
	v_lshrrev_b32_e32 v7, 16, v7
	v_add3_u32 v19, v82, v19, s67
	v_and_or_b32 v19, v19, s57, v7
	s_waitcnt lgkmcnt(3)
	v_bfe_u32 v7, v84, 16, 1
	v_add3_u32 v7, v84, v7, s67
	s_waitcnt lgkmcnt(2)
	v_bfe_u32 v20, v86, 16, 1
	v_lshrrev_b32_e32 v7, 16, v7
	v_add3_u32 v20, v86, v20, s67
	v_and_or_b32 v20, v20, s57, v7
	s_waitcnt lgkmcnt(1)
	v_bfe_u32 v7, v88, 16, 1
	v_add3_u32 v7, v88, v7, s67
	s_waitcnt lgkmcnt(0)
	v_bfe_u32 v21, v90, 16, 1
	v_lshrrev_b32_e32 v7, 16, v7
	v_add3_u32 v21, v90, v21, s67
	v_lshlrev_b32_e32 v164, 1, v12
	v_and_or_b32 v21, v21, s57, v7
	v_lshl_add_u64 v[92:93], v[16:17], 0, v[164:165]
	v_bfe_u32 v7, v79, 16, 1
	global_store_dwordx4 v[92:93], v[18:21], off
	v_add3_u32 v7, v79, v7, s67
	v_lshrrev_b32_e32 v7, 16, v7
	v_bfe_u32 v18, v77, 16, 1
	v_add3_u32 v18, v77, v18, s67
	v_and_or_b32 v18, v18, s57, v7
	v_bfe_u32 v7, v81, 16, 1
	v_add3_u32 v7, v81, v7, s67
	v_bfe_u32 v19, v83, 16, 1
	v_lshrrev_b32_e32 v7, 16, v7
	v_add3_u32 v19, v83, v19, s67
	v_and_or_b32 v19, v19, s57, v7
	v_bfe_u32 v7, v85, 16, 1
	v_add3_u32 v7, v85, v7, s67
	v_bfe_u32 v20, v87, 16, 1
	v_lshrrev_b32_e32 v7, 16, v7
	v_add3_u32 v20, v87, v20, s67
	v_and_or_b32 v20, v20, s57, v7
	v_bfe_u32 v7, v89, 16, 1
	v_add3_u32 v7, v89, v7, s67
	v_bfe_u32 v21, v91, 16, 1
	v_lshrrev_b32_e32 v7, 16, v7
	v_add3_u32 v21, v91, v21, s67
	v_lshlrev_b32_e32 v164, 1, v14
	v_and_or_b32 v21, v21, s57, v7
	v_lshl_add_u64 v[16:17], v[16:17], 0, v[164:165]
	global_store_dwordx4 v[16:17], v[18:21], off
	s_waitcnt lgkmcnt(0)

; __device__ __forceinline__ float bf2f(bf16_t b) { return __uint_as_float(((unsigned)b) << 16); }
; __device__ __forceinline__ bf16_t f2bf(float f) { unsigned u = __float_as_uint(f); return (bf16_t)((u + 0x7fffu + ((u >> 16) & 1u)) >> 16); }
; #define LAS __attribute__((address_space(3)))
; #define INP(k) ({ int k_ = (k); asm volatile("" : "+s"(k_)); a.in[k_]; })
; __device__ __forceinline__ void cvt_item_ln(const float* W, int K, int N, int k0, int n0, bf16_t* dst, LAS float* scr, int lane, const float* g, const float* b, float* csp, float* cbp) {
;     float cs = 0.f, cb = 0.f;
; #pragma unroll
;     for (int i = 0; i < 32; ++i) { const int kk = 2 * i + (lane >> 5), n = n0 + (lane & 31); const float w = n < N ? W[(size_t)(k0 + kk) * N + n] : 0.f; const float wg = w * g[k0 + kk];
;         scr[kk * 33 + (lane & 31)] = wg; cs += bf2f(f2bf(wg)); cb += b[k0 + kk] * w; }
; __global__ void __launch_bounds__(NWAVES * 64) mega(Args a) {
;     ...
;                 if (r < I_SQ) { const int kb = r / 32, nb = r % 32;
;                     cvt_item_ln(INP(15) + (size_t)l * 1024 * 1024, 1024, 1024, 64 * kb, 32 * nb, WL + WO_XQ + (size_t)(32 * nb) * 1024, scr, lane, INP(13) + l * D, INP(14) + l * D, cspl + kb * CSN + CS_Q + 32 * nb, cspl + (16 + kb) * CSN + CS_Q + 32 * nb); continue; } r -= I_SQ;
.LBB0_779:
	s_andn2_b64 vcc, exec, s[4:5]
	s_cbranch_vccnz .LBB0_783
	s_add_i32 s4, s25, 0xfffff8f0
	s_lshr_b32 s14, s4, 5
	s_mov_b32 s4, 15
	s_ashr_i32 s5, s4, 31
	s_lshl_b64 s[4:5], s[4:5], 3
	s_add_u32 s4, s0, s4
	s_addc_u32 s5, s1, s5
	s_load_dwordx2 s[4:5], s[4:5], 0x0
	s_lshl_b64 s[12:13], s[10:11], 22
	s_mov_b32 s16, 13
	s_mov_b32 s28, 14
	s_waitcnt lgkmcnt(0)
	s_add_u32 s4, s4, s12
	s_addc_u32 s5, s5, s13
	s_lshl_b32 s13, s10, 9
	s_sub_i32 s13, s6, s13
	s_add_i32 s13, s13, 0x8000
	s_ashr_i32 s17, s16, 31
	s_lshl_b32 s12, s14, 6
	s_and_b32 s13, s13, 0x3e0
	s_lshl_b64 s[16:17], s[16:17], 3
	s_add_u32 s16, s0, s16
	s_addc_u32 s17, s1, s17
	s_load_dwordx2 s[16:17], s[16:17], 0x0
	v_or_b32_e32 v7, s13, v1
	s_lshl_b32 s26, s10, 10
	v_lshlrev_b32_e32 v164, 2, v7
	s_ashr_i32 s27, s26, 31
	v_lshl_add_u64 v[18:19], s[4:5], 0, v[164:165]
	v_or_b32_e32 v164, s12, v2
	s_lshl_b64 s[26:27], s[26:27], 2
	v_lshlrev_b64 v[16:17], 12, v[164:165]
	s_waitcnt lgkmcnt(0)
	s_add_u32 s16, s16, s26
	v_lshl_add_u64 v[16:17], v[18:19], 0, v[16:17]
	s_addc_u32 s17, s17, s27
	v_mov_b32_e32 v180, v16
	v_mov_b32_e32 v181, v17
	v_lshlrev_b64 v[16:17], 2, v[164:165]
	v_lshl_add_u64 v[20:21], s[16:17], 0, v[16:17]
	s_ashr_i32 s29, s28, 31
	s_lshl_b64 s[28:29], s[28:29], 3
	s_add_u32 s28, s0, s28
	s_addc_u32 s29, s1, s29
	s_load_dwordx2 s[28:29], s[28:29], 0x0
	v_or_b32_e32 v164, s12, v11
	v_add_u32_e32 v78, v5, v9
	s_waitcnt lgkmcnt(0)
	s_add_u32 s26, s28, s26
	s_addc_u32 s27, s29, s27
	v_lshl_add_u64 v[16:17], s[26:27], 0, v[16:17]
	s_mov_b64 s[4:5], 0x2000
	global_load_dword v182, v[180:181], off
	v_lshl_add_u64 v[180:181], v[180:181], 0, s[4:5]
	global_load_dword v190, v[20:21], off
	global_load_dword v198, v[16:17], off
	global_load_dword v183, v[180:181], off
	v_lshl_add_u64 v[180:181], v[180:181], 0, s[4:5]
	global_load_dword v191, v[20:21], off offset:8
	global_load_dword v199, v[16:17], off offset:8
	global_load_dword v184, v[180:181], off
	v_lshl_add_u64 v[180:181], v[180:181], 0, s[4:5]
	global_load_dword v192, v[20:21], off offset:16
	global_load_dword v200, v[16:17], off offset:16
	global_load_dword v185, v[180:181], off
	v_lshl_add_u64 v[180:181], v[180:181], 0, s[4:5]
	global_load_dword v193, v[20:21], off offset:24
	global_load_dword v201, v[16:17], off offset:24
	global_load_dword v186, v[180:181], off
	v_lshl_add_u64 v[180:181], v[180:181], 0, s[4:5]
	global_load_dword v194, v[20:21], off offset:32
	global_load_dword v202, v[16:17], off offset:32
	global_load_dword v187, v[180:181], off
	v_lshl_add_u64 v[180:181], v[180:181], 0, s[4:5]
	global_load_dword v195, v[20:21], off offset:40
	global_load_dword v203, v[16:17], off offset:40
	global_load_dword v188, v[180:181], off
	v_lshl_add_u64 v[180:181], v[180:181], 0, s[4:5]
	global_load_dword v196, v[20:21], off offset:48
	global_load_dword v204, v[16:17], off offset:48
	global_load_dword v189, v[180:181], off
	v_lshl_add_u64 v[180:181], v[180:181], 0, s[4:5]
	global_load_dword v197, v[20:21], off offset:56
	global_load_dword v205, v[16:17], off offset:56
	global_load_dword v206, v[180:181], off
	v_lshl_add_u64 v[180:181], v[180:181], 0, s[4:5]
	global_load_dword v214, v[20:21], off offset:64
	global_load_dword v222, v[16:17], off offset:64
	global_load_dword v207, v[180:181], off
	v_lshl_add_u64 v[180:181], v[180:181], 0, s[4:5]
	global_load_dword v215, v[20:21], off offset:72
	global_load_dword v223, v[16:17], off offset:72
	global_load_dword v208, v[180:181], off
	v_lshl_add_u64 v[180:181], v[180:181], 0, s[4:5]
	global_load_dword v216, v[20:21], off offset:80
	global_load_dword v79, v[16:17], off offset:80
	global_load_dword v209, v[180:181], off
	v_lshl_add_u64 v[180:181], v[180:181], 0, s[4:5]
	global_load_dword v217, v[20:21], off offset:88
	global_load_dword v80, v[16:17], off offset:88
	global_load_dword v210, v[180:181], off
	v_lshl_add_u64 v[180:181], v[180:181], 0, s[4:5]
	global_load_dword v218, v[20:21], off offset:96
	global_load_dword v81, v[16:17], off offset:96
	global_load_dword v211, v[180:181], off
	v_lshl_add_u64 v[180:181], v[180:181], 0, s[4:5]
	global_load_dword v219, v[20:21], off offset:104
	global_load_dword v82, v[16:17], off offset:104
	global_load_dword v212, v[180:181], off
	v_lshl_add_u64 v[180:181], v[180:181], 0, s[4:5]
	global_load_dword v220, v[20:21], off offset:112
	global_load_dword v83, v[16:17], off offset:112
	global_load_dword v213, v[180:181], off
	v_lshl_add_u64 v[180:181], v[180:181], 0, s[4:5]
	global_load_dword v221, v[20:21], off offset:120
	global_load_dword v84, v[16:17], off offset:120
	s_waitcnt vmcnt(24)
; __device__ __forceinline__ float bf2f(bf16_t b) { return __uint_as_float(((unsigned)b) << 16); }
; __device__ __forceinline__ bf16_t f2bf(float f) { unsigned u = __float_as_uint(f); return (bf16_t)((u + 0x7fffu + ((u >> 16) & 1u)) >> 16); }
; __device__ __forceinline__ void cvt_item_ln(const float* W, int K, int N, int k0, int n0, bf16_t* dst, LAS float* scr, int lane, const float* g, const float* b, float* csp, float* cbp) {
;     ...
; #pragma unroll
;     for (int i = 0; i < 32; ++i) { const int kk = 2 * i + (lane >> 5), n = n0 + (lane & 31); const float w = n < N ? W[(size_t)(k0 + kk) * N + n] : 0.f; const float wg = w * g[k0 + kk];
;         scr[kk * 33 + (lane & 31)] = wg; cs += bf2f(f2bf(wg)); cb += b[k0 + kk] * w; }
	v_mul_f32_e32 v85, v182, v190
	ds_write_b32 v78, v85
	v_bfe_u32 v86, v85, 16, 1
	v_add3_u32 v86, v85, v86, s67
	v_and_b32_e32 v86, 0xffff0000, v86
	v_add_f32_e32 v18, 0, v86
	v_fma_f32 v7, v182, v198, 0
	v_mul_f32_e32 v85, v183, v191
	ds_write_b32 v78, v85 offset:264
	v_bfe_u32 v86, v85, 16, 1
	v_add3_u32 v86, v85, v86, s67
	v_and_b32_e32 v86, 0xffff0000, v86
	v_add_f32_e32 v18, v18, v86
	v_fmac_f32_e32 v7, v183, v199
	v_mul_f32_e32 v85, v184, v192
	ds_write_b32 v78, v85 offset:528
	v_bfe_u32 v86, v85, 16, 1
	v_add3_u32 v86, v85, v86, s67
	v_and_b32_e32 v86, 0xffff0000, v86
	v_add_f32_e32 v18, v18, v86
	v_fmac_f32_e32 v7, v184, v200
	v_mul_f32_e32 v85, v185, v193
	ds_write_b32 v78, v85 offset:792
	v_bfe_u32 v86, v85, 16, 1
	v_add3_u32 v86, v85, v86, s67
	v_and_b32_e32 v86, 0xffff0000, v86
	v_add_f32_e32 v18, v18, v86
	v_fmac_f32_e32 v7, v185, v201
	v_mul_f32_e32 v85, v186, v194
	ds_write_b32 v78, v85 offset:1056
	v_bfe_u32 v86, v85, 16, 1
	v_add3_u32 v86, v85, v86, s67
	v_and_b32_e32 v86, 0xffff0000, v86
	v_add_f32_e32 v18, v18, v86
	v_fmac_f32_e32 v7, v186, v202
	v_mul_f32_e32 v85, v187, v195
	ds_write_b32 v78, v85 offset:1320
	v_bfe_u32 v86, v85, 16, 1
	v_add3_u32 v86, v85, v86, s67
	v_and_b32_e32 v86, 0xffff0000, v86
	v_add_f32_e32 v18, v18, v86
	v_fmac_f32_e32 v7, v187, v203
	v_mul_f32_e32 v85, v188, v196
	ds_write_b32 v78, v85 offset:1584
	v_bfe_u32 v86, v85, 16, 1
	v_add3_u32 v86, v85, v86, s67
	v_and_b32_e32 v86, 0xffff0000, v86
	v_add_f32_e32 v18, v18, v86
	v_fmac_f32_e32 v7, v188, v204
	v_mul_f32_e32 v85, v189, v197
	ds_write_b32 v78, v85 offset:1848
	v_bfe_u32 v86, v85, 16, 1
	v_add3_u32 v86, v85, v86, s67
	v_and_b32_e32 v86, 0xffff0000, v86
	v_add_f32_e32 v18, v18, v86
	v_fmac_f32_e32 v7, v189, v205
	global_load_dword v182, v[180:181], off
	v_lshl_add_u64 v[180:181], v[180:181], 0, s[4:5]
	global_load_dword v190, v[20:21], off offset:128
	global_load_dword v198, v[16:17], off offset:128
	global_load_dword v183, v[180:181], off
	v_lshl_add_u64 v[180:181], v[180:181], 0, s[4:5]
	global_load_dword v191, v[20:21], off offset:136
	global_load_dword v199, v[16:17], off offset:136
	global_load_dword v184, v[180:181], off
	v_lshl_add_u64 v[180:181], v[180:181], 0, s[4:5]
	global_load_dword v192, v[20:21], off offset:144
	global_load_dword v200, v[16:17], off offset:144
	global_load_dword v185, v[180:181], off
	v_lshl_add_u64 v[180:181], v[180:181], 0, s[4:5]
	global_load_dword v193, v[20:21], off offset:152
	global_load_dword v201, v[16:17], off offset:152
	global_load_dword v186, v[180:181], off
	v_lshl_add_u64 v[180:181], v[180:181], 0, s[4:5]
	global_load_dword v194, v[20:21], off offset:160
	global_load_dword v202, v[16:17], off offset:160
	global_load_dword v187, v[180:181], off
	v_lshl_add_u64 v[180:181], v[180:181], 0, s[4:5]
	global_load_dword v195, v[20:21], off offset:168
	global_load_dword v203, v[16:17], off offset:168
	global_load_dword v188, v[180:181], off
	v_lshl_add_u64 v[180:181], v[180:181], 0, s[4:5]
	global_load_dword v196, v[20:21], off offset:176
	global_load_dword v204, v[16:17], off offset:176
	global_load_dword v189, v[180:181], off
	v_lshl_add_u64 v[180:181], v[180:181], 0, s[4:5]
	global_load_dword v197, v[20:21], off offset:184
	global_load_dword v205, v[16:17], off offset:184
	s_waitcnt vmcnt(24)
	v_mul_f32_e32 v85, v206, v214
	ds_write_b32 v78, v85 offset:2112
	v_bfe_u32 v86, v85, 16, 1
	v_add3_u32 v86, v85, v86, s67
	v_and_b32_e32 v86, 0xffff0000, v86
	v_add_f32_e32 v18, v18, v86
	v_fmac_f32_e32 v7, v206, v222
	v_mul_f32_e32 v85, v207, v215
	ds_write_b32 v78, v85 offset:2376
	v_bfe_u32 v86, v85, 16, 1
	v_add3_u32 v86, v85, v86, s67
	v_and_b32_e32 v86, 0xffff0000, v86
	v_add_f32_e32 v18, v18, v86
	v_fmac_f32_e32 v7, v207, v223
	v_mul_f32_e32 v85, v208, v216
	ds_write_b32 v78, v85 offset:2640
	v_bfe_u32 v86, v85, 16, 1
	v_add3_u32 v86, v85, v86, s67
	v_and_b32_e32 v86, 0xffff0000, v86
	v_add_f32_e32 v18, v18, v86
	v_fmac_f32_e32 v7, v208, v79
	v_mul_f32_e32 v85, v209, v217
	ds_write_b32 v78, v85 offset:2904
	v_bfe_u32 v86, v85, 16, 1
	v_add3_u32 v86, v85, v86, s67
	v_and_b32_e32 v86, 0xffff0000, v86
	v_add_f32_e32 v18, v18, v86
	v_fmac_f32_e32 v7, v209, v80
	v_mul_f32_e32 v85, v210, v218
	ds_write_b32 v78, v85 offset:3168
	v_bfe_u32 v86, v85, 16, 1
	v_add3_u32 v86, v85, v86, s67
	v_and_b32_e32 v86, 0xffff0000, v86
	v_add_f32_e32 v18, v18, v86
	v_fmac_f32_e32 v7, v210, v81
	v_mul_f32_e32 v85, v211, v219
	ds_write_b32 v78, v85 offset:3432
	v_bfe_u32 v86, v85, 16, 1
	v_add3_u32 v86, v85, v86, s67
	v_and_b32_e32 v86, 0xffff0000, v86
	v_add_f32_e32 v18, v18, v86
	v_fmac_f32_e32 v7, v211, v82
	v_mul_f32_e32 v85, v212, v220
	ds_write_b32 v78, v85 offset:3696
	v_bfe_u32 v86, v85, 16, 1
	v_add3_u32 v86, v85, v86, s67
	v_and_b32_e32 v86, 0xffff0000, v86
	v_add_f32_e32 v18, v18, v86
	v_fmac_f32_e32 v7, v212, v83
	v_mul_f32_e32 v85, v213, v221
	ds_write_b32 v78, v85 offset:3960
	v_bfe_u32 v86, v85, 16, 1
	v_add3_u32 v86, v85, v86, s67
	v_and_b32_e32 v86, 0xffff0000, v86
	v_add_f32_e32 v18, v18, v86
	v_fmac_f32_e32 v7, v213, v84
	global_load_dword v206, v[180:181], off
	v_lshl_add_u64 v[180:181], v[180:181], 0, s[4:5]
	global_load_dword v214, v[20:21], off offset:192
	global_load_dword v222, v[16:17], off offset:192
	global_load_dword v207, v[180:181], off
	v_lshl_add_u64 v[180:181], v[180:181], 0, s[4:5]
	global_load_dword v215, v[20:21], off offset:200
	global_load_dword v223, v[16:17], off offset:200
	global_load_dword v208, v[180:181], off
	v_lshl_add_u64 v[180:181], v[180:181], 0, s[4:5]
	global_load_dword v216, v[20:21], off offset:208
	global_load_dword v79, v[16:17], off offset:208
	global_load_dword v209, v[180:181], off
	v_lshl_add_u64 v[180:181], v[180:181], 0, s[4:5]
	global_load_dword v217, v[20:21], off offset:216
	global_load_dword v80, v[16:17], off offset:216
	global_load_dword v210, v[180:181], off
	v_lshl_add_u64 v[180:181], v[180:181], 0, s[4:5]
	global_load_dword v218, v[20:21], off offset:224
	global_load_dword v81, v[16:17], off offset:224
	global_load_dword v211, v[180:181], off
	v_lshl_add_u64 v[180:181], v[180:181], 0, s[4:5]
	global_load_dword v219, v[20:21], off offset:232
	global_load_dword v82, v[16:17], off offset:232
	global_load_dword v212, v[180:181], off
	v_lshl_add_u64 v[180:181], v[180:181], 0, s[4:5]
	global_load_dword v220, v[20:21], off offset:240
	global_load_dword v83, v[16:17], off offset:240
	global_load_dword v213, v[180:181], off
	v_lshl_add_u64 v[180:181], v[180:181], 0, s[4:5]
	global_load_dword v221, v[20:21], off offset:248
	global_load_dword v84, v[16:17], off offset:248
	s_waitcnt vmcnt(24)
; __device__ __forceinline__ float bf2f(bf16_t b) { return __uint_as_float(((unsigned)b) << 16); }
; __device__ __forceinline__ bf16_t f2bf(float f) { unsigned u = __float_as_uint(f); return (bf16_t)((u + 0x7fffu + ((u >> 16) & 1u)) >> 16); }
; __device__ __forceinline__ void cvt_item_ln(const float* W, int K, int N, int k0, int n0, bf16_t* dst, LAS float* scr, int lane, const float* g, const float* b, float* csp, float* cbp) {
;     ...
; #pragma unroll
;     for (int i = 0; i < 32; ++i) { const int kk = 2 * i + (lane >> 5), n = n0 + (lane & 31); const float w = n < N ? W[(size_t)(k0 + kk) * N + n] : 0.f; const float wg = w * g[k0 + kk];
;         scr[kk * 33 + (lane & 31)] = wg; cs += bf2f(f2bf(wg)); cb += b[k0 + kk] * w; }
;     cs += __shfl_xor(cs, 32); cb += __shfl_xor(cb, 32);
;     if (lane < 32) { csp[lane] = cs; cbp[lane] = cb; }
	v_mul_f32_e32 v85, v182, v190
	ds_write_b32 v78, v85 offset:4224
	v_bfe_u32 v86, v85, 16, 1
	v_add3_u32 v86, v85, v86, s67
	v_and_b32_e32 v86, 0xffff0000, v86
	v_add_f32_e32 v18, v18, v86
	v_fmac_f32_e32 v7, v182, v198
	v_mul_f32_e32 v85, v183, v191
	ds_write_b32 v78, v85 offset:4488
	v_bfe_u32 v86, v85, 16, 1
	v_add3_u32 v86, v85, v86, s67
	v_and_b32_e32 v86, 0xffff0000, v86
	v_add_f32_e32 v18, v18, v86
	v_fmac_f32_e32 v7, v183, v199
	v_mul_f32_e32 v85, v184, v192
	ds_write_b32 v78, v85 offset:4752
	v_bfe_u32 v86, v85, 16, 1
	v_add3_u32 v86, v85, v86, s67
	v_and_b32_e32 v86, 0xffff0000, v86
	v_add_f32_e32 v18, v18, v86
	v_fmac_f32_e32 v7, v184, v200
	v_mul_f32_e32 v85, v185, v193
	ds_write_b32 v78, v85 offset:5016
	v_bfe_u32 v86, v85, 16, 1
	v_add3_u32 v86, v85, v86, s67
	v_and_b32_e32 v86, 0xffff0000, v86
	v_add_f32_e32 v18, v18, v86
	v_fmac_f32_e32 v7, v185, v201
	v_mul_f32_e32 v85, v186, v194
	ds_write_b32 v78, v85 offset:5280
	v_bfe_u32 v86, v85, 16, 1
	v_add3_u32 v86, v85, v86, s67
	v_and_b32_e32 v86, 0xffff0000, v86
	v_add_f32_e32 v18, v18, v86
	v_fmac_f32_e32 v7, v186, v202
	v_mul_f32_e32 v85, v187, v195
	ds_write_b32 v78, v85 offset:5544
	v_bfe_u32 v86, v85, 16, 1
	v_add3_u32 v86, v85, v86, s67
	v_and_b32_e32 v86, 0xffff0000, v86
	v_add_f32_e32 v18, v18, v86
	v_fmac_f32_e32 v7, v187, v203
	v_mul_f32_e32 v85, v188, v196
	ds_write_b32 v78, v85 offset:5808
	v_bfe_u32 v86, v85, 16, 1
	v_add3_u32 v86, v85, v86, s67
	v_and_b32_e32 v86, 0xffff0000, v86
	v_add_f32_e32 v18, v18, v86
	v_fmac_f32_e32 v7, v188, v204
	v_mul_f32_e32 v85, v189, v197
	ds_write_b32 v78, v85 offset:6072
	v_bfe_u32 v86, v85, 16, 1
	v_add3_u32 v86, v85, v86, s67
	v_and_b32_e32 v86, 0xffff0000, v86
	v_add_f32_e32 v18, v18, v86
	v_fmac_f32_e32 v7, v189, v205
	s_waitcnt vmcnt(0)
	v_mul_f32_e32 v85, v206, v214
	ds_write_b32 v78, v85 offset:6336
	v_bfe_u32 v86, v85, 16, 1
	v_add3_u32 v86, v85, v86, s67
	v_and_b32_e32 v86, 0xffff0000, v86
	v_add_f32_e32 v18, v18, v86
	v_fmac_f32_e32 v7, v206, v222
	v_mul_f32_e32 v85, v207, v215
	ds_write_b32 v78, v85 offset:6600
	v_bfe_u32 v86, v85, 16, 1
	v_add3_u32 v86, v85, v86, s67
	v_and_b32_e32 v86, 0xffff0000, v86
	v_add_f32_e32 v18, v18, v86
	v_fmac_f32_e32 v7, v207, v223
	v_mul_f32_e32 v85, v208, v216
	ds_write_b32 v78, v85 offset:6864
	v_bfe_u32 v86, v85, 16, 1
	v_add3_u32 v86, v85, v86, s67
	v_and_b32_e32 v86, 0xffff0000, v86
	v_add_f32_e32 v18, v18, v86
	v_fmac_f32_e32 v7, v208, v79
	v_mul_f32_e32 v85, v209, v217
	ds_write_b32 v78, v85 offset:7128
	v_bfe_u32 v86, v85, 16, 1
	v_add3_u32 v86, v85, v86, s67
	v_and_b32_e32 v86, 0xffff0000, v86
	v_add_f32_e32 v18, v18, v86
	v_fmac_f32_e32 v7, v209, v80
	v_mul_f32_e32 v85, v210, v218
	ds_write_b32 v78, v85 offset:7392
	v_bfe_u32 v86, v85, 16, 1
	v_add3_u32 v86, v85, v86, s67
	v_and_b32_e32 v86, 0xffff0000, v86
	v_add_f32_e32 v18, v18, v86
	v_fmac_f32_e32 v7, v210, v81
	v_mul_f32_e32 v85, v211, v219
	ds_write_b32 v78, v85 offset:7656
	v_bfe_u32 v86, v85, 16, 1
	v_add3_u32 v86, v85, v86, s67
	v_and_b32_e32 v86, 0xffff0000, v86
	v_add_f32_e32 v18, v18, v86
	v_fmac_f32_e32 v7, v211, v82
	v_mul_f32_e32 v85, v212, v220
	ds_write_b32 v78, v85 offset:7920
	v_bfe_u32 v86, v85, 16, 1
	v_add3_u32 v86, v85, v86, s67
	v_and_b32_e32 v86, 0xffff0000, v86
	v_add_f32_e32 v18, v18, v86
	v_fmac_f32_e32 v7, v212, v83
	v_mul_f32_e32 v85, v213, v221
	ds_write_b32 v78, v85 offset:8184
	v_bfe_u32 v86, v85, 16, 1
	v_add3_u32 v86, v85, v86, s67
	v_and_b32_e32 v86, 0xffff0000, v86
	v_add_f32_e32 v18, v18, v86
	v_fmac_f32_e32 v7, v213, v84
	v_and_b32_e32 v17, 64, v230
	v_add_u32_e32 v17, 64, v17
	v_xor_b32_e32 v16, 32, v230
	v_cmp_lt_i32_e32 vcc, v16, v17
	s_nop 1
	v_cndmask_b32_e32 v16, v230, v16, vcc
	v_lshlrev_b32_e32 v17, 2, v16
	ds_bpermute_b32 v16, v17, v18
	ds_bpermute_b32 v17, v17, v7
	s_and_saveexec_b64 s[4:5], s[8:9]
	s_cbranch_execz .LBB0_782
	s_mul_i32 s74, s14, 0x2500
	s_lshl_b64 s[14:15], s[74:75], 2
	s_add_u32 s14, s23, s14
	s_addc_u32 s15, s24, s15
	s_lshl_b32 s16, s13, 2
	s_add_u32 s14, s14, s16
	v_lshlrev_b32_e32 v164, 2, v172
	s_addc_u32 s15, s15, 0
	s_waitcnt lgkmcnt(0)
	v_add_f32_e32 v7, v7, v17
	v_add_f32_e32 v20, v18, v16
	v_lshl_add_u64 v[16:17], s[14:15], 0, v[164:165]
	v_add_co_u32_e32 v18, vcc, 0x2000, v16
	s_nop 1
	v_addc_co_u32_e32 v19, vcc, 0, v17, vcc
	v_add_co_u32_e32 v16, vcc, 0x96000, v16
	global_store_dword v[18:19], v20, off offset:3072
	s_nop 0
	v_addc_co_u32_e32 v17, vcc, 0, v17, vcc
	global_store_dword v[16:17], v7, off offset:3072
